# guide 7.11 loop-edge edit: v20 + K-loop counter/pointer-advance/exit-test and L1 pointer-select SALU block moved from the L1 segment head to the end of the L2' segment (5 GEMM loops)
# speedup vs baseline: 1.0060x; 1.0024x over previous
;     __device__ __forceinline__ bool next(int i, Unit& u) const { if (i >= 2) return false; const int xcd = c & 7, off = c >> 3; u.pm = 16 * i + 4 * (xcd >> 1) + (off & 3); u.pn = 8 * (xcd & 1) + (off >> 2); return true; }
; #define PG8_STAGE(bufoff, gbase, voff) do { _Pragma("unroll") for (int _i = 0; _i < 2; ++_i) \
;         __builtin_amdgcn_global_load_lds((const unsigned*)((const char*)(gbase) + (voff)[_i]), (PG8_LAS unsigned*)(lds + (bufoff) + ldsw + _i * 8192), 16, 0, 0); } while (0)
; #define PG8_LDA(dst, b, h) do { _Pragma("unroll") for (int m = 0; m < 4; ++m) _Pragma("unroll") for (int k = 0; k < 2; ++k) dst[m][k] = *(const PG8_LAS bf16x8*)(lds + PG8_SA(b, h) + aoff + m * 2048 + k * 1024); } while (0)
; #define PG8_LDB(dst, b, h) do { _Pragma("unroll") for (int n = 0; n < 2; ++n) _Pragma("unroll") for (int k = 0; k < 2; ++k) dst[n][k] = *(const PG8_LAS bf16x8*)(lds + PG8_SB(b, h) + boff + n * 2048 + k * 1024); } while (0)
; #define PG8_WAIT_V(n) asm volatile("s_waitcnt vmcnt(" #n ")" ::: "memory")
; #define PG8_WAIT_L(n) asm volatile("s_waitcnt lgkmcnt(" #n ")" ::: "memory")
; template <class Epi, class Sched, bool ALIGN_EPI = false, bool SP2 = false>
; __device__ __forceinline__ void gemm_phase(PG8_LAS unsigned char* lds, const Gemm g, const Sched& S, const Epi& E) {
;     ...
;         const bool has_next = S.next(ui + 1, nxt);
;         const char* nA = has_next ? (const char*)g.A + (size_t)nxt.pm * tstep : cA; const char* nB = has_next ? (const char*)g.Bt + (size_t)nxt.pn * tstep : cB;
;         constexpr int NSEG = Epi::HAS_MID ? 2 : 1; int t = 0;
; #pragma unroll
;         for (int seg = 0; seg < NSEG; ++seg) { const int tend = (seg + 1 < NSEG) ? (nt >> 1) : nt;
;         for (; t < tend; t += 2) {
;             const bool last = (t == nt - 2);
;             const char* a1 = cA + (size_t)(t + 1) * kstep;
;             const char* a2 = last ? nA : cA + (size_t)(t + 2) * kstep; const char* b2 = last ? nB : cB + (size_t)(t + 2) * kstep;
;             const char* a3 = a2 + kstep; const char* b3 = b2 + kstep;
;             if (last && has_next) S.a_ready(nxt);
;             if constexpr (SP2) {
;             PG8_LDB(B0, 0, 0); PG8_LDB(B1, 0, 1); PG8_SCHED; PG8_LDA(At, 0, 0); PG8_STAGE(PG8_SA(1, 1), a1 + hstep, voffA);
;             PG8_WAIT_V(8); PG8_WAIT_L(0); PG8_BAR; PG8_MMA(0, 0, At, B0); PG8_MMA(0, 1, At, B1); PG8_BAR; PG8_SCHED;
.LBB0_114:
	s_ashr_i32 s25, s24, 31
	s_lshl_b64 s[42:43], s[24:25], 21
	s_add_u32 s42, s66, s42
	s_addc_u32 s43, s67, s43
	s_and_b64 s[44:45], s[0:1], exec
	s_cselect_b32 s25, s43, s49
	s_cselect_b32 s64, s42, s48
	s_ashr_i32 s19, s18, 31
	s_lshl_b64 s[44:45], s[18:19], 21
	s_add_u32 s44, s4, s44
	s_addc_u32 s45, s5, s45
	s_and_b64 s[68:69], s[0:1], exec
	s_cselect_b32 s19, s45, s51
	s_cselect_b32 s65, s44, s50
	s_add_u32 s48, s48, 0xc000
	s_addc_u32 s49, s49, 0
	s_add_u32 s68, s50, 0x10000
	s_addc_u32 s69, s51, 0
	s_mov_b32 s76, -2
	s_nop 3
	s_add_u32 s50, s48, 0x4000
	s_addc_u32 s51, s49, 0
	s_cmp_eq_u32 s76, 60
	s_cselect_b32 s74, s64, s50
	s_cselect_b32 s75, s25, s51
	s_cselect_b32 s72, s65, s68
	s_cselect_b32 s73, s19, s69
	s_add_u32 s50, s74, 0x8000
	s_addc_u32 s51, s75, 0
	s_sub_u32 s50, s48, 0x4000
	s_subb_u32 s51, s49, 0
	ds_read_b128 v[154:157], v150
	ds_read_b128 v[158:161], v150 offset:1024
	ds_read_b128 v[162:165], v150 offset:2048
	ds_read_b128 v[166:169], v150 offset:3072
	ds_read_b128 v[170:173], v151
	ds_read_b128 v[174:177], v151 offset:1024
	ds_read_b128 v[180:183], v151 offset:2048
	ds_read_b128 v[184:187], v151 offset:3072
	s_mov_b32 m0, s58
	s_nop 0
	global_load_lds_dwordx4 v130, s[50:51]
	s_mov_b32 m0, s59
	s_nop 0
	global_load_lds_dwordx4 v134, s[50:51]
	s_add_i32 m0, s28, 0xc000
	ds_read_b128 v[188:191], v152
	ds_read_b128 v[196:199], v152 offset:1024
	ds_read_b128 v[200:203], v152 offset:2048
	ds_read_b128 v[204:207], v152 offset:3072
	ds_read_b128 v[208:211], v152 offset:4096
	ds_read_b128 v[212:215], v152 offset:5120
	ds_read_b128 v[216:219], v152 offset:6144
	ds_read_b128 v[220:223], v152 offset:7168
	global_load_lds_dwordx4 v140, s[48:49]
	s_add_i32 m0, s28, 0xe000
	s_nop 0
	global_load_lds_dwordx4 v142, s[48:49]
	s_waitcnt vmcnt(8)
	s_waitcnt lgkmcnt(0)
	s_barrier
	s_waitcnt lgkmcnt(0)
	v_mfma_f32_16x16x32_bf16 v[126:129], v[154:157], v[188:191], 0
	v_mfma_f32_16x16x32_bf16 v[126:129], v[158:161], v[196:199], v[126:129]
	v_mfma_f32_16x16x32_bf16 v[110:113], v[158:161], v[204:207], 0
	v_mfma_f32_16x16x32_bf16 v[110:113], v[154:157], v[200:203], v[110:113]
	v_mfma_f32_16x16x32_bf16 v[94:97], v[154:157], v[208:211], 0
	v_mfma_f32_16x16x32_bf16 v[94:97], v[158:161], v[212:215], v[94:97]
	v_mfma_f32_16x16x32_bf16 v[78:81], v[158:161], v[220:223], 0
	v_mfma_f32_16x16x32_bf16 v[78:81], v[154:157], v[216:219], v[78:81]
	v_mfma_f32_16x16x32_bf16 v[70:73], v[162:165], v[216:219], 0
	v_mfma_f32_16x16x32_bf16 v[70:73], v[166:169], v[220:223], v[70:73]
	v_mfma_f32_16x16x32_bf16 v[86:89], v[166:169], v[212:215], 0
	v_mfma_f32_16x16x32_bf16 v[86:89], v[162:165], v[208:211], v[86:89]
	v_mfma_f32_16x16x32_bf16 v[102:105], v[162:165], v[200:203], 0
	v_mfma_f32_16x16x32_bf16 v[102:105], v[166:169], v[204:207], v[102:105]
	v_mfma_f32_16x16x32_bf16 v[118:121], v[166:169], v[196:199], 0
	v_mfma_f32_16x16x32_bf16 v[118:121], v[162:165], v[188:191], v[118:121]
	v_mfma_f32_16x16x32_bf16 v[122:125], v[170:173], v[188:191], 0
	v_mfma_f32_16x16x32_bf16 v[122:125], v[174:177], v[196:199], v[122:125]
	v_mfma_f32_16x16x32_bf16 v[106:109], v[174:177], v[204:207], 0
	v_mfma_f32_16x16x32_bf16 v[106:109], v[170:173], v[200:203], v[106:109]
	v_mfma_f32_16x16x32_bf16 v[90:93], v[170:173], v[208:211], 0
	v_mfma_f32_16x16x32_bf16 v[90:93], v[174:177], v[212:215], v[90:93]
	v_mfma_f32_16x16x32_bf16 v[74:77], v[174:177], v[220:223], 0
	v_mfma_f32_16x16x32_bf16 v[74:77], v[170:173], v[216:219], v[74:77]
	v_mfma_f32_16x16x32_bf16 v[66:69], v[180:183], v[216:219], 0
	v_mfma_f32_16x16x32_bf16 v[66:69], v[184:187], v[220:223], v[66:69]
	v_mfma_f32_16x16x32_bf16 v[82:85], v[184:187], v[212:215], 0
	v_mfma_f32_16x16x32_bf16 v[82:85], v[180:183], v[208:211], v[82:85]
	v_mfma_f32_16x16x32_bf16 v[98:101], v[180:183], v[200:203], 0
	v_mfma_f32_16x16x32_bf16 v[98:101], v[184:187], v[204:207], v[98:101]
	v_mfma_f32_16x16x32_bf16 v[114:117], v[184:187], v[196:199], 0
	v_mfma_f32_16x16x32_bf16 v[114:117], v[180:183], v[188:191], v[114:117]
	s_barrier
	s_add_i32 s77, s61, s3
	s_mov_b32 m0, s77
	ds_read_b128 v[188:191], v152 offset:16384
	ds_read_b128 v[196:199], v152 offset:17408
	ds_read_b128 v[200:203], v152 offset:18432
	ds_read_b128 v[204:207], v152 offset:19456
	ds_read_b128 v[208:211], v152 offset:20480
	ds_read_b128 v[212:215], v152 offset:21504
	ds_read_b128 v[216:219], v152 offset:22528
	ds_read_b128 v[220:223], v152 offset:23552
	global_load_lds_dwordx4 v132, s[72:73]
	s_add_i32 m0, s77, 0x2000
	s_add_u32 s78, s72, 0x4000
	s_addc_u32 s79, s73, 0
	s_add_i32 s77, s62, s3
	global_load_lds_dwordx4 v136, s[72:73]
	s_mov_b32 m0, s77
	s_nop 0
	global_load_lds_dwordx4 v132, s[78:79]
	s_add_i32 m0, s77, 0x2000
	s_nop 0
	global_load_lds_dwordx4 v136, s[78:79]
	s_waitcnt vmcnt(6)
	s_waitcnt lgkmcnt(0)
	s_barrier
; #define PG8_STAGE(bufoff, gbase, voff) do { _Pragma("unroll") for (int _i = 0; _i < 2; ++_i) \
;         __builtin_amdgcn_global_load_lds((const unsigned*)((const char*)(gbase) + (voff)[_i]), (PG8_LAS unsigned*)(lds + (bufoff) + ldsw + _i * 8192), 16, 0, 0); } while (0)
; #define PG8_LDA(dst, b, h) do { _Pragma("unroll") for (int m = 0; m < 4; ++m) _Pragma("unroll") for (int k = 0; k < 2; ++k) dst[m][k] = *(const PG8_LAS bf16x8*)(lds + PG8_SA(b, h) + aoff + m * 2048 + k * 1024); } while (0)
; #define PG8_LDB(dst, b, h) do { _Pragma("unroll") for (int n = 0; n < 2; ++n) _Pragma("unroll") for (int k = 0; k < 2; ++k) dst[n][k] = *(const PG8_LAS bf16x8*)(lds + PG8_SB(b, h) + boff + n * 2048 + k * 1024); } while (0)
; #define PG8_MMA(ai, bj, At, Bt) do { __builtin_amdgcn_s_setprio(1); _Pragma("unroll") for (int m = 0; m < 4; ++m) _Pragma("unroll") for (int n = 0; n < 2; ++n) _Pragma("unroll") for (int k = 0; k < 2; ++k) \
;         acc[ai][bj][m][n] = __builtin_amdgcn_mfma_f32_16x16x32_bf16(Bt[n][k], At[m][k], acc[ai][bj][m][n], 0, 0, 0); __builtin_amdgcn_s_setprio(0); } while (0)
; #define PG8_WAIT_V(n) asm volatile("s_waitcnt vmcnt(" #n ")" ::: "memory")
; #define PG8_WAIT_L(n) asm volatile("s_waitcnt lgkmcnt(" #n ")" ::: "memory")
; #define PG8_BAR __builtin_amdgcn_s_barrier()
; #define PG8_SCHED __builtin_amdgcn_sched_barrier(0)
; template <class Epi, class Sched, bool ALIGN_EPI = false, bool SP2 = false>
; __device__ __forceinline__ void gemm_phase(PG8_LAS unsigned char* lds, const Gemm g, const Sched& S, const Epi& E) {
;     ...
;             PG8_WAIT_V(8); PG8_WAIT_L(0); PG8_BAR; PG8_MMA(0, 0, At, B0); PG8_MMA(0, 1, At, B1); PG8_BAR; PG8_SCHED;
;             PG8_LDA(At, 0, 1); PG8_STAGE(PG8_SB(0, 0), b2, voffB); PG8_STAGE(PG8_SB(0, 1), b2 + hstep, voffB); PG8_STAGE(PG8_SA(0, 0), a2, voffA);
;             PG8_WAIT_V(8); PG8_WAIT_L(0); PG8_BAR; PG8_MMA(1, 0, At, B0); PG8_MMA(1, 1, At, B1); PG8_BAR; PG8_SCHED;
;             PG8_LDB(B0, 1, 0); PG8_LDB(B1, 1, 1); PG8_SCHED; PG8_LDA(At, 1, 0); PG8_STAGE(PG8_SA(0, 1), a2 + hstep, voffA);
;             PG8_WAIT_V(8); PG8_WAIT_L(0); PG8_BAR; PG8_MMA(0, 0, At, B0); PG8_MMA(0, 1, At, B1); PG8_BAR; PG8_SCHED;
	s_waitcnt lgkmcnt(0)
	v_mfma_f32_16x16x32_bf16 v[62:65], v[154:157], v[188:191], 0
	v_mfma_f32_16x16x32_bf16 v[62:65], v[158:161], v[196:199], v[62:65]
	v_mfma_f32_16x16x32_bf16 v[46:49], v[158:161], v[204:207], 0
	v_mfma_f32_16x16x32_bf16 v[46:49], v[154:157], v[200:203], v[46:49]
	v_mfma_f32_16x16x32_bf16 v[30:33], v[154:157], v[208:211], 0
	v_mfma_f32_16x16x32_bf16 v[30:33], v[158:161], v[212:215], v[30:33]
	v_mfma_f32_16x16x32_bf16 v[14:17], v[158:161], v[220:223], 0
	v_mfma_f32_16x16x32_bf16 v[14:17], v[154:157], v[216:219], v[14:17]
	v_mfma_f32_16x16x32_bf16 v[6:9], v[162:165], v[216:219], 0
	v_mfma_f32_16x16x32_bf16 v[6:9], v[166:169], v[220:223], v[6:9]
	v_mfma_f32_16x16x32_bf16 v[22:25], v[166:169], v[212:215], 0
	v_mfma_f32_16x16x32_bf16 v[22:25], v[162:165], v[208:211], v[22:25]
	v_mfma_f32_16x16x32_bf16 v[38:41], v[162:165], v[200:203], 0
	v_mfma_f32_16x16x32_bf16 v[38:41], v[166:169], v[204:207], v[38:41]
	v_mfma_f32_16x16x32_bf16 v[54:57], v[166:169], v[196:199], 0
	v_mfma_f32_16x16x32_bf16 v[54:57], v[162:165], v[188:191], v[54:57]
	v_mfma_f32_16x16x32_bf16 v[58:61], v[170:173], v[188:191], 0
	v_mfma_f32_16x16x32_bf16 v[58:61], v[174:177], v[196:199], v[58:61]
	v_mfma_f32_16x16x32_bf16 v[42:45], v[174:177], v[204:207], 0
	v_mfma_f32_16x16x32_bf16 v[42:45], v[170:173], v[200:203], v[42:45]
	v_mfma_f32_16x16x32_bf16 v[26:29], v[170:173], v[208:211], 0
	v_mfma_f32_16x16x32_bf16 v[26:29], v[174:177], v[212:215], v[26:29]
	v_mfma_f32_16x16x32_bf16 v[10:13], v[174:177], v[220:223], 0
	v_mfma_f32_16x16x32_bf16 v[10:13], v[170:173], v[216:219], v[10:13]
	v_mfma_f32_16x16x32_bf16 v[2:5], v[180:183], v[216:219], 0
	v_mfma_f32_16x16x32_bf16 v[2:5], v[184:187], v[220:223], v[2:5]
	v_mfma_f32_16x16x32_bf16 v[18:21], v[184:187], v[212:215], 0
	v_mfma_f32_16x16x32_bf16 v[18:21], v[180:183], v[208:211], v[18:21]
	v_mfma_f32_16x16x32_bf16 v[34:37], v[180:183], v[200:203], 0
	v_mfma_f32_16x16x32_bf16 v[34:37], v[184:187], v[204:207], v[34:37]
	v_mfma_f32_16x16x32_bf16 v[50:53], v[184:187], v[196:199], 0
	v_mfma_f32_16x16x32_bf16 v[50:53], v[180:183], v[188:191], v[50:53]
	s_barrier
	s_add_i32 s77, 0, 0x18000
	v_add_u32_e32 v138, s77, v148
	s_add_i32 s78, 0, 0x1c000
	ds_read_b128 v[154:157], v138
	ds_read_b128 v[158:161], v138 offset:1024
	ds_read_b128 v[162:165], v138 offset:2048
	ds_read_b128 v[166:169], v138 offset:3072
	v_add_u32_e32 v138, s78, v148
	ds_read_b128 v[170:173], v138
	ds_read_b128 v[174:177], v138 offset:1024
	ds_read_b128 v[180:183], v138 offset:2048
	ds_read_b128 v[184:187], v138 offset:3072
	s_mov_b32 m0, s28
	s_nop 0
	global_load_lds_dwordx4 v130, s[74:75]
	s_mov_b32 m0, s29
	s_nop 0
	global_load_lds_dwordx4 v134, s[74:75]
	s_add_u32 s74, s74, 0x4000
	s_addc_u32 s75, s75, 0
	s_mov_b32 m0, s30
	ds_read_b128 v[188:191], v152 offset:32768
	ds_read_b128 v[196:199], v152 offset:33792
	ds_read_b128 v[200:203], v152 offset:34816
	ds_read_b128 v[204:207], v152 offset:35840
	ds_read_b128 v[208:211], v152 offset:36864
	ds_read_b128 v[212:215], v152 offset:37888
	ds_read_b128 v[216:219], v152 offset:38912
	ds_read_b128 v[220:223], v152 offset:39936
	global_load_lds_dwordx4 v130, s[74:75]
	s_mov_b32 m0, s31
	s_nop 0
	global_load_lds_dwordx4 v134, s[74:75]
	s_waitcnt vmcnt(8)
	s_waitcnt lgkmcnt(0)
	s_barrier
	s_waitcnt lgkmcnt(0)
	v_mfma_f32_16x16x32_bf16 v[126:129], v[154:157], v[188:191], v[126:129]
	v_mfma_f32_16x16x32_bf16 v[126:129], v[158:161], v[196:199], v[126:129]
	v_mfma_f32_16x16x32_bf16 v[110:113], v[158:161], v[204:207], v[110:113]
	v_mfma_f32_16x16x32_bf16 v[110:113], v[154:157], v[200:203], v[110:113]
	v_mfma_f32_16x16x32_bf16 v[94:97], v[154:157], v[208:211], v[94:97]
	v_mfma_f32_16x16x32_bf16 v[94:97], v[158:161], v[212:215], v[94:97]
	v_mfma_f32_16x16x32_bf16 v[78:81], v[158:161], v[220:223], v[78:81]
	v_mfma_f32_16x16x32_bf16 v[78:81], v[154:157], v[216:219], v[78:81]
	v_mfma_f32_16x16x32_bf16 v[70:73], v[162:165], v[216:219], v[70:73]
	v_mfma_f32_16x16x32_bf16 v[70:73], v[166:169], v[220:223], v[70:73]
	v_mfma_f32_16x16x32_bf16 v[86:89], v[166:169], v[212:215], v[86:89]
	v_mfma_f32_16x16x32_bf16 v[86:89], v[162:165], v[208:211], v[86:89]
	v_mfma_f32_16x16x32_bf16 v[102:105], v[162:165], v[200:203], v[102:105]
	v_mfma_f32_16x16x32_bf16 v[102:105], v[166:169], v[204:207], v[102:105]
	v_mfma_f32_16x16x32_bf16 v[118:121], v[166:169], v[196:199], v[118:121]
	v_mfma_f32_16x16x32_bf16 v[118:121], v[162:165], v[188:191], v[118:121]
	v_mfma_f32_16x16x32_bf16 v[122:125], v[170:173], v[188:191], v[122:125]
	v_mfma_f32_16x16x32_bf16 v[122:125], v[174:177], v[196:199], v[122:125]
	v_mfma_f32_16x16x32_bf16 v[106:109], v[174:177], v[204:207], v[106:109]
	v_mfma_f32_16x16x32_bf16 v[106:109], v[170:173], v[200:203], v[106:109]
	v_mfma_f32_16x16x32_bf16 v[90:93], v[170:173], v[208:211], v[90:93]
	v_mfma_f32_16x16x32_bf16 v[90:93], v[174:177], v[212:215], v[90:93]
	v_mfma_f32_16x16x32_bf16 v[74:77], v[174:177], v[220:223], v[74:77]
	v_mfma_f32_16x16x32_bf16 v[74:77], v[170:173], v[216:219], v[74:77]
	v_mfma_f32_16x16x32_bf16 v[66:69], v[180:183], v[216:219], v[66:69]
	v_mfma_f32_16x16x32_bf16 v[66:69], v[184:187], v[220:223], v[66:69]
	v_mfma_f32_16x16x32_bf16 v[82:85], v[184:187], v[212:215], v[82:85]
	v_mfma_f32_16x16x32_bf16 v[82:85], v[180:183], v[208:211], v[82:85]
	v_mfma_f32_16x16x32_bf16 v[98:101], v[180:183], v[200:203], v[98:101]
	v_mfma_f32_16x16x32_bf16 v[98:101], v[184:187], v[204:207], v[98:101]
	v_mfma_f32_16x16x32_bf16 v[114:117], v[184:187], v[196:199], v[114:117]
	v_mfma_f32_16x16x32_bf16 v[114:117], v[180:183], v[188:191], v[114:117]
	s_barrier
; #define PG8_STAGE(bufoff, gbase, voff) do { _Pragma("unroll") for (int _i = 0; _i < 2; ++_i) \
;         __builtin_amdgcn_global_load_lds((const unsigned*)((const char*)(gbase) + (voff)[_i]), (PG8_LAS unsigned*)(lds + (bufoff) + ldsw + _i * 8192), 16, 0, 0); } while (0)
; #define PG8_LDA(dst, b, h) do { _Pragma("unroll") for (int m = 0; m < 4; ++m) _Pragma("unroll") for (int k = 0; k < 2; ++k) dst[m][k] = *(const PG8_LAS bf16x8*)(lds + PG8_SA(b, h) + aoff + m * 2048 + k * 1024); } while (0)
; #define PG8_LDB(dst, b, h) do { _Pragma("unroll") for (int n = 0; n < 2; ++n) _Pragma("unroll") for (int k = 0; k < 2; ++k) dst[n][k] = *(const PG8_LAS bf16x8*)(lds + PG8_SB(b, h) + boff + n * 2048 + k * 1024); } while (0)
; template <class Epi, class Sched, bool ALIGN_EPI = false, bool SP2 = false>
; __device__ __forceinline__ void gemm_phase(PG8_LAS unsigned char* lds, const Gemm g, const Sched& S, const Epi& E) {
;     ...
;         for (; t < tend; t += 2) {
;             const bool last = (t == nt - 2);
;             const char* a1 = cA + (size_t)(t + 1) * kstep;
;             const char* a2 = last ? nA : cA + (size_t)(t + 2) * kstep; const char* b2 = last ? nB : cB + (size_t)(t + 2) * kstep;
;             const char* a3 = a2 + kstep; const char* b3 = b2 + kstep;
;             if (last && has_next) S.a_ready(nxt);
;             if constexpr (SP2) {
;             PG8_LDB(B0, 0, 0); PG8_LDB(B1, 0, 1); PG8_SCHED; PG8_LDA(At, 0, 0); PG8_STAGE(PG8_SA(1, 1), a1 + hstep, voffA);
;             PG8_WAIT_V(8); PG8_WAIT_L(0); PG8_BAR; PG8_MMA(0, 0, At, B0); PG8_MMA(0, 1, At, B1); PG8_BAR; PG8_SCHED;
;             PG8_LDA(At, 0, 1); PG8_STAGE(PG8_SB(0, 0), b2, voffB); PG8_STAGE(PG8_SB(0, 1), b2 + hstep, voffB); PG8_STAGE(PG8_SA(0, 0), a2, voffA);
;             PG8_WAIT_V(8); PG8_WAIT_L(0); PG8_BAR; PG8_MMA(1, 0, At, B0); PG8_MMA(1, 1, At, B1); PG8_BAR; PG8_SCHED;
;             PG8_LDB(B0, 1, 0); PG8_LDB(B1, 1, 1); PG8_SCHED; PG8_LDA(At, 1, 0); PG8_STAGE(PG8_SA(0, 1), a2 + hstep, voffA);
;             PG8_WAIT_V(8); PG8_WAIT_L(0); PG8_BAR; PG8_MMA(0, 0, At, B0); PG8_MMA(0, 1, At, B1); PG8_BAR; PG8_SCHED;
;             PG8_LDA(At, 1, 1); PG8_STAGE(PG8_SB(1, 0), b3, voffB); PG8_STAGE(PG8_SB(1, 1), b3 + hstep, voffB); PG8_STAGE(PG8_SA(1, 0), a3, voffA);
;             PG8_WAIT_V(8); PG8_WAIT_L(0); PG8_BAR; PG8_MMA(1, 0, At, B0); PG8_MMA(1, 1, At, B1); PG8_BAR; PG8_SCHED;
	s_add_u32 s74, s72, 0x8000
	s_addc_u32 s75, s73, 0
	s_add_i32 s77, s77, s3
	s_mov_b32 m0, s77
	ds_read_b128 v[188:191], v152 offset:49152
	ds_read_b128 v[196:199], v152 offset:50176
	ds_read_b128 v[200:203], v152 offset:51200
	ds_read_b128 v[204:207], v152 offset:52224
	ds_read_b128 v[208:211], v152 offset:53248
	ds_read_b128 v[212:215], v152 offset:54272
	ds_read_b128 v[216:219], v152 offset:55296
	ds_read_b128 v[220:223], v152 offset:56320
	global_load_lds_dwordx4 v132, s[74:75]
	s_add_i32 m0, s77, 0x2000
	s_add_u32 s72, s72, 0xc000
	v_lshl_add_u64 v[224:225], s[74:75], 0, v[136:137]
	s_addc_u32 s73, s73, 0
	s_add_i32 s74, s78, s3
	global_load_lds_dwordx4 v[224:225], off
	s_mov_b32 m0, s74
	s_nop 0
	global_load_lds_dwordx4 v132, s[72:73]
	s_add_i32 m0, s74, 0x2000
	s_nop 0
	global_load_lds_dwordx4 v136, s[72:73]
	s_add_i32 s76, s76, 2
	s_add_u32 s48, s48, 0x10000
	s_addc_u32 s49, s49, 0
	s_add_u32 s68, s68, 0x10000
	s_addc_u32 s69, s69, 0
	s_add_u32 s50, s48, 0x4000
	s_addc_u32 s51, s49, 0
	s_cmp_eq_u32 s76, 60
	s_cselect_b32 s74, s64, s50
	s_cselect_b32 s75, s25, s51
	s_cselect_b32 s72, s65, s68
	s_cselect_b32 s73, s19, s69
	s_add_u32 s50, s74, 0x8000
	s_addc_u32 s51, s75, 0
	s_sub_u32 s50, s48, 0x4000
	s_subb_u32 s51, s49, 0
	s_cmp_gt_u32 s76, 61
	s_waitcnt vmcnt(6)
	s_waitcnt lgkmcnt(0)
	s_barrier
	s_waitcnt lgkmcnt(0)
	v_mfma_f32_16x16x32_bf16 v[62:65], v[154:157], v[188:191], v[62:65]
	v_mfma_f32_16x16x32_bf16 v[62:65], v[158:161], v[196:199], v[62:65]
	v_mfma_f32_16x16x32_bf16 v[46:49], v[158:161], v[204:207], v[46:49]
	v_mfma_f32_16x16x32_bf16 v[46:49], v[154:157], v[200:203], v[46:49]
	v_mfma_f32_16x16x32_bf16 v[30:33], v[154:157], v[208:211], v[30:33]
	v_mfma_f32_16x16x32_bf16 v[30:33], v[158:161], v[212:215], v[30:33]
	v_mfma_f32_16x16x32_bf16 v[14:17], v[158:161], v[220:223], v[14:17]
	v_mfma_f32_16x16x32_bf16 v[14:17], v[154:157], v[216:219], v[14:17]
	v_mfma_f32_16x16x32_bf16 v[6:9], v[162:165], v[216:219], v[6:9]
	v_mfma_f32_16x16x32_bf16 v[6:9], v[166:169], v[220:223], v[6:9]
	v_mfma_f32_16x16x32_bf16 v[22:25], v[166:169], v[212:215], v[22:25]
	v_mfma_f32_16x16x32_bf16 v[22:25], v[162:165], v[208:211], v[22:25]
	v_mfma_f32_16x16x32_bf16 v[38:41], v[162:165], v[200:203], v[38:41]
	v_mfma_f32_16x16x32_bf16 v[38:41], v[166:169], v[204:207], v[38:41]
	v_mfma_f32_16x16x32_bf16 v[54:57], v[166:169], v[196:199], v[54:57]
	v_mfma_f32_16x16x32_bf16 v[54:57], v[162:165], v[188:191], v[54:57]
	v_mfma_f32_16x16x32_bf16 v[58:61], v[170:173], v[188:191], v[58:61]
	v_mfma_f32_16x16x32_bf16 v[58:61], v[174:177], v[196:199], v[58:61]
	v_mfma_f32_16x16x32_bf16 v[42:45], v[174:177], v[204:207], v[42:45]
	v_mfma_f32_16x16x32_bf16 v[42:45], v[170:173], v[200:203], v[42:45]
	v_mfma_f32_16x16x32_bf16 v[26:29], v[170:173], v[208:211], v[26:29]
	v_mfma_f32_16x16x32_bf16 v[26:29], v[174:177], v[212:215], v[26:29]
	v_mfma_f32_16x16x32_bf16 v[10:13], v[174:177], v[220:223], v[10:13]
	v_mfma_f32_16x16x32_bf16 v[10:13], v[170:173], v[216:219], v[10:13]
	v_mfma_f32_16x16x32_bf16 v[2:5], v[180:183], v[216:219], v[2:5]
	v_mfma_f32_16x16x32_bf16 v[2:5], v[184:187], v[220:223], v[2:5]
	v_mfma_f32_16x16x32_bf16 v[18:21], v[184:187], v[212:215], v[18:21]
	v_mfma_f32_16x16x32_bf16 v[18:21], v[180:183], v[208:211], v[18:21]
	v_mfma_f32_16x16x32_bf16 v[34:37], v[180:183], v[200:203], v[34:37]
	v_mfma_f32_16x16x32_bf16 v[34:37], v[184:187], v[204:207], v[34:37]
	v_mfma_f32_16x16x32_bf16 v[50:53], v[184:187], v[196:199], v[50:53]
	v_mfma_f32_16x16x32_bf16 v[50:53], v[180:183], v[188:191], v[50:53]
	s_barrier
.LBB0_115:
	ds_read_b128 v[154:157], v150
	ds_read_b128 v[158:161], v150 offset:1024
	ds_read_b128 v[162:165], v150 offset:2048
	ds_read_b128 v[166:169], v150 offset:3072
	ds_read_b128 v[170:173], v151
	ds_read_b128 v[174:177], v151 offset:1024
	ds_read_b128 v[180:183], v151 offset:2048
	ds_read_b128 v[184:187], v151 offset:3072
	s_mov_b32 m0, s58
	s_nop 0
	global_load_lds_dwordx4 v130, s[50:51]
	s_mov_b32 m0, s59
	s_nop 0
	global_load_lds_dwordx4 v134, s[50:51]
	s_add_i32 m0, s28, 0xc000
	ds_read_b128 v[188:191], v152
	ds_read_b128 v[196:199], v152 offset:1024
	ds_read_b128 v[200:203], v152 offset:2048
	ds_read_b128 v[204:207], v152 offset:3072
	ds_read_b128 v[208:211], v152 offset:4096
	ds_read_b128 v[212:215], v152 offset:5120
	ds_read_b128 v[216:219], v152 offset:6144
	ds_read_b128 v[220:223], v152 offset:7168
	global_load_lds_dwordx4 v140, s[48:49]
	s_add_i32 m0, s28, 0xe000
	s_nop 0
	global_load_lds_dwordx4 v142, s[48:49]
	s_waitcnt vmcnt(8)
	s_waitcnt lgkmcnt(0)
	s_barrier
; #define PG8_STAGE(bufoff, gbase, voff) do { _Pragma("unroll") for (int _i = 0; _i < 2; ++_i) \
;         __builtin_amdgcn_global_load_lds((const unsigned*)((const char*)(gbase) + (voff)[_i]), (PG8_LAS unsigned*)(lds + (bufoff) + ldsw + _i * 8192), 16, 0, 0); } while (0)
; #define PG8_LDA(dst, b, h) do { _Pragma("unroll") for (int m = 0; m < 4; ++m) _Pragma("unroll") for (int k = 0; k < 2; ++k) dst[m][k] = *(const PG8_LAS bf16x8*)(lds + PG8_SA(b, h) + aoff + m * 2048 + k * 1024); } while (0)
; #define PG8_LDB(dst, b, h) do { _Pragma("unroll") for (int n = 0; n < 2; ++n) _Pragma("unroll") for (int k = 0; k < 2; ++k) dst[n][k] = *(const PG8_LAS bf16x8*)(lds + PG8_SB(b, h) + boff + n * 2048 + k * 1024); } while (0)
; #define PG8_MMA(ai, bj, At, Bt) do { __builtin_amdgcn_s_setprio(1); _Pragma("unroll") for (int m = 0; m < 4; ++m) _Pragma("unroll") for (int n = 0; n < 2; ++n) _Pragma("unroll") for (int k = 0; k < 2; ++k) \
;         acc[ai][bj][m][n] = __builtin_amdgcn_mfma_f32_16x16x32_bf16(Bt[n][k], At[m][k], acc[ai][bj][m][n], 0, 0, 0); __builtin_amdgcn_s_setprio(0); } while (0)
; #define PG8_WAIT_V(n) asm volatile("s_waitcnt vmcnt(" #n ")" ::: "memory")
; #define PG8_WAIT_L(n) asm volatile("s_waitcnt lgkmcnt(" #n ")" ::: "memory")
; #define PG8_BAR __builtin_amdgcn_s_barrier()
; #define PG8_SCHED __builtin_amdgcn_sched_barrier(0)
; template <class Epi, class Sched, bool ALIGN_EPI = false, bool SP2 = false>
; __device__ __forceinline__ void gemm_phase(PG8_LAS unsigned char* lds, const Gemm g, const Sched& S, const Epi& E) {
;     ...
;             PG8_LDB(B0, 0, 0); PG8_LDB(B1, 0, 1); PG8_SCHED; PG8_LDA(At, 0, 0); PG8_STAGE(PG8_SA(1, 1), a1 + hstep, voffA);
;             PG8_WAIT_V(8); PG8_WAIT_L(0); PG8_BAR; PG8_MMA(0, 0, At, B0); PG8_MMA(0, 1, At, B1); PG8_BAR; PG8_SCHED;
;             PG8_LDA(At, 0, 1); PG8_STAGE(PG8_SB(0, 0), b2, voffB); PG8_STAGE(PG8_SB(0, 1), b2 + hstep, voffB); PG8_STAGE(PG8_SA(0, 0), a2, voffA);
;             PG8_WAIT_V(8); PG8_WAIT_L(0); PG8_BAR; PG8_MMA(1, 0, At, B0); PG8_MMA(1, 1, At, B1); PG8_BAR; PG8_SCHED;
	s_waitcnt lgkmcnt(0)
	v_mfma_f32_16x16x32_bf16 v[126:129], v[154:157], v[188:191], v[126:129]
	v_mfma_f32_16x16x32_bf16 v[126:129], v[158:161], v[196:199], v[126:129]
	v_mfma_f32_16x16x32_bf16 v[110:113], v[158:161], v[204:207], v[110:113]
	v_mfma_f32_16x16x32_bf16 v[110:113], v[154:157], v[200:203], v[110:113]
	v_mfma_f32_16x16x32_bf16 v[94:97], v[154:157], v[208:211], v[94:97]
	v_mfma_f32_16x16x32_bf16 v[94:97], v[158:161], v[212:215], v[94:97]
	v_mfma_f32_16x16x32_bf16 v[78:81], v[158:161], v[220:223], v[78:81]
	v_mfma_f32_16x16x32_bf16 v[78:81], v[154:157], v[216:219], v[78:81]
	v_mfma_f32_16x16x32_bf16 v[70:73], v[162:165], v[216:219], v[70:73]
	v_mfma_f32_16x16x32_bf16 v[70:73], v[166:169], v[220:223], v[70:73]
	v_mfma_f32_16x16x32_bf16 v[86:89], v[166:169], v[212:215], v[86:89]
	v_mfma_f32_16x16x32_bf16 v[86:89], v[162:165], v[208:211], v[86:89]
	v_mfma_f32_16x16x32_bf16 v[102:105], v[162:165], v[200:203], v[102:105]
	v_mfma_f32_16x16x32_bf16 v[102:105], v[166:169], v[204:207], v[102:105]
	v_mfma_f32_16x16x32_bf16 v[118:121], v[166:169], v[196:199], v[118:121]
	v_mfma_f32_16x16x32_bf16 v[118:121], v[162:165], v[188:191], v[118:121]
	v_mfma_f32_16x16x32_bf16 v[122:125], v[170:173], v[188:191], v[122:125]
	v_mfma_f32_16x16x32_bf16 v[122:125], v[174:177], v[196:199], v[122:125]
	v_mfma_f32_16x16x32_bf16 v[106:109], v[174:177], v[204:207], v[106:109]
	v_mfma_f32_16x16x32_bf16 v[106:109], v[170:173], v[200:203], v[106:109]
	v_mfma_f32_16x16x32_bf16 v[90:93], v[170:173], v[208:211], v[90:93]
	v_mfma_f32_16x16x32_bf16 v[90:93], v[174:177], v[212:215], v[90:93]
	v_mfma_f32_16x16x32_bf16 v[74:77], v[174:177], v[220:223], v[74:77]
	v_mfma_f32_16x16x32_bf16 v[74:77], v[170:173], v[216:219], v[74:77]
	v_mfma_f32_16x16x32_bf16 v[66:69], v[180:183], v[216:219], v[66:69]
	v_mfma_f32_16x16x32_bf16 v[66:69], v[184:187], v[220:223], v[66:69]
	v_mfma_f32_16x16x32_bf16 v[82:85], v[184:187], v[212:215], v[82:85]
	v_mfma_f32_16x16x32_bf16 v[82:85], v[180:183], v[208:211], v[82:85]
	v_mfma_f32_16x16x32_bf16 v[98:101], v[180:183], v[200:203], v[98:101]
	v_mfma_f32_16x16x32_bf16 v[98:101], v[184:187], v[204:207], v[98:101]
	v_mfma_f32_16x16x32_bf16 v[114:117], v[184:187], v[196:199], v[114:117]
	v_mfma_f32_16x16x32_bf16 v[114:117], v[180:183], v[188:191], v[114:117]
	s_barrier
	s_add_i32 s77, s61, s3
	s_mov_b32 m0, s77
	ds_read_b128 v[188:191], v152 offset:16384
	ds_read_b128 v[196:199], v152 offset:17408
	ds_read_b128 v[200:203], v152 offset:18432
	ds_read_b128 v[204:207], v152 offset:19456
	ds_read_b128 v[208:211], v152 offset:20480
	ds_read_b128 v[212:215], v152 offset:21504
	ds_read_b128 v[216:219], v152 offset:22528
	ds_read_b128 v[220:223], v152 offset:23552
	global_load_lds_dwordx4 v132, s[72:73]
	s_add_i32 m0, s77, 0x2000
	s_add_u32 s78, s72, 0x4000
	s_addc_u32 s79, s73, 0
	s_add_i32 s77, s62, s3
	global_load_lds_dwordx4 v136, s[72:73]
	s_mov_b32 m0, s77
	s_nop 0
	global_load_lds_dwordx4 v132, s[78:79]
	s_add_i32 m0, s77, 0x2000
	s_nop 0
	global_load_lds_dwordx4 v136, s[78:79]
	s_waitcnt vmcnt(6)
	s_waitcnt lgkmcnt(0)
	s_barrier
	s_waitcnt lgkmcnt(0)
	v_mfma_f32_16x16x32_bf16 v[62:65], v[154:157], v[188:191], v[62:65]
	v_mfma_f32_16x16x32_bf16 v[62:65], v[158:161], v[196:199], v[62:65]
	v_mfma_f32_16x16x32_bf16 v[46:49], v[158:161], v[204:207], v[46:49]
	v_mfma_f32_16x16x32_bf16 v[46:49], v[154:157], v[200:203], v[46:49]
	v_mfma_f32_16x16x32_bf16 v[30:33], v[154:157], v[208:211], v[30:33]
	v_mfma_f32_16x16x32_bf16 v[30:33], v[158:161], v[212:215], v[30:33]
	v_mfma_f32_16x16x32_bf16 v[14:17], v[158:161], v[220:223], v[14:17]
	v_mfma_f32_16x16x32_bf16 v[14:17], v[154:157], v[216:219], v[14:17]
	v_mfma_f32_16x16x32_bf16 v[6:9], v[162:165], v[216:219], v[6:9]
	v_mfma_f32_16x16x32_bf16 v[6:9], v[166:169], v[220:223], v[6:9]
	v_mfma_f32_16x16x32_bf16 v[22:25], v[166:169], v[212:215], v[22:25]
	v_mfma_f32_16x16x32_bf16 v[22:25], v[162:165], v[208:211], v[22:25]
	v_mfma_f32_16x16x32_bf16 v[38:41], v[162:165], v[200:203], v[38:41]
	v_mfma_f32_16x16x32_bf16 v[38:41], v[166:169], v[204:207], v[38:41]
	v_mfma_f32_16x16x32_bf16 v[54:57], v[166:169], v[196:199], v[54:57]
	v_mfma_f32_16x16x32_bf16 v[54:57], v[162:165], v[188:191], v[54:57]
	v_mfma_f32_16x16x32_bf16 v[58:61], v[170:173], v[188:191], v[58:61]
	v_mfma_f32_16x16x32_bf16 v[58:61], v[174:177], v[196:199], v[58:61]
	v_mfma_f32_16x16x32_bf16 v[42:45], v[174:177], v[204:207], v[42:45]
	v_mfma_f32_16x16x32_bf16 v[42:45], v[170:173], v[200:203], v[42:45]
	v_mfma_f32_16x16x32_bf16 v[26:29], v[170:173], v[208:211], v[26:29]
	v_mfma_f32_16x16x32_bf16 v[26:29], v[174:177], v[212:215], v[26:29]
	v_mfma_f32_16x16x32_bf16 v[10:13], v[174:177], v[220:223], v[10:13]
	v_mfma_f32_16x16x32_bf16 v[10:13], v[170:173], v[216:219], v[10:13]
	v_mfma_f32_16x16x32_bf16 v[2:5], v[180:183], v[216:219], v[2:5]
	v_mfma_f32_16x16x32_bf16 v[2:5], v[184:187], v[220:223], v[2:5]
	v_mfma_f32_16x16x32_bf16 v[18:21], v[184:187], v[212:215], v[18:21]
	v_mfma_f32_16x16x32_bf16 v[18:21], v[180:183], v[208:211], v[18:21]
	v_mfma_f32_16x16x32_bf16 v[34:37], v[180:183], v[200:203], v[34:37]
	v_mfma_f32_16x16x32_bf16 v[34:37], v[184:187], v[204:207], v[34:37]
	v_mfma_f32_16x16x32_bf16 v[50:53], v[184:187], v[196:199], v[50:53]
	v_mfma_f32_16x16x32_bf16 v[50:53], v[180:183], v[188:191], v[50:53]
	s_barrier
; #define PG8_STAGE(bufoff, gbase, voff) do { _Pragma("unroll") for (int _i = 0; _i < 2; ++_i) \
;         __builtin_amdgcn_global_load_lds((const unsigned*)((const char*)(gbase) + (voff)[_i]), (PG8_LAS unsigned*)(lds + (bufoff) + ldsw + _i * 8192), 16, 0, 0); } while (0)
; #define PG8_LDA(dst, b, h) do { _Pragma("unroll") for (int m = 0; m < 4; ++m) _Pragma("unroll") for (int k = 0; k < 2; ++k) dst[m][k] = *(const PG8_LAS bf16x8*)(lds + PG8_SA(b, h) + aoff + m * 2048 + k * 1024); } while (0)
; #define PG8_LDB(dst, b, h) do { _Pragma("unroll") for (int n = 0; n < 2; ++n) _Pragma("unroll") for (int k = 0; k < 2; ++k) dst[n][k] = *(const PG8_LAS bf16x8*)(lds + PG8_SB(b, h) + boff + n * 2048 + k * 1024); } while (0)
; #define PG8_MMA(ai, bj, At, Bt) do { __builtin_amdgcn_s_setprio(1); _Pragma("unroll") for (int m = 0; m < 4; ++m) _Pragma("unroll") for (int n = 0; n < 2; ++n) _Pragma("unroll") for (int k = 0; k < 2; ++k) \
;         acc[ai][bj][m][n] = __builtin_amdgcn_mfma_f32_16x16x32_bf16(Bt[n][k], At[m][k], acc[ai][bj][m][n], 0, 0, 0); __builtin_amdgcn_s_setprio(0); } while (0)
; #define PG8_WAIT_V(n) asm volatile("s_waitcnt vmcnt(" #n ")" ::: "memory")
; #define PG8_WAIT_L(n) asm volatile("s_waitcnt lgkmcnt(" #n ")" ::: "memory")
; #define PG8_BAR __builtin_amdgcn_s_barrier()
; #define PG8_SCHED __builtin_amdgcn_sched_barrier(0)
; template <class Epi, class Sched, bool ALIGN_EPI = false, bool SP2 = false>
; __device__ __forceinline__ void gemm_phase(PG8_LAS unsigned char* lds, const Gemm g, const Sched& S, const Epi& E) {
;     ...
;             PG8_LDB(B0, 1, 0); PG8_LDB(B1, 1, 1); PG8_SCHED; PG8_LDA(At, 1, 0); PG8_STAGE(PG8_SA(0, 1), a2 + hstep, voffA);
;             PG8_WAIT_V(8); PG8_WAIT_L(0); PG8_BAR; PG8_MMA(0, 0, At, B0); PG8_MMA(0, 1, At, B1); PG8_BAR; PG8_SCHED;
	s_add_i32 s77, 0, 0x18000
	v_add_u32_e32 v138, s77, v148
	s_add_i32 s78, 0, 0x1c000
	ds_read_b128 v[154:157], v138
	ds_read_b128 v[158:161], v138 offset:1024
	ds_read_b128 v[162:165], v138 offset:2048
	ds_read_b128 v[166:169], v138 offset:3072
	v_add_u32_e32 v138, s78, v148
	ds_read_b128 v[170:173], v138
	ds_read_b128 v[174:177], v138 offset:1024
	ds_read_b128 v[180:183], v138 offset:2048
	ds_read_b128 v[184:187], v138 offset:3072
	s_mov_b32 m0, s28
	s_nop 0
	global_load_lds_dwordx4 v130, s[74:75]
	s_mov_b32 m0, s29
	s_nop 0
	global_load_lds_dwordx4 v134, s[74:75]
	s_add_u32 s74, s74, 0x4000
	s_addc_u32 s75, s75, 0
	s_mov_b32 m0, s30
	ds_read_b128 v[188:191], v152 offset:32768
	ds_read_b128 v[196:199], v152 offset:33792
	ds_read_b128 v[200:203], v152 offset:34816
	ds_read_b128 v[204:207], v152 offset:35840
	ds_read_b128 v[208:211], v152 offset:36864
	ds_read_b128 v[212:215], v152 offset:37888
	ds_read_b128 v[216:219], v152 offset:38912
	ds_read_b128 v[220:223], v152 offset:39936
	global_load_lds_dwordx4 v130, s[74:75]
	s_mov_b32 m0, s31
	s_nop 0
	global_load_lds_dwordx4 v134, s[74:75]
	s_waitcnt vmcnt(8)
	s_waitcnt lgkmcnt(0)
	s_barrier
	s_waitcnt lgkmcnt(0)
	v_mfma_f32_16x16x32_bf16 v[126:129], v[154:157], v[188:191], v[126:129]
	v_mfma_f32_16x16x32_bf16 v[126:129], v[158:161], v[196:199], v[126:129]
	v_mfma_f32_16x16x32_bf16 v[110:113], v[158:161], v[204:207], v[110:113]
	v_mfma_f32_16x16x32_bf16 v[110:113], v[154:157], v[200:203], v[110:113]
	v_mfma_f32_16x16x32_bf16 v[94:97], v[154:157], v[208:211], v[94:97]
	v_mfma_f32_16x16x32_bf16 v[94:97], v[158:161], v[212:215], v[94:97]
	v_mfma_f32_16x16x32_bf16 v[78:81], v[158:161], v[220:223], v[78:81]
	v_mfma_f32_16x16x32_bf16 v[78:81], v[154:157], v[216:219], v[78:81]
	v_mfma_f32_16x16x32_bf16 v[70:73], v[162:165], v[216:219], v[70:73]
	v_mfma_f32_16x16x32_bf16 v[70:73], v[166:169], v[220:223], v[70:73]
	v_mfma_f32_16x16x32_bf16 v[86:89], v[166:169], v[212:215], v[86:89]
	v_mfma_f32_16x16x32_bf16 v[86:89], v[162:165], v[208:211], v[86:89]
	v_mfma_f32_16x16x32_bf16 v[102:105], v[162:165], v[200:203], v[102:105]
	v_mfma_f32_16x16x32_bf16 v[102:105], v[166:169], v[204:207], v[102:105]
	v_mfma_f32_16x16x32_bf16 v[118:121], v[166:169], v[196:199], v[118:121]
	v_mfma_f32_16x16x32_bf16 v[118:121], v[162:165], v[188:191], v[118:121]
	v_mfma_f32_16x16x32_bf16 v[122:125], v[170:173], v[188:191], v[122:125]
	v_mfma_f32_16x16x32_bf16 v[122:125], v[174:177], v[196:199], v[122:125]
	v_mfma_f32_16x16x32_bf16 v[106:109], v[174:177], v[204:207], v[106:109]
	v_mfma_f32_16x16x32_bf16 v[106:109], v[170:173], v[200:203], v[106:109]
	v_mfma_f32_16x16x32_bf16 v[90:93], v[170:173], v[208:211], v[90:93]
	v_mfma_f32_16x16x32_bf16 v[90:93], v[174:177], v[212:215], v[90:93]
	v_mfma_f32_16x16x32_bf16 v[74:77], v[174:177], v[220:223], v[74:77]
	v_mfma_f32_16x16x32_bf16 v[74:77], v[170:173], v[216:219], v[74:77]
	v_mfma_f32_16x16x32_bf16 v[66:69], v[180:183], v[216:219], v[66:69]
	v_mfma_f32_16x16x32_bf16 v[66:69], v[184:187], v[220:223], v[66:69]
	v_mfma_f32_16x16x32_bf16 v[82:85], v[184:187], v[212:215], v[82:85]
	v_mfma_f32_16x16x32_bf16 v[82:85], v[180:183], v[208:211], v[82:85]
	v_mfma_f32_16x16x32_bf16 v[98:101], v[180:183], v[200:203], v[98:101]
	v_mfma_f32_16x16x32_bf16 v[98:101], v[184:187], v[204:207], v[98:101]
	v_mfma_f32_16x16x32_bf16 v[114:117], v[184:187], v[196:199], v[114:117]
	v_mfma_f32_16x16x32_bf16 v[114:117], v[180:183], v[188:191], v[114:117]
	s_barrier
; #define PG8_STAGE(bufoff, gbase, voff) do { _Pragma("unroll") for (int _i = 0; _i < 2; ++_i) \
;         __builtin_amdgcn_global_load_lds((const unsigned*)((const char*)(gbase) + (voff)[_i]), (PG8_LAS unsigned*)(lds + (bufoff) + ldsw + _i * 8192), 16, 0, 0); } while (0)
; #define PG8_LDA(dst, b, h) do { _Pragma("unroll") for (int m = 0; m < 4; ++m) _Pragma("unroll") for (int k = 0; k < 2; ++k) dst[m][k] = *(const PG8_LAS bf16x8*)(lds + PG8_SA(b, h) + aoff + m * 2048 + k * 1024); } while (0)
; #define PG8_LDB(dst, b, h) do { _Pragma("unroll") for (int n = 0; n < 2; ++n) _Pragma("unroll") for (int k = 0; k < 2; ++k) dst[n][k] = *(const PG8_LAS bf16x8*)(lds + PG8_SB(b, h) + boff + n * 2048 + k * 1024); } while (0)
; template <class Epi, class Sched, bool ALIGN_EPI = false, bool SP2 = false>
; __device__ __forceinline__ void gemm_phase(PG8_LAS unsigned char* lds, const Gemm g, const Sched& S, const Epi& E) {
;     ...
;         for (; t < tend; t += 2) {
;             const bool last = (t == nt - 2);
;             const char* a1 = cA + (size_t)(t + 1) * kstep;
;             const char* a2 = last ? nA : cA + (size_t)(t + 2) * kstep; const char* b2 = last ? nB : cB + (size_t)(t + 2) * kstep;
;             const char* a3 = a2 + kstep; const char* b3 = b2 + kstep;
;             if (last && has_next) S.a_ready(nxt);
;             if constexpr (SP2) {
;             PG8_LDB(B0, 0, 0); PG8_LDB(B1, 0, 1); PG8_SCHED; PG8_LDA(At, 0, 0); PG8_STAGE(PG8_SA(1, 1), a1 + hstep, voffA);
;             PG8_WAIT_V(8); PG8_WAIT_L(0); PG8_BAR; PG8_MMA(0, 0, At, B0); PG8_MMA(0, 1, At, B1); PG8_BAR; PG8_SCHED;
;             PG8_LDA(At, 0, 1); PG8_STAGE(PG8_SB(0, 0), b2, voffB); PG8_STAGE(PG8_SB(0, 1), b2 + hstep, voffB); PG8_STAGE(PG8_SA(0, 0), a2, voffA);
;             PG8_WAIT_V(8); PG8_WAIT_L(0); PG8_BAR; PG8_MMA(1, 0, At, B0); PG8_MMA(1, 1, At, B1); PG8_BAR; PG8_SCHED;
;             PG8_LDB(B0, 1, 0); PG8_LDB(B1, 1, 1); PG8_SCHED; PG8_LDA(At, 1, 0); PG8_STAGE(PG8_SA(0, 1), a2 + hstep, voffA);
;             PG8_WAIT_V(8); PG8_WAIT_L(0); PG8_BAR; PG8_MMA(0, 0, At, B0); PG8_MMA(0, 1, At, B1); PG8_BAR; PG8_SCHED;
;             PG8_LDA(At, 1, 1); PG8_STAGE(PG8_SB(1, 0), b3, voffB); PG8_STAGE(PG8_SB(1, 1), b3 + hstep, voffB); PG8_STAGE(PG8_SA(1, 0), a3, voffA);
;             PG8_WAIT_V(8); PG8_WAIT_L(0); PG8_BAR; PG8_MMA(1, 0, At, B0); PG8_MMA(1, 1, At, B1); PG8_BAR; PG8_SCHED;
	s_add_u32 s74, s72, 0x8000
	s_addc_u32 s75, s73, 0
	s_add_i32 s77, s77, s3
	s_mov_b32 m0, s77
	ds_read_b128 v[188:191], v152 offset:49152
	ds_read_b128 v[196:199], v152 offset:50176
	ds_read_b128 v[200:203], v152 offset:51200
	ds_read_b128 v[204:207], v152 offset:52224
	ds_read_b128 v[208:211], v152 offset:53248
	ds_read_b128 v[212:215], v152 offset:54272
	ds_read_b128 v[216:219], v152 offset:55296
	ds_read_b128 v[220:223], v152 offset:56320
	global_load_lds_dwordx4 v132, s[74:75]
	s_add_i32 m0, s77, 0x2000
	s_add_u32 s72, s72, 0xc000
	v_lshl_add_u64 v[224:225], s[74:75], 0, v[136:137]
	s_addc_u32 s73, s73, 0
	s_add_i32 s74, s78, s3
	global_load_lds_dwordx4 v[224:225], off
	s_mov_b32 m0, s74
	s_nop 0
	global_load_lds_dwordx4 v132, s[72:73]
	s_add_i32 m0, s74, 0x2000
	s_nop 0
	global_load_lds_dwordx4 v136, s[72:73]
	s_add_i32 s76, s76, 2
	s_add_u32 s48, s48, 0x10000
	s_addc_u32 s49, s49, 0
	s_add_u32 s68, s68, 0x10000
	s_addc_u32 s69, s69, 0
	s_add_u32 s50, s48, 0x4000
	s_addc_u32 s51, s49, 0
	s_cmp_eq_u32 s76, 60
	s_cselect_b32 s74, s64, s50
	s_cselect_b32 s75, s25, s51
	s_cselect_b32 s72, s65, s68
	s_cselect_b32 s73, s19, s69
	s_add_u32 s50, s74, 0x8000
	s_addc_u32 s51, s75, 0
	s_sub_u32 s50, s48, 0x4000
	s_subb_u32 s51, s49, 0
	s_cmp_gt_u32 s76, 61
	s_waitcnt vmcnt(6)
	s_waitcnt lgkmcnt(0)
	s_barrier
	s_waitcnt lgkmcnt(0)
	v_mfma_f32_16x16x32_bf16 v[62:65], v[154:157], v[188:191], v[62:65]
	v_mfma_f32_16x16x32_bf16 v[62:65], v[158:161], v[196:199], v[62:65]
	v_mfma_f32_16x16x32_bf16 v[46:49], v[158:161], v[204:207], v[46:49]
	v_mfma_f32_16x16x32_bf16 v[46:49], v[154:157], v[200:203], v[46:49]
	v_mfma_f32_16x16x32_bf16 v[30:33], v[154:157], v[208:211], v[30:33]
	v_mfma_f32_16x16x32_bf16 v[30:33], v[158:161], v[212:215], v[30:33]
	v_mfma_f32_16x16x32_bf16 v[14:17], v[158:161], v[220:223], v[14:17]
	v_mfma_f32_16x16x32_bf16 v[14:17], v[154:157], v[216:219], v[14:17]
	v_mfma_f32_16x16x32_bf16 v[6:9], v[162:165], v[216:219], v[6:9]
	v_mfma_f32_16x16x32_bf16 v[6:9], v[166:169], v[220:223], v[6:9]
	v_mfma_f32_16x16x32_bf16 v[22:25], v[166:169], v[212:215], v[22:25]
	v_mfma_f32_16x16x32_bf16 v[22:25], v[162:165], v[208:211], v[22:25]
	v_mfma_f32_16x16x32_bf16 v[38:41], v[162:165], v[200:203], v[38:41]
	v_mfma_f32_16x16x32_bf16 v[38:41], v[166:169], v[204:207], v[38:41]
	v_mfma_f32_16x16x32_bf16 v[54:57], v[166:169], v[196:199], v[54:57]
	v_mfma_f32_16x16x32_bf16 v[54:57], v[162:165], v[188:191], v[54:57]
	v_mfma_f32_16x16x32_bf16 v[58:61], v[170:173], v[188:191], v[58:61]
	v_mfma_f32_16x16x32_bf16 v[58:61], v[174:177], v[196:199], v[58:61]
	v_mfma_f32_16x16x32_bf16 v[42:45], v[174:177], v[204:207], v[42:45]
	v_mfma_f32_16x16x32_bf16 v[42:45], v[170:173], v[200:203], v[42:45]
	v_mfma_f32_16x16x32_bf16 v[26:29], v[170:173], v[208:211], v[26:29]
	v_mfma_f32_16x16x32_bf16 v[26:29], v[174:177], v[212:215], v[26:29]
	v_mfma_f32_16x16x32_bf16 v[10:13], v[174:177], v[220:223], v[10:13]
	v_mfma_f32_16x16x32_bf16 v[10:13], v[170:173], v[216:219], v[10:13]
	v_mfma_f32_16x16x32_bf16 v[2:5], v[180:183], v[216:219], v[2:5]
	v_mfma_f32_16x16x32_bf16 v[2:5], v[184:187], v[220:223], v[2:5]
	v_mfma_f32_16x16x32_bf16 v[18:21], v[184:187], v[212:215], v[18:21]
	v_mfma_f32_16x16x32_bf16 v[18:21], v[180:183], v[208:211], v[18:21]
	v_mfma_f32_16x16x32_bf16 v[34:37], v[180:183], v[200:203], v[34:37]
	v_mfma_f32_16x16x32_bf16 v[34:37], v[184:187], v[204:207], v[34:37]
	v_mfma_f32_16x16x32_bf16 v[50:53], v[184:187], v[196:199], v[50:53]
	v_mfma_f32_16x16x32_bf16 v[50:53], v[180:183], v[188:191], v[50:53]
	s_barrier
	s_cbranch_scc0 .LBB0_115
	s_and_b64 vcc, exec, s[14:15]
	s_cbranch_vccz .LBB0_118
	s_barrier

;     __device__ __forceinline__ bool next(int i, Unit& u) const { if (i >= 2) return false; const int xcd = c & 7, off = c >> 3; u.pm = 16 * i + 4 * (xcd >> 1) + (off & 3); u.pn = 8 * (xcd & 1) + (off >> 2); return true; }
; #define PG8_STAGE(bufoff, gbase, voff) do { _Pragma("unroll") for (int _i = 0; _i < 2; ++_i) \
;         __builtin_amdgcn_global_load_lds((const unsigned*)((const char*)(gbase) + (voff)[_i]), (PG8_LAS unsigned*)(lds + (bufoff) + ldsw + _i * 8192), 16, 0, 0); } while (0)
; #define PG8_LDA(dst, b, h) do { _Pragma("unroll") for (int m = 0; m < 4; ++m) _Pragma("unroll") for (int k = 0; k < 2; ++k) dst[m][k] = *(const PG8_LAS bf16x8*)(lds + PG8_SA(b, h) + aoff + m * 2048 + k * 1024); } while (0)
; #define PG8_WAIT_V(n) asm volatile("s_waitcnt vmcnt(" #n ")" ::: "memory")
; #define PG8_BAR __builtin_amdgcn_s_barrier()
; template <class Epi, class Sched, bool ALIGN_EPI = false, bool SP2 = false>
; __device__ __forceinline__ void gemm_phase(PG8_LAS unsigned char* lds, const Gemm g, const Sched& S, const Epi& E) {
;     ...
;         const bool has_next = S.next(ui + 1, nxt);
;         const char* nA = has_next ? (const char*)g.A + (size_t)nxt.pm * tstep : cA; const char* nB = has_next ? (const char*)g.Bt + (size_t)nxt.pn * tstep : cB;
;         constexpr int NSEG = Epi::HAS_MID ? 2 : 1; int t = 0;
; #pragma unroll
;         for (int seg = 0; seg < NSEG; ++seg) { const int tend = (seg + 1 < NSEG) ? (nt >> 1) : nt;
;         for (; t < tend; t += 2) {
;             const bool last = (t == nt - 2);
;             const char* a1 = cA + (size_t)(t + 1) * kstep;
;             const char* a2 = last ? nA : cA + (size_t)(t + 2) * kstep; const char* b2 = last ? nB : cB + (size_t)(t + 2) * kstep;
;             const char* a3 = a2 + kstep; const char* b3 = b2 + kstep;
;             if (last && has_next) S.a_ready(nxt);
;             if constexpr (SP2) {
;             PG8_LDB(B0, 0, 0); PG8_LDB(B1, 0, 1); PG8_SCHED; PG8_LDA(At, 0, 0); PG8_STAGE(PG8_SA(1, 1), a1 + hstep, voffA);
;             PG8_WAIT_V(8); PG8_WAIT_L(0); PG8_BAR; PG8_MMA(0, 0, At, B0); PG8_MMA(0, 1, At, B1); PG8_BAR; PG8_SCHED;
;             PG8_LDA(At, 0, 1); PG8_STAGE(PG8_SB(0, 0), b2, voffB); PG8_STAGE(PG8_SB(0, 1), b2 + hstep, voffB); PG8_STAGE(PG8_SA(0, 0), a2, voffA);
;             PG8_WAIT_V(8); PG8_WAIT_L(0); PG8_BAR; PG8_MMA(1, 0, At, B0); PG8_MMA(1, 1, At, B1); PG8_BAR; PG8_SCHED;
.LBB0_199:
	s_add_u32 s44, s44, 0xc000
	s_addc_u32 s45, s45, 0
	s_add_u32 s74, s46, 0x10000
	s_addc_u32 s75, s47, 0
	s_mov_b32 s76, -2
	s_waitcnt lgkmcnt(0)
	s_nop 3
	s_add_u32 s46, s44, 0x4000
	s_addc_u32 s47, s45, 0
	s_cmpk_eq_i32 s76, 0xa8
	s_cselect_b32 s50, s6, s46
	s_cselect_b32 s51, s7, s47
	s_cselect_b32 s48, s24, s74
	s_cselect_b32 s49, s25, s75
	s_add_u32 s46, s50, 0x8000
	s_addc_u32 s47, s51, 0
	s_sub_u32 s46, s44, 0x4000
	s_subb_u32 s47, s45, 0
	ds_read_b128 v[148:151], v154
	ds_read_b128 v[158:161], v154 offset:1024
	ds_read_b128 v[162:165], v154 offset:2048
	ds_read_b128 v[166:169], v154 offset:3072
	ds_read_b128 v[170:173], v155
	ds_read_b128 v[174:177], v155 offset:1024
	ds_read_b128 v[180:183], v155 offset:2048
	ds_read_b128 v[184:187], v155 offset:3072
	s_mov_b32 m0, s57
	s_nop 0
	global_load_lds_dwordx4 v130, s[46:47]
	s_mov_b32 m0, s58
	s_nop 0
	global_load_lds_dwordx4 v134, s[46:47]
	s_add_i32 m0, s26, 0xc000
	ds_read_b128 v[188:191], v156
	ds_read_b128 v[196:199], v156 offset:1024
	ds_read_b128 v[200:203], v156 offset:2048
	ds_read_b128 v[204:207], v156 offset:3072
	ds_read_b128 v[208:211], v156 offset:4096
	ds_read_b128 v[212:215], v156 offset:5120
	ds_read_b128 v[216:219], v156 offset:6144
	ds_read_b128 v[220:223], v156 offset:7168
	global_load_lds_dwordx4 v140, s[44:45]
	s_add_i32 m0, s26, 0xe000
	s_nop 0
	global_load_lds_dwordx4 v142, s[44:45]
	s_waitcnt vmcnt(8)
	s_waitcnt lgkmcnt(0)
	s_barrier
	s_waitcnt lgkmcnt(0)
	v_mfma_f32_16x16x32_bf16 v[126:129], v[148:151], v[188:191], 0
	v_mfma_f32_16x16x32_bf16 v[126:129], v[158:161], v[196:199], v[126:129]
	v_mfma_f32_16x16x32_bf16 v[110:113], v[158:161], v[204:207], 0
	v_mfma_f32_16x16x32_bf16 v[110:113], v[148:151], v[200:203], v[110:113]
	v_mfma_f32_16x16x32_bf16 v[94:97], v[148:151], v[208:211], 0
	v_mfma_f32_16x16x32_bf16 v[94:97], v[158:161], v[212:215], v[94:97]
	v_mfma_f32_16x16x32_bf16 v[78:81], v[158:161], v[220:223], 0
	v_mfma_f32_16x16x32_bf16 v[78:81], v[148:151], v[216:219], v[78:81]
	v_mfma_f32_16x16x32_bf16 v[74:77], v[162:165], v[216:219], 0
	v_mfma_f32_16x16x32_bf16 v[74:77], v[166:169], v[220:223], v[74:77]
	v_mfma_f32_16x16x32_bf16 v[90:93], v[166:169], v[212:215], 0
	v_mfma_f32_16x16x32_bf16 v[90:93], v[162:165], v[208:211], v[90:93]
	v_mfma_f32_16x16x32_bf16 v[106:109], v[162:165], v[200:203], 0
	v_mfma_f32_16x16x32_bf16 v[106:109], v[166:169], v[204:207], v[106:109]
	v_mfma_f32_16x16x32_bf16 v[122:125], v[166:169], v[196:199], 0
	v_mfma_f32_16x16x32_bf16 v[122:125], v[162:165], v[188:191], v[122:125]
	v_mfma_f32_16x16x32_bf16 v[118:121], v[170:173], v[188:191], 0
	v_mfma_f32_16x16x32_bf16 v[118:121], v[174:177], v[196:199], v[118:121]
	v_mfma_f32_16x16x32_bf16 v[102:105], v[174:177], v[204:207], 0
	v_mfma_f32_16x16x32_bf16 v[102:105], v[170:173], v[200:203], v[102:105]
	v_mfma_f32_16x16x32_bf16 v[86:89], v[170:173], v[208:211], 0
	v_mfma_f32_16x16x32_bf16 v[86:89], v[174:177], v[212:215], v[86:89]
	v_mfma_f32_16x16x32_bf16 v[70:73], v[174:177], v[220:223], 0
	v_mfma_f32_16x16x32_bf16 v[70:73], v[170:173], v[216:219], v[70:73]
	v_mfma_f32_16x16x32_bf16 v[66:69], v[180:183], v[216:219], 0
	v_mfma_f32_16x16x32_bf16 v[66:69], v[184:187], v[220:223], v[66:69]
	v_mfma_f32_16x16x32_bf16 v[82:85], v[184:187], v[212:215], 0
	v_mfma_f32_16x16x32_bf16 v[82:85], v[180:183], v[208:211], v[82:85]
	v_mfma_f32_16x16x32_bf16 v[98:101], v[180:183], v[200:203], 0
	v_mfma_f32_16x16x32_bf16 v[98:101], v[184:187], v[204:207], v[98:101]
	v_mfma_f32_16x16x32_bf16 v[114:117], v[184:187], v[196:199], 0
	v_mfma_f32_16x16x32_bf16 v[114:117], v[180:183], v[188:191], v[114:117]
	s_barrier
	s_add_i32 s77, s59, s3
	s_mov_b32 m0, s77
	ds_read_b128 v[188:191], v156 offset:16384
	ds_read_b128 v[196:199], v156 offset:17408
	ds_read_b128 v[200:203], v156 offset:18432
	ds_read_b128 v[204:207], v156 offset:19456
	ds_read_b128 v[208:211], v156 offset:20480
	ds_read_b128 v[212:215], v156 offset:21504
	ds_read_b128 v[216:219], v156 offset:22528
	ds_read_b128 v[220:223], v156 offset:23552
	global_load_lds_dwordx4 v132, s[48:49]
	s_add_i32 m0, s77, 0x2000
	s_add_u32 s78, s48, 0x4000
	s_addc_u32 s79, s49, 0
	s_add_i32 s77, s61, s3
	global_load_lds_dwordx4 v136, s[48:49]
	s_mov_b32 m0, s77
	s_nop 0
	global_load_lds_dwordx4 v132, s[78:79]
	s_add_i32 m0, s77, 0x2000
	s_nop 0
	global_load_lds_dwordx4 v136, s[78:79]
	s_waitcnt vmcnt(6)
	s_waitcnt lgkmcnt(0)
	s_barrier
	s_waitcnt lgkmcnt(0)
	v_mfma_f32_16x16x32_bf16 v[62:65], v[148:151], v[188:191], 0
	v_mfma_f32_16x16x32_bf16 v[62:65], v[158:161], v[196:199], v[62:65]
	v_mfma_f32_16x16x32_bf16 v[46:49], v[158:161], v[204:207], 0
	v_mfma_f32_16x16x32_bf16 v[46:49], v[148:151], v[200:203], v[46:49]
	v_mfma_f32_16x16x32_bf16 v[30:33], v[148:151], v[208:211], 0
	v_mfma_f32_16x16x32_bf16 v[30:33], v[158:161], v[212:215], v[30:33]
	v_mfma_f32_16x16x32_bf16 v[14:17], v[158:161], v[220:223], 0
	v_mfma_f32_16x16x32_bf16 v[14:17], v[148:151], v[216:219], v[14:17]
	v_mfma_f32_16x16x32_bf16 v[10:13], v[162:165], v[216:219], 0
	v_mfma_f32_16x16x32_bf16 v[10:13], v[166:169], v[220:223], v[10:13]
	v_mfma_f32_16x16x32_bf16 v[26:29], v[166:169], v[212:215], 0
	v_mfma_f32_16x16x32_bf16 v[26:29], v[162:165], v[208:211], v[26:29]
	v_mfma_f32_16x16x32_bf16 v[42:45], v[162:165], v[200:203], 0
	v_mfma_f32_16x16x32_bf16 v[42:45], v[166:169], v[204:207], v[42:45]
	v_mfma_f32_16x16x32_bf16 v[58:61], v[166:169], v[196:199], 0
	v_mfma_f32_16x16x32_bf16 v[58:61], v[162:165], v[188:191], v[58:61]
	v_mfma_f32_16x16x32_bf16 v[54:57], v[170:173], v[188:191], 0
	v_mfma_f32_16x16x32_bf16 v[54:57], v[174:177], v[196:199], v[54:57]
	v_mfma_f32_16x16x32_bf16 v[38:41], v[174:177], v[204:207], 0
	v_mfma_f32_16x16x32_bf16 v[38:41], v[170:173], v[200:203], v[38:41]
	v_mfma_f32_16x16x32_bf16 v[22:25], v[170:173], v[208:211], 0
	v_mfma_f32_16x16x32_bf16 v[22:25], v[174:177], v[212:215], v[22:25]
	v_mfma_f32_16x16x32_bf16 v[6:9], v[174:177], v[220:223], 0
	v_mfma_f32_16x16x32_bf16 v[6:9], v[170:173], v[216:219], v[6:9]
	v_mfma_f32_16x16x32_bf16 v[2:5], v[180:183], v[216:219], 0
	v_mfma_f32_16x16x32_bf16 v[2:5], v[184:187], v[220:223], v[2:5]
	v_mfma_f32_16x16x32_bf16 v[18:21], v[184:187], v[212:215], 0
	v_mfma_f32_16x16x32_bf16 v[18:21], v[180:183], v[208:211], v[18:21]
	v_mfma_f32_16x16x32_bf16 v[34:37], v[180:183], v[200:203], 0
	v_mfma_f32_16x16x32_bf16 v[34:37], v[184:187], v[204:207], v[34:37]
	v_mfma_f32_16x16x32_bf16 v[50:53], v[184:187], v[196:199], 0
	v_mfma_f32_16x16x32_bf16 v[50:53], v[180:183], v[188:191], v[50:53]
	s_barrier
; #define PG8_STAGE(bufoff, gbase, voff) do { _Pragma("unroll") for (int _i = 0; _i < 2; ++_i) \
;         __builtin_amdgcn_global_load_lds((const unsigned*)((const char*)(gbase) + (voff)[_i]), (PG8_LAS unsigned*)(lds + (bufoff) + ldsw + _i * 8192), 16, 0, 0); } while (0)
; #define PG8_LDA(dst, b, h) do { _Pragma("unroll") for (int m = 0; m < 4; ++m) _Pragma("unroll") for (int k = 0; k < 2; ++k) dst[m][k] = *(const PG8_LAS bf16x8*)(lds + PG8_SA(b, h) + aoff + m * 2048 + k * 1024); } while (0)
; #define PG8_LDB(dst, b, h) do { _Pragma("unroll") for (int n = 0; n < 2; ++n) _Pragma("unroll") for (int k = 0; k < 2; ++k) dst[n][k] = *(const PG8_LAS bf16x8*)(lds + PG8_SB(b, h) + boff + n * 2048 + k * 1024); } while (0)
; template <class Epi, class Sched, bool ALIGN_EPI = false, bool SP2 = false>
; __device__ __forceinline__ void gemm_phase(PG8_LAS unsigned char* lds, const Gemm g, const Sched& S, const Epi& E) {
;     ...
;         for (; t < tend; t += 2) {
;             const bool last = (t == nt - 2);
;             const char* a1 = cA + (size_t)(t + 1) * kstep;
;             const char* a2 = last ? nA : cA + (size_t)(t + 2) * kstep; const char* b2 = last ? nB : cB + (size_t)(t + 2) * kstep;
;             const char* a3 = a2 + kstep; const char* b3 = b2 + kstep;
;             if (last && has_next) S.a_ready(nxt);
;             if constexpr (SP2) {
;             PG8_LDB(B0, 0, 0); PG8_LDB(B1, 0, 1); PG8_SCHED; PG8_LDA(At, 0, 0); PG8_STAGE(PG8_SA(1, 1), a1 + hstep, voffA);
;             PG8_WAIT_V(8); PG8_WAIT_L(0); PG8_BAR; PG8_MMA(0, 0, At, B0); PG8_MMA(0, 1, At, B1); PG8_BAR; PG8_SCHED;
;             PG8_LDA(At, 0, 1); PG8_STAGE(PG8_SB(0, 0), b2, voffB); PG8_STAGE(PG8_SB(0, 1), b2 + hstep, voffB); PG8_STAGE(PG8_SA(0, 0), a2, voffA);
;             PG8_WAIT_V(8); PG8_WAIT_L(0); PG8_BAR; PG8_MMA(1, 0, At, B0); PG8_MMA(1, 1, At, B1); PG8_BAR; PG8_SCHED;
;             PG8_LDB(B0, 1, 0); PG8_LDB(B1, 1, 1); PG8_SCHED; PG8_LDA(At, 1, 0); PG8_STAGE(PG8_SA(0, 1), a2 + hstep, voffA);
;             PG8_WAIT_V(8); PG8_WAIT_L(0); PG8_BAR; PG8_MMA(0, 0, At, B0); PG8_MMA(0, 1, At, B1); PG8_BAR; PG8_SCHED;
;             PG8_LDA(At, 1, 1); PG8_STAGE(PG8_SB(1, 0), b3, voffB); PG8_STAGE(PG8_SB(1, 1), b3 + hstep, voffB); PG8_STAGE(PG8_SA(1, 0), a3, voffA);
;             PG8_WAIT_V(8); PG8_WAIT_L(0); PG8_BAR; PG8_MMA(1, 0, At, B0); PG8_MMA(1, 1, At, B1); PG8_BAR; PG8_SCHED;
	s_add_i32 s77, 0, 0x18000
	v_add_u32_e32 v138, s77, v153
	s_add_i32 s78, 0, 0x1c000
	ds_read_b128 v[148:151], v138
	ds_read_b128 v[158:161], v138 offset:1024
	ds_read_b128 v[162:165], v138 offset:2048
	ds_read_b128 v[166:169], v138 offset:3072
	v_add_u32_e32 v138, s78, v153
	ds_read_b128 v[170:173], v138
	ds_read_b128 v[174:177], v138 offset:1024
	ds_read_b128 v[180:183], v138 offset:2048
	ds_read_b128 v[184:187], v138 offset:3072
	s_mov_b32 m0, s26
	s_nop 0
	global_load_lds_dwordx4 v130, s[50:51]
	s_mov_b32 m0, s27
	s_nop 0
	global_load_lds_dwordx4 v134, s[50:51]
	s_add_u32 s50, s50, 0x4000
	s_addc_u32 s51, s51, 0
	s_mov_b32 m0, s28
	ds_read_b128 v[188:191], v156 offset:32768
	ds_read_b128 v[196:199], v156 offset:33792
	ds_read_b128 v[200:203], v156 offset:34816
	ds_read_b128 v[204:207], v156 offset:35840
	ds_read_b128 v[208:211], v156 offset:36864
	ds_read_b128 v[212:215], v156 offset:37888
	ds_read_b128 v[216:219], v156 offset:38912
	ds_read_b128 v[220:223], v156 offset:39936
	global_load_lds_dwordx4 v130, s[50:51]
	s_mov_b32 m0, s29
	s_nop 0
	global_load_lds_dwordx4 v134, s[50:51]
	s_waitcnt vmcnt(8)
	s_waitcnt lgkmcnt(0)
	s_barrier
	s_waitcnt lgkmcnt(0)
	v_mfma_f32_16x16x32_bf16 v[126:129], v[148:151], v[188:191], v[126:129]
	v_mfma_f32_16x16x32_bf16 v[126:129], v[158:161], v[196:199], v[126:129]
	v_mfma_f32_16x16x32_bf16 v[110:113], v[158:161], v[204:207], v[110:113]
	v_mfma_f32_16x16x32_bf16 v[110:113], v[148:151], v[200:203], v[110:113]
	v_mfma_f32_16x16x32_bf16 v[94:97], v[148:151], v[208:211], v[94:97]
	v_mfma_f32_16x16x32_bf16 v[94:97], v[158:161], v[212:215], v[94:97]
	v_mfma_f32_16x16x32_bf16 v[78:81], v[158:161], v[220:223], v[78:81]
	v_mfma_f32_16x16x32_bf16 v[78:81], v[148:151], v[216:219], v[78:81]
	v_mfma_f32_16x16x32_bf16 v[74:77], v[162:165], v[216:219], v[74:77]
	v_mfma_f32_16x16x32_bf16 v[74:77], v[166:169], v[220:223], v[74:77]
	v_mfma_f32_16x16x32_bf16 v[90:93], v[166:169], v[212:215], v[90:93]
	v_mfma_f32_16x16x32_bf16 v[90:93], v[162:165], v[208:211], v[90:93]
	v_mfma_f32_16x16x32_bf16 v[106:109], v[162:165], v[200:203], v[106:109]
	v_mfma_f32_16x16x32_bf16 v[106:109], v[166:169], v[204:207], v[106:109]
	v_mfma_f32_16x16x32_bf16 v[122:125], v[166:169], v[196:199], v[122:125]
	v_mfma_f32_16x16x32_bf16 v[122:125], v[162:165], v[188:191], v[122:125]
	v_mfma_f32_16x16x32_bf16 v[118:121], v[170:173], v[188:191], v[118:121]
	v_mfma_f32_16x16x32_bf16 v[118:121], v[174:177], v[196:199], v[118:121]
	v_mfma_f32_16x16x32_bf16 v[102:105], v[174:177], v[204:207], v[102:105]
	v_mfma_f32_16x16x32_bf16 v[102:105], v[170:173], v[200:203], v[102:105]
	v_mfma_f32_16x16x32_bf16 v[86:89], v[170:173], v[208:211], v[86:89]
	v_mfma_f32_16x16x32_bf16 v[86:89], v[174:177], v[212:215], v[86:89]
	v_mfma_f32_16x16x32_bf16 v[70:73], v[174:177], v[220:223], v[70:73]
	v_mfma_f32_16x16x32_bf16 v[70:73], v[170:173], v[216:219], v[70:73]
	v_mfma_f32_16x16x32_bf16 v[66:69], v[180:183], v[216:219], v[66:69]
	v_mfma_f32_16x16x32_bf16 v[66:69], v[184:187], v[220:223], v[66:69]
	v_mfma_f32_16x16x32_bf16 v[82:85], v[184:187], v[212:215], v[82:85]
	v_mfma_f32_16x16x32_bf16 v[82:85], v[180:183], v[208:211], v[82:85]
	v_mfma_f32_16x16x32_bf16 v[98:101], v[180:183], v[200:203], v[98:101]
	v_mfma_f32_16x16x32_bf16 v[98:101], v[184:187], v[204:207], v[98:101]
	v_mfma_f32_16x16x32_bf16 v[114:117], v[184:187], v[196:199], v[114:117]
	v_mfma_f32_16x16x32_bf16 v[114:117], v[180:183], v[188:191], v[114:117]
	s_barrier
	s_add_u32 s50, s48, 0x8000
	s_addc_u32 s51, s49, 0
	s_add_i32 s77, s77, s3
	s_mov_b32 m0, s77
	ds_read_b128 v[188:191], v156 offset:49152
	ds_read_b128 v[196:199], v156 offset:50176
	ds_read_b128 v[200:203], v156 offset:51200
	ds_read_b128 v[204:207], v156 offset:52224
	ds_read_b128 v[208:211], v156 offset:53248
	ds_read_b128 v[212:215], v156 offset:54272
	ds_read_b128 v[216:219], v156 offset:55296
	ds_read_b128 v[220:223], v156 offset:56320
	global_load_lds_dwordx4 v132, s[50:51]
	s_add_i32 m0, s77, 0x2000
	s_add_u32 s48, s48, 0xc000
	v_lshl_add_u64 v[224:225], s[50:51], 0, v[136:137]
	s_addc_u32 s49, s49, 0
	s_add_i32 s50, s78, s3
	global_load_lds_dwordx4 v[224:225], off
	s_mov_b32 m0, s50
	s_nop 0
	global_load_lds_dwordx4 v132, s[48:49]
	s_add_i32 m0, s50, 0x2000
	s_nop 0
	global_load_lds_dwordx4 v136, s[48:49]
	s_add_i32 s76, s76, 2
	s_add_u32 s44, s44, 0x10000
	s_addc_u32 s45, s45, 0
	s_add_u32 s74, s74, 0x10000
	s_addc_u32 s75, s75, 0
	s_add_u32 s46, s44, 0x4000
	s_addc_u32 s47, s45, 0
	s_cmpk_eq_i32 s76, 0xa8
	s_cselect_b32 s50, s6, s46
	s_cselect_b32 s51, s7, s47
	s_cselect_b32 s48, s24, s74
	s_cselect_b32 s49, s25, s75
	s_add_u32 s46, s50, 0x8000
	s_addc_u32 s47, s51, 0
	s_sub_u32 s46, s44, 0x4000
	s_subb_u32 s47, s45, 0
	s_cmpk_gt_u32 s76, 0xa9
	s_waitcnt vmcnt(6)
	s_waitcnt lgkmcnt(0)
	s_barrier
	s_waitcnt lgkmcnt(0)
	v_mfma_f32_16x16x32_bf16 v[62:65], v[148:151], v[188:191], v[62:65]
	v_mfma_f32_16x16x32_bf16 v[62:65], v[158:161], v[196:199], v[62:65]
	v_mfma_f32_16x16x32_bf16 v[46:49], v[158:161], v[204:207], v[46:49]
	v_mfma_f32_16x16x32_bf16 v[46:49], v[148:151], v[200:203], v[46:49]
	v_mfma_f32_16x16x32_bf16 v[30:33], v[148:151], v[208:211], v[30:33]
	v_mfma_f32_16x16x32_bf16 v[30:33], v[158:161], v[212:215], v[30:33]
	v_mfma_f32_16x16x32_bf16 v[14:17], v[158:161], v[220:223], v[14:17]
	v_mfma_f32_16x16x32_bf16 v[14:17], v[148:151], v[216:219], v[14:17]
	v_mfma_f32_16x16x32_bf16 v[10:13], v[162:165], v[216:219], v[10:13]
	v_mfma_f32_16x16x32_bf16 v[10:13], v[166:169], v[220:223], v[10:13]
	v_mfma_f32_16x16x32_bf16 v[26:29], v[166:169], v[212:215], v[26:29]
	v_mfma_f32_16x16x32_bf16 v[26:29], v[162:165], v[208:211], v[26:29]
	v_mfma_f32_16x16x32_bf16 v[42:45], v[162:165], v[200:203], v[42:45]
	v_mfma_f32_16x16x32_bf16 v[42:45], v[166:169], v[204:207], v[42:45]
	v_mfma_f32_16x16x32_bf16 v[58:61], v[166:169], v[196:199], v[58:61]
	v_mfma_f32_16x16x32_bf16 v[58:61], v[162:165], v[188:191], v[58:61]
	v_mfma_f32_16x16x32_bf16 v[54:57], v[170:173], v[188:191], v[54:57]
	v_mfma_f32_16x16x32_bf16 v[54:57], v[174:177], v[196:199], v[54:57]
	v_mfma_f32_16x16x32_bf16 v[38:41], v[174:177], v[204:207], v[38:41]
	v_mfma_f32_16x16x32_bf16 v[38:41], v[170:173], v[200:203], v[38:41]
	v_mfma_f32_16x16x32_bf16 v[22:25], v[170:173], v[208:211], v[22:25]
	v_mfma_f32_16x16x32_bf16 v[22:25], v[174:177], v[212:215], v[22:25]
	v_mfma_f32_16x16x32_bf16 v[6:9], v[174:177], v[220:223], v[6:9]
	v_mfma_f32_16x16x32_bf16 v[6:9], v[170:173], v[216:219], v[6:9]
	v_mfma_f32_16x16x32_bf16 v[2:5], v[180:183], v[216:219], v[2:5]
	v_mfma_f32_16x16x32_bf16 v[2:5], v[184:187], v[220:223], v[2:5]
	v_mfma_f32_16x16x32_bf16 v[18:21], v[184:187], v[212:215], v[18:21]
	v_mfma_f32_16x16x32_bf16 v[18:21], v[180:183], v[208:211], v[18:21]
	v_mfma_f32_16x16x32_bf16 v[34:37], v[180:183], v[200:203], v[34:37]
	v_mfma_f32_16x16x32_bf16 v[34:37], v[184:187], v[204:207], v[34:37]
	v_mfma_f32_16x16x32_bf16 v[50:53], v[184:187], v[196:199], v[50:53]
	v_mfma_f32_16x16x32_bf16 v[50:53], v[180:183], v[188:191], v[50:53]
	s_barrier
; #define PG8_STAGE(bufoff, gbase, voff) do { _Pragma("unroll") for (int _i = 0; _i < 2; ++_i) \
;         __builtin_amdgcn_global_load_lds((const unsigned*)((const char*)(gbase) + (voff)[_i]), (PG8_LAS unsigned*)(lds + (bufoff) + ldsw + _i * 8192), 16, 0, 0); } while (0)
; #define PG8_LDA(dst, b, h) do { _Pragma("unroll") for (int m = 0; m < 4; ++m) _Pragma("unroll") for (int k = 0; k < 2; ++k) dst[m][k] = *(const PG8_LAS bf16x8*)(lds + PG8_SA(b, h) + aoff + m * 2048 + k * 1024); } while (0)
; #define PG8_LDB(dst, b, h) do { _Pragma("unroll") for (int n = 0; n < 2; ++n) _Pragma("unroll") for (int k = 0; k < 2; ++k) dst[n][k] = *(const PG8_LAS bf16x8*)(lds + PG8_SB(b, h) + boff + n * 2048 + k * 1024); } while (0)
; #define PG8_MMA(ai, bj, At, Bt) do { __builtin_amdgcn_s_setprio(1); _Pragma("unroll") for (int m = 0; m < 4; ++m) _Pragma("unroll") for (int n = 0; n < 2; ++n) _Pragma("unroll") for (int k = 0; k < 2; ++k) \
;         acc[ai][bj][m][n] = __builtin_amdgcn_mfma_f32_16x16x32_bf16(Bt[n][k], At[m][k], acc[ai][bj][m][n], 0, 0, 0); __builtin_amdgcn_s_setprio(0); } while (0)
; #define PG8_WAIT_V(n) asm volatile("s_waitcnt vmcnt(" #n ")" ::: "memory")
; #define PG8_WAIT_L(n) asm volatile("s_waitcnt lgkmcnt(" #n ")" ::: "memory")
; template <class Epi, class Sched, bool ALIGN_EPI = false, bool SP2 = false>
; __device__ __forceinline__ void gemm_phase(PG8_LAS unsigned char* lds, const Gemm g, const Sched& S, const Epi& E) {
;     ...
;         for (; t < tend; t += 2) {
;             const bool last = (t == nt - 2);
;             const char* a1 = cA + (size_t)(t + 1) * kstep;
;             const char* a2 = last ? nA : cA + (size_t)(t + 2) * kstep; const char* b2 = last ? nB : cB + (size_t)(t + 2) * kstep;
;             const char* a3 = a2 + kstep; const char* b3 = b2 + kstep;
;             if (last && has_next) S.a_ready(nxt);
;             if constexpr (SP2) {
;             PG8_LDB(B0, 0, 0); PG8_LDB(B1, 0, 1); PG8_SCHED; PG8_LDA(At, 0, 0); PG8_STAGE(PG8_SA(1, 1), a1 + hstep, voffA);
;             PG8_WAIT_V(8); PG8_WAIT_L(0); PG8_BAR; PG8_MMA(0, 0, At, B0); PG8_MMA(0, 1, At, B1); PG8_BAR; PG8_SCHED;
;             PG8_LDA(At, 0, 1); PG8_STAGE(PG8_SB(0, 0), b2, voffB); PG8_STAGE(PG8_SB(0, 1), b2 + hstep, voffB); PG8_STAGE(PG8_SA(0, 0), a2, voffA);
;             PG8_WAIT_V(8); PG8_WAIT_L(0); PG8_BAR; PG8_MMA(1, 0, At, B0); PG8_MMA(1, 1, At, B1); PG8_BAR; PG8_SCHED;
.LBB0_200:
	ds_read_b128 v[148:151], v154
	ds_read_b128 v[158:161], v154 offset:1024
	ds_read_b128 v[162:165], v154 offset:2048
	ds_read_b128 v[166:169], v154 offset:3072
	ds_read_b128 v[170:173], v155
	ds_read_b128 v[174:177], v155 offset:1024
	ds_read_b128 v[180:183], v155 offset:2048
	ds_read_b128 v[184:187], v155 offset:3072
	s_mov_b32 m0, s57
	s_nop 0
	global_load_lds_dwordx4 v130, s[46:47]
	s_mov_b32 m0, s58
	s_nop 0
	global_load_lds_dwordx4 v134, s[46:47]
	s_add_i32 m0, s26, 0xc000
	ds_read_b128 v[188:191], v156
	ds_read_b128 v[196:199], v156 offset:1024
	ds_read_b128 v[200:203], v156 offset:2048
	ds_read_b128 v[204:207], v156 offset:3072
	ds_read_b128 v[208:211], v156 offset:4096
	ds_read_b128 v[212:215], v156 offset:5120
	ds_read_b128 v[216:219], v156 offset:6144
	ds_read_b128 v[220:223], v156 offset:7168
	global_load_lds_dwordx4 v140, s[44:45]
	s_add_i32 m0, s26, 0xe000
	s_nop 0
	global_load_lds_dwordx4 v142, s[44:45]
	s_waitcnt vmcnt(8)
	s_waitcnt lgkmcnt(0)
	s_barrier
	s_waitcnt lgkmcnt(0)
	v_mfma_f32_16x16x32_bf16 v[126:129], v[148:151], v[188:191], v[126:129]
	v_mfma_f32_16x16x32_bf16 v[126:129], v[158:161], v[196:199], v[126:129]
	v_mfma_f32_16x16x32_bf16 v[110:113], v[158:161], v[204:207], v[110:113]
	v_mfma_f32_16x16x32_bf16 v[110:113], v[148:151], v[200:203], v[110:113]
	v_mfma_f32_16x16x32_bf16 v[94:97], v[148:151], v[208:211], v[94:97]
	v_mfma_f32_16x16x32_bf16 v[94:97], v[158:161], v[212:215], v[94:97]
	v_mfma_f32_16x16x32_bf16 v[78:81], v[158:161], v[220:223], v[78:81]
	v_mfma_f32_16x16x32_bf16 v[78:81], v[148:151], v[216:219], v[78:81]
	v_mfma_f32_16x16x32_bf16 v[74:77], v[162:165], v[216:219], v[74:77]
	v_mfma_f32_16x16x32_bf16 v[74:77], v[166:169], v[220:223], v[74:77]
	v_mfma_f32_16x16x32_bf16 v[90:93], v[166:169], v[212:215], v[90:93]
	v_mfma_f32_16x16x32_bf16 v[90:93], v[162:165], v[208:211], v[90:93]
	v_mfma_f32_16x16x32_bf16 v[106:109], v[162:165], v[200:203], v[106:109]
	v_mfma_f32_16x16x32_bf16 v[106:109], v[166:169], v[204:207], v[106:109]
	v_mfma_f32_16x16x32_bf16 v[122:125], v[166:169], v[196:199], v[122:125]
	v_mfma_f32_16x16x32_bf16 v[122:125], v[162:165], v[188:191], v[122:125]
	v_mfma_f32_16x16x32_bf16 v[118:121], v[170:173], v[188:191], v[118:121]
	v_mfma_f32_16x16x32_bf16 v[118:121], v[174:177], v[196:199], v[118:121]
	v_mfma_f32_16x16x32_bf16 v[102:105], v[174:177], v[204:207], v[102:105]
	v_mfma_f32_16x16x32_bf16 v[102:105], v[170:173], v[200:203], v[102:105]
	v_mfma_f32_16x16x32_bf16 v[86:89], v[170:173], v[208:211], v[86:89]
	v_mfma_f32_16x16x32_bf16 v[86:89], v[174:177], v[212:215], v[86:89]
	v_mfma_f32_16x16x32_bf16 v[70:73], v[174:177], v[220:223], v[70:73]
	v_mfma_f32_16x16x32_bf16 v[70:73], v[170:173], v[216:219], v[70:73]
	v_mfma_f32_16x16x32_bf16 v[66:69], v[180:183], v[216:219], v[66:69]
	v_mfma_f32_16x16x32_bf16 v[66:69], v[184:187], v[220:223], v[66:69]
	v_mfma_f32_16x16x32_bf16 v[82:85], v[184:187], v[212:215], v[82:85]
	v_mfma_f32_16x16x32_bf16 v[82:85], v[180:183], v[208:211], v[82:85]
	v_mfma_f32_16x16x32_bf16 v[98:101], v[180:183], v[200:203], v[98:101]
	v_mfma_f32_16x16x32_bf16 v[98:101], v[184:187], v[204:207], v[98:101]
	v_mfma_f32_16x16x32_bf16 v[114:117], v[184:187], v[196:199], v[114:117]
	v_mfma_f32_16x16x32_bf16 v[114:117], v[180:183], v[188:191], v[114:117]
	s_barrier
	s_add_i32 s77, s59, s3
	s_mov_b32 m0, s77
	ds_read_b128 v[188:191], v156 offset:16384
	ds_read_b128 v[196:199], v156 offset:17408
	ds_read_b128 v[200:203], v156 offset:18432
	ds_read_b128 v[204:207], v156 offset:19456
	ds_read_b128 v[208:211], v156 offset:20480
	ds_read_b128 v[212:215], v156 offset:21504
	ds_read_b128 v[216:219], v156 offset:22528
	ds_read_b128 v[220:223], v156 offset:23552
	global_load_lds_dwordx4 v132, s[48:49]
	s_add_i32 m0, s77, 0x2000
	s_add_u32 s78, s48, 0x4000
	s_addc_u32 s79, s49, 0
	s_add_i32 s77, s61, s3
	global_load_lds_dwordx4 v136, s[48:49]
	s_mov_b32 m0, s77
	s_nop 0
	global_load_lds_dwordx4 v132, s[78:79]
	s_add_i32 m0, s77, 0x2000
	s_nop 0
	global_load_lds_dwordx4 v136, s[78:79]
	s_waitcnt vmcnt(6)
	s_waitcnt lgkmcnt(0)
	s_barrier
	s_waitcnt lgkmcnt(0)
	v_mfma_f32_16x16x32_bf16 v[62:65], v[148:151], v[188:191], v[62:65]
	v_mfma_f32_16x16x32_bf16 v[62:65], v[158:161], v[196:199], v[62:65]
	v_mfma_f32_16x16x32_bf16 v[46:49], v[158:161], v[204:207], v[46:49]
	v_mfma_f32_16x16x32_bf16 v[46:49], v[148:151], v[200:203], v[46:49]
	v_mfma_f32_16x16x32_bf16 v[30:33], v[148:151], v[208:211], v[30:33]
	v_mfma_f32_16x16x32_bf16 v[30:33], v[158:161], v[212:215], v[30:33]
	v_mfma_f32_16x16x32_bf16 v[14:17], v[158:161], v[220:223], v[14:17]
	v_mfma_f32_16x16x32_bf16 v[14:17], v[148:151], v[216:219], v[14:17]
	v_mfma_f32_16x16x32_bf16 v[10:13], v[162:165], v[216:219], v[10:13]
	v_mfma_f32_16x16x32_bf16 v[10:13], v[166:169], v[220:223], v[10:13]
	v_mfma_f32_16x16x32_bf16 v[26:29], v[166:169], v[212:215], v[26:29]
	v_mfma_f32_16x16x32_bf16 v[26:29], v[162:165], v[208:211], v[26:29]
	v_mfma_f32_16x16x32_bf16 v[42:45], v[162:165], v[200:203], v[42:45]
	v_mfma_f32_16x16x32_bf16 v[42:45], v[166:169], v[204:207], v[42:45]
	v_mfma_f32_16x16x32_bf16 v[58:61], v[166:169], v[196:199], v[58:61]
	v_mfma_f32_16x16x32_bf16 v[58:61], v[162:165], v[188:191], v[58:61]
	v_mfma_f32_16x16x32_bf16 v[54:57], v[170:173], v[188:191], v[54:57]
	v_mfma_f32_16x16x32_bf16 v[54:57], v[174:177], v[196:199], v[54:57]
	v_mfma_f32_16x16x32_bf16 v[38:41], v[174:177], v[204:207], v[38:41]
	v_mfma_f32_16x16x32_bf16 v[38:41], v[170:173], v[200:203], v[38:41]
	v_mfma_f32_16x16x32_bf16 v[22:25], v[170:173], v[208:211], v[22:25]
	v_mfma_f32_16x16x32_bf16 v[22:25], v[174:177], v[212:215], v[22:25]
	v_mfma_f32_16x16x32_bf16 v[6:9], v[174:177], v[220:223], v[6:9]
	v_mfma_f32_16x16x32_bf16 v[6:9], v[170:173], v[216:219], v[6:9]
	v_mfma_f32_16x16x32_bf16 v[2:5], v[180:183], v[216:219], v[2:5]
	v_mfma_f32_16x16x32_bf16 v[2:5], v[184:187], v[220:223], v[2:5]
	v_mfma_f32_16x16x32_bf16 v[18:21], v[184:187], v[212:215], v[18:21]
	v_mfma_f32_16x16x32_bf16 v[18:21], v[180:183], v[208:211], v[18:21]
	v_mfma_f32_16x16x32_bf16 v[34:37], v[180:183], v[200:203], v[34:37]
	v_mfma_f32_16x16x32_bf16 v[34:37], v[184:187], v[204:207], v[34:37]
	v_mfma_f32_16x16x32_bf16 v[50:53], v[184:187], v[196:199], v[50:53]
	v_mfma_f32_16x16x32_bf16 v[50:53], v[180:183], v[188:191], v[50:53]
	s_barrier
; #define PG8_STAGE(bufoff, gbase, voff) do { _Pragma("unroll") for (int _i = 0; _i < 2; ++_i) \
;         __builtin_amdgcn_global_load_lds((const unsigned*)((const char*)(gbase) + (voff)[_i]), (PG8_LAS unsigned*)(lds + (bufoff) + ldsw + _i * 8192), 16, 0, 0); } while (0)
; #define PG8_LDA(dst, b, h) do { _Pragma("unroll") for (int m = 0; m < 4; ++m) _Pragma("unroll") for (int k = 0; k < 2; ++k) dst[m][k] = *(const PG8_LAS bf16x8*)(lds + PG8_SA(b, h) + aoff + m * 2048 + k * 1024); } while (0)
; #define PG8_LDB(dst, b, h) do { _Pragma("unroll") for (int n = 0; n < 2; ++n) _Pragma("unroll") for (int k = 0; k < 2; ++k) dst[n][k] = *(const PG8_LAS bf16x8*)(lds + PG8_SB(b, h) + boff + n * 2048 + k * 1024); } while (0)
; #define PG8_MMA(ai, bj, At, Bt) do { __builtin_amdgcn_s_setprio(1); _Pragma("unroll") for (int m = 0; m < 4; ++m) _Pragma("unroll") for (int n = 0; n < 2; ++n) _Pragma("unroll") for (int k = 0; k < 2; ++k) \
;         acc[ai][bj][m][n] = __builtin_amdgcn_mfma_f32_16x16x32_bf16(Bt[n][k], At[m][k], acc[ai][bj][m][n], 0, 0, 0); __builtin_amdgcn_s_setprio(0); } while (0)
; #define PG8_WAIT_V(n) asm volatile("s_waitcnt vmcnt(" #n ")" ::: "memory")
; #define PG8_WAIT_L(n) asm volatile("s_waitcnt lgkmcnt(" #n ")" ::: "memory")
; #define PG8_BAR __builtin_amdgcn_s_barrier()
; #define PG8_SCHED __builtin_amdgcn_sched_barrier(0)
; template <class Epi, class Sched, bool ALIGN_EPI = false, bool SP2 = false>
; __device__ __forceinline__ void gemm_phase(PG8_LAS unsigned char* lds, const Gemm g, const Sched& S, const Epi& E) {
;     ...
;             PG8_LDB(B0, 1, 0); PG8_LDB(B1, 1, 1); PG8_SCHED; PG8_LDA(At, 1, 0); PG8_STAGE(PG8_SA(0, 1), a2 + hstep, voffA);
;             PG8_WAIT_V(8); PG8_WAIT_L(0); PG8_BAR; PG8_MMA(0, 0, At, B0); PG8_MMA(0, 1, At, B1); PG8_BAR; PG8_SCHED;
	s_add_i32 s77, 0, 0x18000
	v_add_u32_e32 v138, s77, v153
	s_add_i32 s78, 0, 0x1c000
	ds_read_b128 v[148:151], v138
	ds_read_b128 v[158:161], v138 offset:1024
	ds_read_b128 v[162:165], v138 offset:2048
	ds_read_b128 v[166:169], v138 offset:3072
	v_add_u32_e32 v138, s78, v153
	ds_read_b128 v[170:173], v138
	ds_read_b128 v[174:177], v138 offset:1024
	ds_read_b128 v[180:183], v138 offset:2048
	ds_read_b128 v[184:187], v138 offset:3072
	s_mov_b32 m0, s26
	s_nop 0
	global_load_lds_dwordx4 v130, s[50:51]
	s_mov_b32 m0, s27
	s_nop 0
	global_load_lds_dwordx4 v134, s[50:51]
	s_add_u32 s50, s50, 0x4000
	s_addc_u32 s51, s51, 0
	s_mov_b32 m0, s28
	ds_read_b128 v[188:191], v156 offset:32768
	ds_read_b128 v[196:199], v156 offset:33792
	ds_read_b128 v[200:203], v156 offset:34816
	ds_read_b128 v[204:207], v156 offset:35840
	ds_read_b128 v[208:211], v156 offset:36864
	ds_read_b128 v[212:215], v156 offset:37888
	ds_read_b128 v[216:219], v156 offset:38912
	ds_read_b128 v[220:223], v156 offset:39936
	global_load_lds_dwordx4 v130, s[50:51]
	s_mov_b32 m0, s29
	s_nop 0
	global_load_lds_dwordx4 v134, s[50:51]
	s_waitcnt vmcnt(8)
	s_waitcnt lgkmcnt(0)
	s_barrier
	s_waitcnt lgkmcnt(0)
	v_mfma_f32_16x16x32_bf16 v[126:129], v[148:151], v[188:191], v[126:129]
	v_mfma_f32_16x16x32_bf16 v[126:129], v[158:161], v[196:199], v[126:129]
	v_mfma_f32_16x16x32_bf16 v[110:113], v[158:161], v[204:207], v[110:113]
	v_mfma_f32_16x16x32_bf16 v[110:113], v[148:151], v[200:203], v[110:113]
	v_mfma_f32_16x16x32_bf16 v[94:97], v[148:151], v[208:211], v[94:97]
	v_mfma_f32_16x16x32_bf16 v[94:97], v[158:161], v[212:215], v[94:97]
	v_mfma_f32_16x16x32_bf16 v[78:81], v[158:161], v[220:223], v[78:81]
	v_mfma_f32_16x16x32_bf16 v[78:81], v[148:151], v[216:219], v[78:81]
	v_mfma_f32_16x16x32_bf16 v[74:77], v[162:165], v[216:219], v[74:77]
	v_mfma_f32_16x16x32_bf16 v[74:77], v[166:169], v[220:223], v[74:77]
	v_mfma_f32_16x16x32_bf16 v[90:93], v[166:169], v[212:215], v[90:93]
	v_mfma_f32_16x16x32_bf16 v[90:93], v[162:165], v[208:211], v[90:93]
	v_mfma_f32_16x16x32_bf16 v[106:109], v[162:165], v[200:203], v[106:109]
	v_mfma_f32_16x16x32_bf16 v[106:109], v[166:169], v[204:207], v[106:109]
	v_mfma_f32_16x16x32_bf16 v[122:125], v[166:169], v[196:199], v[122:125]
	v_mfma_f32_16x16x32_bf16 v[122:125], v[162:165], v[188:191], v[122:125]
	v_mfma_f32_16x16x32_bf16 v[118:121], v[170:173], v[188:191], v[118:121]
	v_mfma_f32_16x16x32_bf16 v[118:121], v[174:177], v[196:199], v[118:121]
	v_mfma_f32_16x16x32_bf16 v[102:105], v[174:177], v[204:207], v[102:105]
	v_mfma_f32_16x16x32_bf16 v[102:105], v[170:173], v[200:203], v[102:105]
	v_mfma_f32_16x16x32_bf16 v[86:89], v[170:173], v[208:211], v[86:89]
	v_mfma_f32_16x16x32_bf16 v[86:89], v[174:177], v[212:215], v[86:89]
	v_mfma_f32_16x16x32_bf16 v[70:73], v[174:177], v[220:223], v[70:73]
	v_mfma_f32_16x16x32_bf16 v[70:73], v[170:173], v[216:219], v[70:73]
	v_mfma_f32_16x16x32_bf16 v[66:69], v[180:183], v[216:219], v[66:69]
	v_mfma_f32_16x16x32_bf16 v[66:69], v[184:187], v[220:223], v[66:69]
	v_mfma_f32_16x16x32_bf16 v[82:85], v[184:187], v[212:215], v[82:85]
	v_mfma_f32_16x16x32_bf16 v[82:85], v[180:183], v[208:211], v[82:85]
	v_mfma_f32_16x16x32_bf16 v[98:101], v[180:183], v[200:203], v[98:101]
	v_mfma_f32_16x16x32_bf16 v[98:101], v[184:187], v[204:207], v[98:101]
	v_mfma_f32_16x16x32_bf16 v[114:117], v[184:187], v[196:199], v[114:117]
	v_mfma_f32_16x16x32_bf16 v[114:117], v[180:183], v[188:191], v[114:117]
	s_barrier
; #define PG8_STAGE(bufoff, gbase, voff) do { _Pragma("unroll") for (int _i = 0; _i < 2; ++_i) \
;         __builtin_amdgcn_global_load_lds((const unsigned*)((const char*)(gbase) + (voff)[_i]), (PG8_LAS unsigned*)(lds + (bufoff) + ldsw + _i * 8192), 16, 0, 0); } while (0)
; #define PG8_LDA(dst, b, h) do { _Pragma("unroll") for (int m = 0; m < 4; ++m) _Pragma("unroll") for (int k = 0; k < 2; ++k) dst[m][k] = *(const PG8_LAS bf16x8*)(lds + PG8_SA(b, h) + aoff + m * 2048 + k * 1024); } while (0)
; #define PG8_LDB(dst, b, h) do { _Pragma("unroll") for (int n = 0; n < 2; ++n) _Pragma("unroll") for (int k = 0; k < 2; ++k) dst[n][k] = *(const PG8_LAS bf16x8*)(lds + PG8_SB(b, h) + boff + n * 2048 + k * 1024); } while (0)
; template <class Epi, class Sched, bool ALIGN_EPI = false, bool SP2 = false>
; __device__ __forceinline__ void gemm_phase(PG8_LAS unsigned char* lds, const Gemm g, const Sched& S, const Epi& E) {
;     ...
;         for (; t < tend; t += 2) {
;             const bool last = (t == nt - 2);
;             const char* a1 = cA + (size_t)(t + 1) * kstep;
;             const char* a2 = last ? nA : cA + (size_t)(t + 2) * kstep; const char* b2 = last ? nB : cB + (size_t)(t + 2) * kstep;
;             const char* a3 = a2 + kstep; const char* b3 = b2 + kstep;
;             if (last && has_next) S.a_ready(nxt);
;             if constexpr (SP2) {
;             PG8_LDB(B0, 0, 0); PG8_LDB(B1, 0, 1); PG8_SCHED; PG8_LDA(At, 0, 0); PG8_STAGE(PG8_SA(1, 1), a1 + hstep, voffA);
;             PG8_WAIT_V(8); PG8_WAIT_L(0); PG8_BAR; PG8_MMA(0, 0, At, B0); PG8_MMA(0, 1, At, B1); PG8_BAR; PG8_SCHED;
;             PG8_LDA(At, 0, 1); PG8_STAGE(PG8_SB(0, 0), b2, voffB); PG8_STAGE(PG8_SB(0, 1), b2 + hstep, voffB); PG8_STAGE(PG8_SA(0, 0), a2, voffA);
;             PG8_WAIT_V(8); PG8_WAIT_L(0); PG8_BAR; PG8_MMA(1, 0, At, B0); PG8_MMA(1, 1, At, B1); PG8_BAR; PG8_SCHED;
;             PG8_LDB(B0, 1, 0); PG8_LDB(B1, 1, 1); PG8_SCHED; PG8_LDA(At, 1, 0); PG8_STAGE(PG8_SA(0, 1), a2 + hstep, voffA);
;             PG8_WAIT_V(8); PG8_WAIT_L(0); PG8_BAR; PG8_MMA(0, 0, At, B0); PG8_MMA(0, 1, At, B1); PG8_BAR; PG8_SCHED;
;             PG8_LDA(At, 1, 1); PG8_STAGE(PG8_SB(1, 0), b3, voffB); PG8_STAGE(PG8_SB(1, 1), b3 + hstep, voffB); PG8_STAGE(PG8_SA(1, 0), a3, voffA);
;             PG8_WAIT_V(8); PG8_WAIT_L(0); PG8_BAR; PG8_MMA(1, 0, At, B0); PG8_MMA(1, 1, At, B1); PG8_BAR; PG8_SCHED;
	s_add_u32 s50, s48, 0x8000
	s_addc_u32 s51, s49, 0
	s_add_i32 s77, s77, s3
	s_mov_b32 m0, s77
	ds_read_b128 v[188:191], v156 offset:49152
	ds_read_b128 v[196:199], v156 offset:50176
	ds_read_b128 v[200:203], v156 offset:51200
	ds_read_b128 v[204:207], v156 offset:52224
	ds_read_b128 v[208:211], v156 offset:53248
	ds_read_b128 v[212:215], v156 offset:54272
	ds_read_b128 v[216:219], v156 offset:55296
	ds_read_b128 v[220:223], v156 offset:56320
	global_load_lds_dwordx4 v132, s[50:51]
	s_add_i32 m0, s77, 0x2000
	s_add_u32 s48, s48, 0xc000
	v_lshl_add_u64 v[224:225], s[50:51], 0, v[136:137]
	s_addc_u32 s49, s49, 0
	s_add_i32 s50, s78, s3
	global_load_lds_dwordx4 v[224:225], off
	s_mov_b32 m0, s50
	s_nop 0
	global_load_lds_dwordx4 v132, s[48:49]
	s_add_i32 m0, s50, 0x2000
	s_nop 0
	global_load_lds_dwordx4 v136, s[48:49]
	s_add_i32 s76, s76, 2
	s_add_u32 s44, s44, 0x10000
	s_addc_u32 s45, s45, 0
	s_add_u32 s74, s74, 0x10000
	s_addc_u32 s75, s75, 0
	s_add_u32 s46, s44, 0x4000
	s_addc_u32 s47, s45, 0
	s_cmpk_eq_i32 s76, 0xa8
	s_cselect_b32 s50, s6, s46
	s_cselect_b32 s51, s7, s47
	s_cselect_b32 s48, s24, s74
	s_cselect_b32 s49, s25, s75
	s_add_u32 s46, s50, 0x8000
	s_addc_u32 s47, s51, 0
	s_sub_u32 s46, s44, 0x4000
	s_subb_u32 s47, s45, 0
	s_cmpk_gt_u32 s76, 0xa9
	s_waitcnt vmcnt(6)
	s_waitcnt lgkmcnt(0)
	s_barrier
	s_waitcnt lgkmcnt(0)
	v_mfma_f32_16x16x32_bf16 v[62:65], v[148:151], v[188:191], v[62:65]
	v_mfma_f32_16x16x32_bf16 v[62:65], v[158:161], v[196:199], v[62:65]
	v_mfma_f32_16x16x32_bf16 v[46:49], v[158:161], v[204:207], v[46:49]
	v_mfma_f32_16x16x32_bf16 v[46:49], v[148:151], v[200:203], v[46:49]
	v_mfma_f32_16x16x32_bf16 v[30:33], v[148:151], v[208:211], v[30:33]
	v_mfma_f32_16x16x32_bf16 v[30:33], v[158:161], v[212:215], v[30:33]
	v_mfma_f32_16x16x32_bf16 v[14:17], v[158:161], v[220:223], v[14:17]
	v_mfma_f32_16x16x32_bf16 v[14:17], v[148:151], v[216:219], v[14:17]
	v_mfma_f32_16x16x32_bf16 v[10:13], v[162:165], v[216:219], v[10:13]
	v_mfma_f32_16x16x32_bf16 v[10:13], v[166:169], v[220:223], v[10:13]
	v_mfma_f32_16x16x32_bf16 v[26:29], v[166:169], v[212:215], v[26:29]
	v_mfma_f32_16x16x32_bf16 v[26:29], v[162:165], v[208:211], v[26:29]
	v_mfma_f32_16x16x32_bf16 v[42:45], v[162:165], v[200:203], v[42:45]
	v_mfma_f32_16x16x32_bf16 v[42:45], v[166:169], v[204:207], v[42:45]
	v_mfma_f32_16x16x32_bf16 v[58:61], v[166:169], v[196:199], v[58:61]
	v_mfma_f32_16x16x32_bf16 v[58:61], v[162:165], v[188:191], v[58:61]
	v_mfma_f32_16x16x32_bf16 v[54:57], v[170:173], v[188:191], v[54:57]
	v_mfma_f32_16x16x32_bf16 v[54:57], v[174:177], v[196:199], v[54:57]
	v_mfma_f32_16x16x32_bf16 v[38:41], v[174:177], v[204:207], v[38:41]
	v_mfma_f32_16x16x32_bf16 v[38:41], v[170:173], v[200:203], v[38:41]
	v_mfma_f32_16x16x32_bf16 v[22:25], v[170:173], v[208:211], v[22:25]
	v_mfma_f32_16x16x32_bf16 v[22:25], v[174:177], v[212:215], v[22:25]
	v_mfma_f32_16x16x32_bf16 v[6:9], v[174:177], v[220:223], v[6:9]
	v_mfma_f32_16x16x32_bf16 v[6:9], v[170:173], v[216:219], v[6:9]
	v_mfma_f32_16x16x32_bf16 v[2:5], v[180:183], v[216:219], v[2:5]
	v_mfma_f32_16x16x32_bf16 v[2:5], v[184:187], v[220:223], v[2:5]
	v_mfma_f32_16x16x32_bf16 v[18:21], v[184:187], v[212:215], v[18:21]
	v_mfma_f32_16x16x32_bf16 v[18:21], v[180:183], v[208:211], v[18:21]
	v_mfma_f32_16x16x32_bf16 v[34:37], v[180:183], v[200:203], v[34:37]
	v_mfma_f32_16x16x32_bf16 v[34:37], v[184:187], v[204:207], v[34:37]
	v_mfma_f32_16x16x32_bf16 v[50:53], v[184:187], v[196:199], v[50:53]
	v_mfma_f32_16x16x32_bf16 v[50:53], v[180:183], v[188:191], v[50:53]
	s_barrier
	s_cbranch_scc0 .LBB0_200
	s_and_b64 vcc, exec, s[18:19]
	s_cbranch_vccz .LBB0_203
	s_barrier

;     __device__ __forceinline__ bool next(int i, Unit& u) const { if (i >= 2) return false; const int xcd = c & 7, off = c >> 3; u.pm = 16 * i + 4 * (xcd >> 1) + (off & 3); u.pn = 8 * (xcd & 1) + (off >> 2); return true; }
; #define PG8_STAGE(bufoff, gbase, voff) do { _Pragma("unroll") for (int _i = 0; _i < 2; ++_i) \
;         __builtin_amdgcn_global_load_lds((const unsigned*)((const char*)(gbase) + (voff)[_i]), (PG8_LAS unsigned*)(lds + (bufoff) + ldsw + _i * 8192), 16, 0, 0); } while (0)
; #define PG8_LDA(dst, b, h) do { _Pragma("unroll") for (int m = 0; m < 4; ++m) _Pragma("unroll") for (int k = 0; k < 2; ++k) dst[m][k] = *(const PG8_LAS bf16x8*)(lds + PG8_SA(b, h) + aoff + m * 2048 + k * 1024); } while (0)
; #define PG8_LDB(dst, b, h) do { _Pragma("unroll") for (int n = 0; n < 2; ++n) _Pragma("unroll") for (int k = 0; k < 2; ++k) dst[n][k] = *(const PG8_LAS bf16x8*)(lds + PG8_SB(b, h) + boff + n * 2048 + k * 1024); } while (0)
; #define PG8_WAIT_V(n) asm volatile("s_waitcnt vmcnt(" #n ")" ::: "memory")
; #define PG8_WAIT_L(n) asm volatile("s_waitcnt lgkmcnt(" #n ")" ::: "memory")
; template <class Epi, class Sched, bool ALIGN_EPI = false, bool SP2 = false>
; __device__ __forceinline__ void gemm_phase(PG8_LAS unsigned char* lds, const Gemm g, const Sched& S, const Epi& E) {
;     ...
;         const bool has_next = S.next(ui + 1, nxt);
;         const char* nA = has_next ? (const char*)g.A + (size_t)nxt.pm * tstep : cA; const char* nB = has_next ? (const char*)g.Bt + (size_t)nxt.pn * tstep : cB;
;         constexpr int NSEG = Epi::HAS_MID ? 2 : 1; int t = 0;
; #pragma unroll
;         for (int seg = 0; seg < NSEG; ++seg) { const int tend = (seg + 1 < NSEG) ? (nt >> 1) : nt;
;         for (; t < tend; t += 2) {
;             const bool last = (t == nt - 2);
;             const char* a1 = cA + (size_t)(t + 1) * kstep;
;             const char* a2 = last ? nA : cA + (size_t)(t + 2) * kstep; const char* b2 = last ? nB : cB + (size_t)(t + 2) * kstep;
;             const char* a3 = a2 + kstep; const char* b3 = b2 + kstep;
;             if (last && has_next) S.a_ready(nxt);
;             if constexpr (SP2) {
;             PG8_LDB(B0, 0, 0); PG8_LDB(B1, 0, 1); PG8_SCHED; PG8_LDA(At, 0, 0); PG8_STAGE(PG8_SA(1, 1), a1 + hstep, voffA);
;             PG8_WAIT_V(8); PG8_WAIT_L(0); PG8_BAR; PG8_MMA(0, 0, At, B0); PG8_MMA(0, 1, At, B1); PG8_BAR; PG8_SCHED;
.LBB0_289:
	s_ashr_i32 s19, s18, 31
	s_lshl_b64 s[46:47], s[18:19], 21
	s_add_u32 s46, s42, s46
	s_addc_u32 s47, s43, s47
	s_and_b64 s[48:49], s[0:1], exec
	s_cselect_b32 s5, s47, s73
	s_cselect_b32 s19, s46, s72
	s_ashr_i32 s17, s16, 31
	s_lshl_b64 s[48:49], s[16:17], 21
	s_add_u32 s48, s70, s48
	s_addc_u32 s49, s71, s49
	s_and_b64 s[58:59], s[0:1], exec
	s_cselect_b32 s17, s49, s75
	s_cselect_b32 s26, s48, s74
	s_add_u32 s72, s72, 0xc000
	s_addc_u32 s73, s73, 0
	s_add_u32 s33, s74, 0x10000
	s_addc_u32 s56, s75, 0
	s_mov_b32 s58, -2
	s_nop 3
	s_add_u32 s59, s72, 0x4000
	s_addc_u32 s62, s73, 0
	s_cmp_eq_u32 s58, 60
	s_cselect_b32 s78, s19, s59
	s_cselect_b32 s79, s5, s62
	s_cselect_b32 s76, s26, s33
	s_cselect_b32 s77, s17, s56
	s_add_u32 s74, s78, 0x8000
	s_addc_u32 s75, s79, 0
	s_sub_u32 s74, s72, 0x4000
	s_subb_u32 s75, s73, 0
	ds_read_b128 v[146:149], v162
	ds_read_b128 v[150:153], v162 offset:1024
	ds_read_b128 v[154:157], v162 offset:2048
	ds_read_b128 v[168:171], v162 offset:3072
	ds_read_b128 v[172:175], v163
	ds_read_b128 v[180:183], v163 offset:1024
	ds_read_b128 v[184:187], v163 offset:2048
	ds_read_b128 v[188:191], v163 offset:3072
	s_mov_b32 m0, s51
	s_nop 0
	global_load_lds_dwordx4 v130, s[74:75]
	s_mov_b32 m0, s57
	s_nop 0
	global_load_lds_dwordx4 v134, s[74:75]
	s_add_i32 m0, s15, 0xc000
	ds_read_b128 v[198:201], v164
	ds_read_b128 v[202:205], v164 offset:1024
	ds_read_b128 v[206:209], v164 offset:2048
	ds_read_b128 v[210:213], v164 offset:3072
	ds_read_b128 v[214:217], v164 offset:4096
	ds_read_b128 v[218:221], v164 offset:5120
	ds_read_b128 v[222:225], v164 offset:6144
	ds_read_b128 v[226:229], v164 offset:7168
	global_load_lds_dwordx4 v138, s[72:73]
	s_add_i32 m0, s15, 0xe000
	s_nop 0
	global_load_lds_dwordx4 v140, s[72:73]
	s_waitcnt vmcnt(8)
	s_waitcnt lgkmcnt(0)
	s_barrier
	s_waitcnt lgkmcnt(0)
	v_mfma_f32_16x16x32_bf16 v[126:129], v[146:149], v[198:201], 0
	v_mfma_f32_16x16x32_bf16 v[126:129], v[150:153], v[202:205], v[126:129]
	v_mfma_f32_16x16x32_bf16 v[110:113], v[150:153], v[210:213], 0
	v_mfma_f32_16x16x32_bf16 v[110:113], v[146:149], v[206:209], v[110:113]
	v_mfma_f32_16x16x32_bf16 v[94:97], v[146:149], v[214:217], 0
	v_mfma_f32_16x16x32_bf16 v[94:97], v[150:153], v[218:221], v[94:97]
	v_mfma_f32_16x16x32_bf16 v[78:81], v[150:153], v[226:229], 0
	v_mfma_f32_16x16x32_bf16 v[78:81], v[146:149], v[222:225], v[78:81]
	v_mfma_f32_16x16x32_bf16 v[74:77], v[154:157], v[222:225], 0
	v_mfma_f32_16x16x32_bf16 v[74:77], v[168:171], v[226:229], v[74:77]
	v_mfma_f32_16x16x32_bf16 v[90:93], v[168:171], v[218:221], 0
	v_mfma_f32_16x16x32_bf16 v[90:93], v[154:157], v[214:217], v[90:93]
	v_mfma_f32_16x16x32_bf16 v[106:109], v[154:157], v[206:209], 0
	v_mfma_f32_16x16x32_bf16 v[106:109], v[168:171], v[210:213], v[106:109]
	v_mfma_f32_16x16x32_bf16 v[122:125], v[168:171], v[202:205], 0
	v_mfma_f32_16x16x32_bf16 v[122:125], v[154:157], v[198:201], v[122:125]
	v_mfma_f32_16x16x32_bf16 v[118:121], v[172:175], v[198:201], 0
	v_mfma_f32_16x16x32_bf16 v[118:121], v[180:183], v[202:205], v[118:121]
	v_mfma_f32_16x16x32_bf16 v[102:105], v[180:183], v[210:213], 0
	v_mfma_f32_16x16x32_bf16 v[102:105], v[172:175], v[206:209], v[102:105]
	v_mfma_f32_16x16x32_bf16 v[86:89], v[172:175], v[214:217], 0
	v_mfma_f32_16x16x32_bf16 v[86:89], v[180:183], v[218:221], v[86:89]
	v_mfma_f32_16x16x32_bf16 v[70:73], v[180:183], v[226:229], 0
	v_mfma_f32_16x16x32_bf16 v[70:73], v[172:175], v[222:225], v[70:73]
	v_mfma_f32_16x16x32_bf16 v[66:69], v[184:187], v[222:225], 0
	v_mfma_f32_16x16x32_bf16 v[66:69], v[188:191], v[226:229], v[66:69]
	v_mfma_f32_16x16x32_bf16 v[82:85], v[188:191], v[218:221], 0
	v_mfma_f32_16x16x32_bf16 v[82:85], v[184:187], v[214:217], v[82:85]
	v_mfma_f32_16x16x32_bf16 v[98:101], v[184:187], v[206:209], 0
	v_mfma_f32_16x16x32_bf16 v[98:101], v[188:191], v[210:213], v[98:101]
	v_mfma_f32_16x16x32_bf16 v[114:117], v[188:191], v[202:205], 0
	v_mfma_f32_16x16x32_bf16 v[114:117], v[184:187], v[198:201], v[114:117]
	s_barrier
	s_add_i32 s59, s81, s3
	s_mov_b32 m0, s59
	ds_read_b128 v[198:201], v164 offset:16384
	ds_read_b128 v[202:205], v164 offset:17408
	ds_read_b128 v[206:209], v164 offset:18432
	ds_read_b128 v[210:213], v164 offset:19456
	ds_read_b128 v[214:217], v164 offset:20480
	ds_read_b128 v[218:221], v164 offset:21504
	ds_read_b128 v[222:225], v164 offset:22528
	ds_read_b128 v[226:229], v164 offset:23552
	global_load_lds_dwordx4 v132, s[76:77]
	s_add_i32 m0, s59, 0x2000
	s_add_u32 s62, s76, 0x4000
	s_addc_u32 s63, s77, 0
	s_add_i32 s59, s82, s3
	global_load_lds_dwordx4 v136, s[76:77]
	s_mov_b32 m0, s59
	s_nop 0
	global_load_lds_dwordx4 v132, s[62:63]
	s_add_i32 m0, s59, 0x2000
	s_nop 0
	global_load_lds_dwordx4 v136, s[62:63]
	s_waitcnt vmcnt(6)
	s_waitcnt lgkmcnt(0)
	s_barrier
; #define PG8_STAGE(bufoff, gbase, voff) do { _Pragma("unroll") for (int _i = 0; _i < 2; ++_i) \
;         __builtin_amdgcn_global_load_lds((const unsigned*)((const char*)(gbase) + (voff)[_i]), (PG8_LAS unsigned*)(lds + (bufoff) + ldsw + _i * 8192), 16, 0, 0); } while (0)
; #define PG8_LDA(dst, b, h) do { _Pragma("unroll") for (int m = 0; m < 4; ++m) _Pragma("unroll") for (int k = 0; k < 2; ++k) dst[m][k] = *(const PG8_LAS bf16x8*)(lds + PG8_SA(b, h) + aoff + m * 2048 + k * 1024); } while (0)
; #define PG8_LDB(dst, b, h) do { _Pragma("unroll") for (int n = 0; n < 2; ++n) _Pragma("unroll") for (int k = 0; k < 2; ++k) dst[n][k] = *(const PG8_LAS bf16x8*)(lds + PG8_SB(b, h) + boff + n * 2048 + k * 1024); } while (0)
; #define PG8_MMA(ai, bj, At, Bt) do { __builtin_amdgcn_s_setprio(1); _Pragma("unroll") for (int m = 0; m < 4; ++m) _Pragma("unroll") for (int n = 0; n < 2; ++n) _Pragma("unroll") for (int k = 0; k < 2; ++k) \
;         acc[ai][bj][m][n] = __builtin_amdgcn_mfma_f32_16x16x32_bf16(Bt[n][k], At[m][k], acc[ai][bj][m][n], 0, 0, 0); __builtin_amdgcn_s_setprio(0); } while (0)
; #define PG8_WAIT_V(n) asm volatile("s_waitcnt vmcnt(" #n ")" ::: "memory")
; #define PG8_WAIT_L(n) asm volatile("s_waitcnt lgkmcnt(" #n ")" ::: "memory")
; #define PG8_BAR __builtin_amdgcn_s_barrier()
; #define PG8_SCHED __builtin_amdgcn_sched_barrier(0)
; template <class Epi, class Sched, bool ALIGN_EPI = false, bool SP2 = false>
; __device__ __forceinline__ void gemm_phase(PG8_LAS unsigned char* lds, const Gemm g, const Sched& S, const Epi& E) {
;     ...
;             PG8_WAIT_V(8); PG8_WAIT_L(0); PG8_BAR; PG8_MMA(0, 0, At, B0); PG8_MMA(0, 1, At, B1); PG8_BAR; PG8_SCHED;
;             PG8_LDA(At, 0, 1); PG8_STAGE(PG8_SB(0, 0), b2, voffB); PG8_STAGE(PG8_SB(0, 1), b2 + hstep, voffB); PG8_STAGE(PG8_SA(0, 0), a2, voffA);
;             PG8_WAIT_V(8); PG8_WAIT_L(0); PG8_BAR; PG8_MMA(1, 0, At, B0); PG8_MMA(1, 1, At, B1); PG8_BAR; PG8_SCHED;
;             PG8_LDB(B0, 1, 0); PG8_LDB(B1, 1, 1); PG8_SCHED; PG8_LDA(At, 1, 0); PG8_STAGE(PG8_SA(0, 1), a2 + hstep, voffA);
;             PG8_WAIT_V(8); PG8_WAIT_L(0); PG8_BAR; PG8_MMA(0, 0, At, B0); PG8_MMA(0, 1, At, B1); PG8_BAR; PG8_SCHED;
	s_waitcnt lgkmcnt(0)
	v_mfma_f32_16x16x32_bf16 v[62:65], v[146:149], v[198:201], 0
	v_mfma_f32_16x16x32_bf16 v[62:65], v[150:153], v[202:205], v[62:65]
	v_mfma_f32_16x16x32_bf16 v[46:49], v[150:153], v[210:213], 0
	v_mfma_f32_16x16x32_bf16 v[46:49], v[146:149], v[206:209], v[46:49]
	v_mfma_f32_16x16x32_bf16 v[30:33], v[146:149], v[214:217], 0
	v_mfma_f32_16x16x32_bf16 v[30:33], v[150:153], v[218:221], v[30:33]
	v_mfma_f32_16x16x32_bf16 v[14:17], v[150:153], v[226:229], 0
	v_mfma_f32_16x16x32_bf16 v[14:17], v[146:149], v[222:225], v[14:17]
	v_mfma_f32_16x16x32_bf16 v[10:13], v[154:157], v[222:225], 0
	v_mfma_f32_16x16x32_bf16 v[10:13], v[168:171], v[226:229], v[10:13]
	v_mfma_f32_16x16x32_bf16 v[26:29], v[168:171], v[218:221], 0
	v_mfma_f32_16x16x32_bf16 v[26:29], v[154:157], v[214:217], v[26:29]
	v_mfma_f32_16x16x32_bf16 v[42:45], v[154:157], v[206:209], 0
	v_mfma_f32_16x16x32_bf16 v[42:45], v[168:171], v[210:213], v[42:45]
	v_mfma_f32_16x16x32_bf16 v[58:61], v[168:171], v[202:205], 0
	v_mfma_f32_16x16x32_bf16 v[58:61], v[154:157], v[198:201], v[58:61]
	v_mfma_f32_16x16x32_bf16 v[54:57], v[172:175], v[198:201], 0
	v_mfma_f32_16x16x32_bf16 v[54:57], v[180:183], v[202:205], v[54:57]
	v_mfma_f32_16x16x32_bf16 v[38:41], v[180:183], v[210:213], 0
	v_mfma_f32_16x16x32_bf16 v[38:41], v[172:175], v[206:209], v[38:41]
	v_mfma_f32_16x16x32_bf16 v[22:25], v[172:175], v[214:217], 0
	v_mfma_f32_16x16x32_bf16 v[22:25], v[180:183], v[218:221], v[22:25]
	v_mfma_f32_16x16x32_bf16 v[6:9], v[180:183], v[226:229], 0
	v_mfma_f32_16x16x32_bf16 v[6:9], v[172:175], v[222:225], v[6:9]
	v_mfma_f32_16x16x32_bf16 v[2:5], v[184:187], v[222:225], 0
	v_mfma_f32_16x16x32_bf16 v[2:5], v[188:191], v[226:229], v[2:5]
	v_mfma_f32_16x16x32_bf16 v[18:21], v[188:191], v[218:221], 0
	v_mfma_f32_16x16x32_bf16 v[18:21], v[184:187], v[214:217], v[18:21]
	v_mfma_f32_16x16x32_bf16 v[34:37], v[184:187], v[206:209], 0
	v_mfma_f32_16x16x32_bf16 v[34:37], v[188:191], v[210:213], v[34:37]
	v_mfma_f32_16x16x32_bf16 v[50:53], v[188:191], v[202:205], 0
	v_mfma_f32_16x16x32_bf16 v[50:53], v[184:187], v[198:201], v[50:53]
	s_barrier
	s_add_i32 s59, 0, 0x18000
	v_add_u32_e32 v158, s59, v160
	s_add_i32 s64, 0, 0x1c000
	ds_read_b128 v[146:149], v158
	ds_read_b128 v[150:153], v158 offset:1024
	ds_read_b128 v[154:157], v158 offset:2048
	ds_read_b128 v[168:171], v158 offset:3072
	v_add_u32_e32 v158, s64, v160
	ds_read_b128 v[172:175], v158
	ds_read_b128 v[180:183], v158 offset:1024
	ds_read_b128 v[184:187], v158 offset:2048
	ds_read_b128 v[188:191], v158 offset:3072
	s_mov_b32 m0, s15
	s_nop 0
	global_load_lds_dwordx4 v130, s[78:79]
	s_mov_b32 m0, s27
	s_nop 0
	global_load_lds_dwordx4 v134, s[78:79]
	s_add_u32 s62, s78, 0x4000
	s_addc_u32 s63, s79, 0
	s_mov_b32 m0, s28
	ds_read_b128 v[198:201], v164 offset:32768
	ds_read_b128 v[202:205], v164 offset:33792
	ds_read_b128 v[206:209], v164 offset:34816
	ds_read_b128 v[210:213], v164 offset:35840
	ds_read_b128 v[214:217], v164 offset:36864
	ds_read_b128 v[218:221], v164 offset:37888
	ds_read_b128 v[222:225], v164 offset:38912
	ds_read_b128 v[226:229], v164 offset:39936
	global_load_lds_dwordx4 v130, s[62:63]
	s_mov_b32 m0, s29
	s_nop 0
	global_load_lds_dwordx4 v134, s[62:63]
	s_waitcnt vmcnt(8)
	s_waitcnt lgkmcnt(0)
	s_barrier
	s_waitcnt lgkmcnt(0)
	v_mfma_f32_16x16x32_bf16 v[126:129], v[146:149], v[198:201], v[126:129]
	v_mfma_f32_16x16x32_bf16 v[126:129], v[150:153], v[202:205], v[126:129]
	v_mfma_f32_16x16x32_bf16 v[110:113], v[150:153], v[210:213], v[110:113]
	v_mfma_f32_16x16x32_bf16 v[110:113], v[146:149], v[206:209], v[110:113]
	v_mfma_f32_16x16x32_bf16 v[94:97], v[146:149], v[214:217], v[94:97]
	v_mfma_f32_16x16x32_bf16 v[94:97], v[150:153], v[218:221], v[94:97]
	v_mfma_f32_16x16x32_bf16 v[78:81], v[150:153], v[226:229], v[78:81]
	v_mfma_f32_16x16x32_bf16 v[78:81], v[146:149], v[222:225], v[78:81]
	v_mfma_f32_16x16x32_bf16 v[74:77], v[154:157], v[222:225], v[74:77]
	v_mfma_f32_16x16x32_bf16 v[74:77], v[168:171], v[226:229], v[74:77]
	v_mfma_f32_16x16x32_bf16 v[90:93], v[168:171], v[218:221], v[90:93]
	v_mfma_f32_16x16x32_bf16 v[90:93], v[154:157], v[214:217], v[90:93]
	v_mfma_f32_16x16x32_bf16 v[106:109], v[154:157], v[206:209], v[106:109]
	v_mfma_f32_16x16x32_bf16 v[106:109], v[168:171], v[210:213], v[106:109]
	v_mfma_f32_16x16x32_bf16 v[122:125], v[168:171], v[202:205], v[122:125]
	v_mfma_f32_16x16x32_bf16 v[122:125], v[154:157], v[198:201], v[122:125]
	v_mfma_f32_16x16x32_bf16 v[118:121], v[172:175], v[198:201], v[118:121]
	v_mfma_f32_16x16x32_bf16 v[118:121], v[180:183], v[202:205], v[118:121]
	v_mfma_f32_16x16x32_bf16 v[102:105], v[180:183], v[210:213], v[102:105]
	v_mfma_f32_16x16x32_bf16 v[102:105], v[172:175], v[206:209], v[102:105]
	v_mfma_f32_16x16x32_bf16 v[86:89], v[172:175], v[214:217], v[86:89]
	v_mfma_f32_16x16x32_bf16 v[86:89], v[180:183], v[218:221], v[86:89]
	v_mfma_f32_16x16x32_bf16 v[70:73], v[180:183], v[226:229], v[70:73]
	v_mfma_f32_16x16x32_bf16 v[70:73], v[172:175], v[222:225], v[70:73]
	v_mfma_f32_16x16x32_bf16 v[66:69], v[184:187], v[222:225], v[66:69]
	v_mfma_f32_16x16x32_bf16 v[66:69], v[188:191], v[226:229], v[66:69]
	v_mfma_f32_16x16x32_bf16 v[82:85], v[188:191], v[218:221], v[82:85]
	v_mfma_f32_16x16x32_bf16 v[82:85], v[184:187], v[214:217], v[82:85]
	v_mfma_f32_16x16x32_bf16 v[98:101], v[184:187], v[206:209], v[98:101]
	v_mfma_f32_16x16x32_bf16 v[98:101], v[188:191], v[210:213], v[98:101]
	v_mfma_f32_16x16x32_bf16 v[114:117], v[188:191], v[202:205], v[114:117]
	v_mfma_f32_16x16x32_bf16 v[114:117], v[184:187], v[198:201], v[114:117]
	s_barrier
; #define PG8_STAGE(bufoff, gbase, voff) do { _Pragma("unroll") for (int _i = 0; _i < 2; ++_i) \
;         __builtin_amdgcn_global_load_lds((const unsigned*)((const char*)(gbase) + (voff)[_i]), (PG8_LAS unsigned*)(lds + (bufoff) + ldsw + _i * 8192), 16, 0, 0); } while (0)
; #define PG8_LDA(dst, b, h) do { _Pragma("unroll") for (int m = 0; m < 4; ++m) _Pragma("unroll") for (int k = 0; k < 2; ++k) dst[m][k] = *(const PG8_LAS bf16x8*)(lds + PG8_SA(b, h) + aoff + m * 2048 + k * 1024); } while (0)
; #define PG8_LDB(dst, b, h) do { _Pragma("unroll") for (int n = 0; n < 2; ++n) _Pragma("unroll") for (int k = 0; k < 2; ++k) dst[n][k] = *(const PG8_LAS bf16x8*)(lds + PG8_SB(b, h) + boff + n * 2048 + k * 1024); } while (0)
; template <class Epi, class Sched, bool ALIGN_EPI = false, bool SP2 = false>
; __device__ __forceinline__ void gemm_phase(PG8_LAS unsigned char* lds, const Gemm g, const Sched& S, const Epi& E) {
;     ...
;         for (; t < tend; t += 2) {
;             const bool last = (t == nt - 2);
;             const char* a1 = cA + (size_t)(t + 1) * kstep;
;             const char* a2 = last ? nA : cA + (size_t)(t + 2) * kstep; const char* b2 = last ? nB : cB + (size_t)(t + 2) * kstep;
;             const char* a3 = a2 + kstep; const char* b3 = b2 + kstep;
;             if (last && has_next) S.a_ready(nxt);
;             if constexpr (SP2) {
;             PG8_LDB(B0, 0, 0); PG8_LDB(B1, 0, 1); PG8_SCHED; PG8_LDA(At, 0, 0); PG8_STAGE(PG8_SA(1, 1), a1 + hstep, voffA);
;             PG8_WAIT_V(8); PG8_WAIT_L(0); PG8_BAR; PG8_MMA(0, 0, At, B0); PG8_MMA(0, 1, At, B1); PG8_BAR; PG8_SCHED;
;             PG8_LDA(At, 0, 1); PG8_STAGE(PG8_SB(0, 0), b2, voffB); PG8_STAGE(PG8_SB(0, 1), b2 + hstep, voffB); PG8_STAGE(PG8_SA(0, 0), a2, voffA);
;             PG8_WAIT_V(8); PG8_WAIT_L(0); PG8_BAR; PG8_MMA(1, 0, At, B0); PG8_MMA(1, 1, At, B1); PG8_BAR; PG8_SCHED;
;             PG8_LDB(B0, 1, 0); PG8_LDB(B1, 1, 1); PG8_SCHED; PG8_LDA(At, 1, 0); PG8_STAGE(PG8_SA(0, 1), a2 + hstep, voffA);
;             PG8_WAIT_V(8); PG8_WAIT_L(0); PG8_BAR; PG8_MMA(0, 0, At, B0); PG8_MMA(0, 1, At, B1); PG8_BAR; PG8_SCHED;
;             PG8_LDA(At, 1, 1); PG8_STAGE(PG8_SB(1, 0), b3, voffB); PG8_STAGE(PG8_SB(1, 1), b3 + hstep, voffB); PG8_STAGE(PG8_SA(1, 0), a3, voffA);
;             PG8_WAIT_V(8); PG8_WAIT_L(0); PG8_BAR; PG8_MMA(1, 0, At, B0); PG8_MMA(1, 1, At, B1); PG8_BAR; PG8_SCHED;
	s_add_u32 s62, s76, 0x8000
	s_addc_u32 s63, s77, 0
	s_add_i32 s59, s59, s3
	s_mov_b32 m0, s59
	ds_read_b128 v[198:201], v164 offset:49152
	ds_read_b128 v[202:205], v164 offset:50176
	ds_read_b128 v[206:209], v164 offset:51200
	ds_read_b128 v[210:213], v164 offset:52224
	ds_read_b128 v[214:217], v164 offset:53248
	ds_read_b128 v[218:221], v164 offset:54272
	ds_read_b128 v[222:225], v164 offset:55296
	ds_read_b128 v[226:229], v164 offset:56320
	global_load_lds_dwordx4 v132, s[62:63]
	s_add_i32 m0, s59, 0x2000
	v_lshl_add_u64 v[158:159], s[62:63], 0, v[136:137]
	s_add_u32 s62, s76, 0xc000
	s_addc_u32 s63, s77, 0
	s_add_i32 s59, s64, s3
	global_load_lds_dwordx4 v[158:159], off
	s_mov_b32 m0, s59
	s_nop 0
	global_load_lds_dwordx4 v132, s[62:63]
	s_add_i32 m0, s59, 0x2000
	s_nop 0
	global_load_lds_dwordx4 v136, s[62:63]
	s_add_i32 s58, s58, 2
	s_add_u32 s72, s72, 0x10000
	s_addc_u32 s73, s73, 0
	s_add_u32 s33, s33, 0x10000
	s_addc_u32 s56, s56, 0
	s_add_u32 s59, s72, 0x4000
	s_addc_u32 s62, s73, 0
	s_cmp_eq_u32 s58, 60
	s_cselect_b32 s78, s19, s59
	s_cselect_b32 s79, s5, s62
	s_cselect_b32 s76, s26, s33
	s_cselect_b32 s77, s17, s56
	s_add_u32 s74, s78, 0x8000
	s_addc_u32 s75, s79, 0
	s_sub_u32 s74, s72, 0x4000
	s_subb_u32 s75, s73, 0
	s_cmp_gt_u32 s58, 61
	s_waitcnt vmcnt(6)
	s_waitcnt lgkmcnt(0)
	s_barrier
	s_waitcnt lgkmcnt(0)
	v_mfma_f32_16x16x32_bf16 v[62:65], v[146:149], v[198:201], v[62:65]
	v_mfma_f32_16x16x32_bf16 v[62:65], v[150:153], v[202:205], v[62:65]
	v_mfma_f32_16x16x32_bf16 v[46:49], v[150:153], v[210:213], v[46:49]
	v_mfma_f32_16x16x32_bf16 v[46:49], v[146:149], v[206:209], v[46:49]
	v_mfma_f32_16x16x32_bf16 v[30:33], v[146:149], v[214:217], v[30:33]
	v_mfma_f32_16x16x32_bf16 v[30:33], v[150:153], v[218:221], v[30:33]
	v_mfma_f32_16x16x32_bf16 v[14:17], v[150:153], v[226:229], v[14:17]
	v_mfma_f32_16x16x32_bf16 v[14:17], v[146:149], v[222:225], v[14:17]
	v_mfma_f32_16x16x32_bf16 v[10:13], v[154:157], v[222:225], v[10:13]
	v_mfma_f32_16x16x32_bf16 v[10:13], v[168:171], v[226:229], v[10:13]
	v_mfma_f32_16x16x32_bf16 v[26:29], v[168:171], v[218:221], v[26:29]
	v_mfma_f32_16x16x32_bf16 v[26:29], v[154:157], v[214:217], v[26:29]
	v_mfma_f32_16x16x32_bf16 v[42:45], v[154:157], v[206:209], v[42:45]
	v_mfma_f32_16x16x32_bf16 v[42:45], v[168:171], v[210:213], v[42:45]
	v_mfma_f32_16x16x32_bf16 v[58:61], v[168:171], v[202:205], v[58:61]
	v_mfma_f32_16x16x32_bf16 v[58:61], v[154:157], v[198:201], v[58:61]
	v_mfma_f32_16x16x32_bf16 v[54:57], v[172:175], v[198:201], v[54:57]
	v_mfma_f32_16x16x32_bf16 v[54:57], v[180:183], v[202:205], v[54:57]
	v_mfma_f32_16x16x32_bf16 v[38:41], v[180:183], v[210:213], v[38:41]
	v_mfma_f32_16x16x32_bf16 v[38:41], v[172:175], v[206:209], v[38:41]
	v_mfma_f32_16x16x32_bf16 v[22:25], v[172:175], v[214:217], v[22:25]
	v_mfma_f32_16x16x32_bf16 v[22:25], v[180:183], v[218:221], v[22:25]
	v_mfma_f32_16x16x32_bf16 v[6:9], v[180:183], v[226:229], v[6:9]
	v_mfma_f32_16x16x32_bf16 v[6:9], v[172:175], v[222:225], v[6:9]
	v_mfma_f32_16x16x32_bf16 v[2:5], v[184:187], v[222:225], v[2:5]
	v_mfma_f32_16x16x32_bf16 v[2:5], v[188:191], v[226:229], v[2:5]
	v_mfma_f32_16x16x32_bf16 v[18:21], v[188:191], v[218:221], v[18:21]
	v_mfma_f32_16x16x32_bf16 v[18:21], v[184:187], v[214:217], v[18:21]
	v_mfma_f32_16x16x32_bf16 v[34:37], v[184:187], v[206:209], v[34:37]
	v_mfma_f32_16x16x32_bf16 v[34:37], v[188:191], v[210:213], v[34:37]
	v_mfma_f32_16x16x32_bf16 v[50:53], v[188:191], v[202:205], v[50:53]
	v_mfma_f32_16x16x32_bf16 v[50:53], v[184:187], v[198:201], v[50:53]
	s_barrier
.LBB0_290:
	ds_read_b128 v[146:149], v162
	ds_read_b128 v[150:153], v162 offset:1024
	ds_read_b128 v[154:157], v162 offset:2048
	ds_read_b128 v[168:171], v162 offset:3072
	ds_read_b128 v[172:175], v163
	ds_read_b128 v[180:183], v163 offset:1024
	ds_read_b128 v[184:187], v163 offset:2048
	ds_read_b128 v[188:191], v163 offset:3072
	s_mov_b32 m0, s51
	s_nop 0
	global_load_lds_dwordx4 v130, s[74:75]
	s_mov_b32 m0, s57
	s_nop 0
	global_load_lds_dwordx4 v134, s[74:75]
	s_add_i32 m0, s15, 0xc000
	ds_read_b128 v[198:201], v164
	ds_read_b128 v[202:205], v164 offset:1024
	ds_read_b128 v[206:209], v164 offset:2048
	ds_read_b128 v[210:213], v164 offset:3072
	ds_read_b128 v[214:217], v164 offset:4096
	ds_read_b128 v[218:221], v164 offset:5120
	ds_read_b128 v[222:225], v164 offset:6144
	ds_read_b128 v[226:229], v164 offset:7168
	global_load_lds_dwordx4 v138, s[72:73]
	s_add_i32 m0, s15, 0xe000
	s_nop 0
	global_load_lds_dwordx4 v140, s[72:73]
	s_waitcnt vmcnt(8)
	s_waitcnt lgkmcnt(0)
	s_barrier
; #define PG8_STAGE(bufoff, gbase, voff) do { _Pragma("unroll") for (int _i = 0; _i < 2; ++_i) \
;         __builtin_amdgcn_global_load_lds((const unsigned*)((const char*)(gbase) + (voff)[_i]), (PG8_LAS unsigned*)(lds + (bufoff) + ldsw + _i * 8192), 16, 0, 0); } while (0)
; #define PG8_LDA(dst, b, h) do { _Pragma("unroll") for (int m = 0; m < 4; ++m) _Pragma("unroll") for (int k = 0; k < 2; ++k) dst[m][k] = *(const PG8_LAS bf16x8*)(lds + PG8_SA(b, h) + aoff + m * 2048 + k * 1024); } while (0)
; #define PG8_LDB(dst, b, h) do { _Pragma("unroll") for (int n = 0; n < 2; ++n) _Pragma("unroll") for (int k = 0; k < 2; ++k) dst[n][k] = *(const PG8_LAS bf16x8*)(lds + PG8_SB(b, h) + boff + n * 2048 + k * 1024); } while (0)
; #define PG8_MMA(ai, bj, At, Bt) do { __builtin_amdgcn_s_setprio(1); _Pragma("unroll") for (int m = 0; m < 4; ++m) _Pragma("unroll") for (int n = 0; n < 2; ++n) _Pragma("unroll") for (int k = 0; k < 2; ++k) \
;         acc[ai][bj][m][n] = __builtin_amdgcn_mfma_f32_16x16x32_bf16(Bt[n][k], At[m][k], acc[ai][bj][m][n], 0, 0, 0); __builtin_amdgcn_s_setprio(0); } while (0)
; #define PG8_WAIT_V(n) asm volatile("s_waitcnt vmcnt(" #n ")" ::: "memory")
; #define PG8_WAIT_L(n) asm volatile("s_waitcnt lgkmcnt(" #n ")" ::: "memory")
; #define PG8_BAR __builtin_amdgcn_s_barrier()
; #define PG8_SCHED __builtin_amdgcn_sched_barrier(0)
; template <class Epi, class Sched, bool ALIGN_EPI = false, bool SP2 = false>
; __device__ __forceinline__ void gemm_phase(PG8_LAS unsigned char* lds, const Gemm g, const Sched& S, const Epi& E) {
;     ...
;             PG8_LDB(B0, 0, 0); PG8_LDB(B1, 0, 1); PG8_SCHED; PG8_LDA(At, 0, 0); PG8_STAGE(PG8_SA(1, 1), a1 + hstep, voffA);
;             PG8_WAIT_V(8); PG8_WAIT_L(0); PG8_BAR; PG8_MMA(0, 0, At, B0); PG8_MMA(0, 1, At, B1); PG8_BAR; PG8_SCHED;
;             PG8_LDA(At, 0, 1); PG8_STAGE(PG8_SB(0, 0), b2, voffB); PG8_STAGE(PG8_SB(0, 1), b2 + hstep, voffB); PG8_STAGE(PG8_SA(0, 0), a2, voffA);
;             PG8_WAIT_V(8); PG8_WAIT_L(0); PG8_BAR; PG8_MMA(1, 0, At, B0); PG8_MMA(1, 1, At, B1); PG8_BAR; PG8_SCHED;
	s_waitcnt lgkmcnt(0)
	v_mfma_f32_16x16x32_bf16 v[126:129], v[146:149], v[198:201], v[126:129]
	v_mfma_f32_16x16x32_bf16 v[126:129], v[150:153], v[202:205], v[126:129]
	v_mfma_f32_16x16x32_bf16 v[110:113], v[150:153], v[210:213], v[110:113]
	v_mfma_f32_16x16x32_bf16 v[110:113], v[146:149], v[206:209], v[110:113]
	v_mfma_f32_16x16x32_bf16 v[94:97], v[146:149], v[214:217], v[94:97]
	v_mfma_f32_16x16x32_bf16 v[94:97], v[150:153], v[218:221], v[94:97]
	v_mfma_f32_16x16x32_bf16 v[78:81], v[150:153], v[226:229], v[78:81]
	v_mfma_f32_16x16x32_bf16 v[78:81], v[146:149], v[222:225], v[78:81]
	v_mfma_f32_16x16x32_bf16 v[74:77], v[154:157], v[222:225], v[74:77]
	v_mfma_f32_16x16x32_bf16 v[74:77], v[168:171], v[226:229], v[74:77]
	v_mfma_f32_16x16x32_bf16 v[90:93], v[168:171], v[218:221], v[90:93]
	v_mfma_f32_16x16x32_bf16 v[90:93], v[154:157], v[214:217], v[90:93]
	v_mfma_f32_16x16x32_bf16 v[106:109], v[154:157], v[206:209], v[106:109]
	v_mfma_f32_16x16x32_bf16 v[106:109], v[168:171], v[210:213], v[106:109]
	v_mfma_f32_16x16x32_bf16 v[122:125], v[168:171], v[202:205], v[122:125]
	v_mfma_f32_16x16x32_bf16 v[122:125], v[154:157], v[198:201], v[122:125]
	v_mfma_f32_16x16x32_bf16 v[118:121], v[172:175], v[198:201], v[118:121]
	v_mfma_f32_16x16x32_bf16 v[118:121], v[180:183], v[202:205], v[118:121]
	v_mfma_f32_16x16x32_bf16 v[102:105], v[180:183], v[210:213], v[102:105]
	v_mfma_f32_16x16x32_bf16 v[102:105], v[172:175], v[206:209], v[102:105]
	v_mfma_f32_16x16x32_bf16 v[86:89], v[172:175], v[214:217], v[86:89]
	v_mfma_f32_16x16x32_bf16 v[86:89], v[180:183], v[218:221], v[86:89]
	v_mfma_f32_16x16x32_bf16 v[70:73], v[180:183], v[226:229], v[70:73]
	v_mfma_f32_16x16x32_bf16 v[70:73], v[172:175], v[222:225], v[70:73]
	v_mfma_f32_16x16x32_bf16 v[66:69], v[184:187], v[222:225], v[66:69]
	v_mfma_f32_16x16x32_bf16 v[66:69], v[188:191], v[226:229], v[66:69]
	v_mfma_f32_16x16x32_bf16 v[82:85], v[188:191], v[218:221], v[82:85]
	v_mfma_f32_16x16x32_bf16 v[82:85], v[184:187], v[214:217], v[82:85]
	v_mfma_f32_16x16x32_bf16 v[98:101], v[184:187], v[206:209], v[98:101]
	v_mfma_f32_16x16x32_bf16 v[98:101], v[188:191], v[210:213], v[98:101]
	v_mfma_f32_16x16x32_bf16 v[114:117], v[188:191], v[202:205], v[114:117]
	v_mfma_f32_16x16x32_bf16 v[114:117], v[184:187], v[198:201], v[114:117]
	s_barrier
	s_add_i32 s59, s81, s3
	s_mov_b32 m0, s59
	ds_read_b128 v[198:201], v164 offset:16384
	ds_read_b128 v[202:205], v164 offset:17408
	ds_read_b128 v[206:209], v164 offset:18432
	ds_read_b128 v[210:213], v164 offset:19456
	ds_read_b128 v[214:217], v164 offset:20480
	ds_read_b128 v[218:221], v164 offset:21504
	ds_read_b128 v[222:225], v164 offset:22528
	ds_read_b128 v[226:229], v164 offset:23552
	global_load_lds_dwordx4 v132, s[76:77]
	s_add_i32 m0, s59, 0x2000
	s_add_u32 s62, s76, 0x4000
	s_addc_u32 s63, s77, 0
	s_add_i32 s59, s82, s3
	global_load_lds_dwordx4 v136, s[76:77]
	s_mov_b32 m0, s59
	s_nop 0
	global_load_lds_dwordx4 v132, s[62:63]
	s_add_i32 m0, s59, 0x2000
	s_nop 0
	global_load_lds_dwordx4 v136, s[62:63]
	s_waitcnt vmcnt(6)
	s_waitcnt lgkmcnt(0)
	s_barrier
	s_waitcnt lgkmcnt(0)
	v_mfma_f32_16x16x32_bf16 v[62:65], v[146:149], v[198:201], v[62:65]
	v_mfma_f32_16x16x32_bf16 v[62:65], v[150:153], v[202:205], v[62:65]
	v_mfma_f32_16x16x32_bf16 v[46:49], v[150:153], v[210:213], v[46:49]
	v_mfma_f32_16x16x32_bf16 v[46:49], v[146:149], v[206:209], v[46:49]
	v_mfma_f32_16x16x32_bf16 v[30:33], v[146:149], v[214:217], v[30:33]
	v_mfma_f32_16x16x32_bf16 v[30:33], v[150:153], v[218:221], v[30:33]
	v_mfma_f32_16x16x32_bf16 v[14:17], v[150:153], v[226:229], v[14:17]
	v_mfma_f32_16x16x32_bf16 v[14:17], v[146:149], v[222:225], v[14:17]
	v_mfma_f32_16x16x32_bf16 v[10:13], v[154:157], v[222:225], v[10:13]
	v_mfma_f32_16x16x32_bf16 v[10:13], v[168:171], v[226:229], v[10:13]
	v_mfma_f32_16x16x32_bf16 v[26:29], v[168:171], v[218:221], v[26:29]
	v_mfma_f32_16x16x32_bf16 v[26:29], v[154:157], v[214:217], v[26:29]
	v_mfma_f32_16x16x32_bf16 v[42:45], v[154:157], v[206:209], v[42:45]
	v_mfma_f32_16x16x32_bf16 v[42:45], v[168:171], v[210:213], v[42:45]
	v_mfma_f32_16x16x32_bf16 v[58:61], v[168:171], v[202:205], v[58:61]
	v_mfma_f32_16x16x32_bf16 v[58:61], v[154:157], v[198:201], v[58:61]
	v_mfma_f32_16x16x32_bf16 v[54:57], v[172:175], v[198:201], v[54:57]
	v_mfma_f32_16x16x32_bf16 v[54:57], v[180:183], v[202:205], v[54:57]
	v_mfma_f32_16x16x32_bf16 v[38:41], v[180:183], v[210:213], v[38:41]
	v_mfma_f32_16x16x32_bf16 v[38:41], v[172:175], v[206:209], v[38:41]
	v_mfma_f32_16x16x32_bf16 v[22:25], v[172:175], v[214:217], v[22:25]
	v_mfma_f32_16x16x32_bf16 v[22:25], v[180:183], v[218:221], v[22:25]
	v_mfma_f32_16x16x32_bf16 v[6:9], v[180:183], v[226:229], v[6:9]
	v_mfma_f32_16x16x32_bf16 v[6:9], v[172:175], v[222:225], v[6:9]
	v_mfma_f32_16x16x32_bf16 v[2:5], v[184:187], v[222:225], v[2:5]
	v_mfma_f32_16x16x32_bf16 v[2:5], v[188:191], v[226:229], v[2:5]
	v_mfma_f32_16x16x32_bf16 v[18:21], v[188:191], v[218:221], v[18:21]
	v_mfma_f32_16x16x32_bf16 v[18:21], v[184:187], v[214:217], v[18:21]
	v_mfma_f32_16x16x32_bf16 v[34:37], v[184:187], v[206:209], v[34:37]
	v_mfma_f32_16x16x32_bf16 v[34:37], v[188:191], v[210:213], v[34:37]
	v_mfma_f32_16x16x32_bf16 v[50:53], v[188:191], v[202:205], v[50:53]
	v_mfma_f32_16x16x32_bf16 v[50:53], v[184:187], v[198:201], v[50:53]
	s_barrier
; #define PG8_STAGE(bufoff, gbase, voff) do { _Pragma("unroll") for (int _i = 0; _i < 2; ++_i) \
;         __builtin_amdgcn_global_load_lds((const unsigned*)((const char*)(gbase) + (voff)[_i]), (PG8_LAS unsigned*)(lds + (bufoff) + ldsw + _i * 8192), 16, 0, 0); } while (0)
; #define PG8_LDA(dst, b, h) do { _Pragma("unroll") for (int m = 0; m < 4; ++m) _Pragma("unroll") for (int k = 0; k < 2; ++k) dst[m][k] = *(const PG8_LAS bf16x8*)(lds + PG8_SA(b, h) + aoff + m * 2048 + k * 1024); } while (0)
; #define PG8_LDB(dst, b, h) do { _Pragma("unroll") for (int n = 0; n < 2; ++n) _Pragma("unroll") for (int k = 0; k < 2; ++k) dst[n][k] = *(const PG8_LAS bf16x8*)(lds + PG8_SB(b, h) + boff + n * 2048 + k * 1024); } while (0)
; #define PG8_MMA(ai, bj, At, Bt) do { __builtin_amdgcn_s_setprio(1); _Pragma("unroll") for (int m = 0; m < 4; ++m) _Pragma("unroll") for (int n = 0; n < 2; ++n) _Pragma("unroll") for (int k = 0; k < 2; ++k) \
;         acc[ai][bj][m][n] = __builtin_amdgcn_mfma_f32_16x16x32_bf16(Bt[n][k], At[m][k], acc[ai][bj][m][n], 0, 0, 0); __builtin_amdgcn_s_setprio(0); } while (0)
; #define PG8_WAIT_V(n) asm volatile("s_waitcnt vmcnt(" #n ")" ::: "memory")
; #define PG8_WAIT_L(n) asm volatile("s_waitcnt lgkmcnt(" #n ")" ::: "memory")
; #define PG8_BAR __builtin_amdgcn_s_barrier()
; #define PG8_SCHED __builtin_amdgcn_sched_barrier(0)
; template <class Epi, class Sched, bool ALIGN_EPI = false, bool SP2 = false>
; __device__ __forceinline__ void gemm_phase(PG8_LAS unsigned char* lds, const Gemm g, const Sched& S, const Epi& E) {
;     ...
;             PG8_LDB(B0, 1, 0); PG8_LDB(B1, 1, 1); PG8_SCHED; PG8_LDA(At, 1, 0); PG8_STAGE(PG8_SA(0, 1), a2 + hstep, voffA);
;             PG8_WAIT_V(8); PG8_WAIT_L(0); PG8_BAR; PG8_MMA(0, 0, At, B0); PG8_MMA(0, 1, At, B1); PG8_BAR; PG8_SCHED;
	s_add_i32 s59, 0, 0x18000
	v_add_u32_e32 v158, s59, v160
	s_add_i32 s64, 0, 0x1c000
	ds_read_b128 v[146:149], v158
	ds_read_b128 v[150:153], v158 offset:1024
	ds_read_b128 v[154:157], v158 offset:2048
	ds_read_b128 v[168:171], v158 offset:3072
	v_add_u32_e32 v158, s64, v160
	ds_read_b128 v[172:175], v158
	ds_read_b128 v[180:183], v158 offset:1024
	ds_read_b128 v[184:187], v158 offset:2048
	ds_read_b128 v[188:191], v158 offset:3072
	s_mov_b32 m0, s15
	s_nop 0
	global_load_lds_dwordx4 v130, s[78:79]
	s_mov_b32 m0, s27
	s_nop 0
	global_load_lds_dwordx4 v134, s[78:79]
	s_add_u32 s62, s78, 0x4000
	s_addc_u32 s63, s79, 0
	s_mov_b32 m0, s28
	ds_read_b128 v[198:201], v164 offset:32768
	ds_read_b128 v[202:205], v164 offset:33792
	ds_read_b128 v[206:209], v164 offset:34816
	ds_read_b128 v[210:213], v164 offset:35840
	ds_read_b128 v[214:217], v164 offset:36864
	ds_read_b128 v[218:221], v164 offset:37888
	ds_read_b128 v[222:225], v164 offset:38912
	ds_read_b128 v[226:229], v164 offset:39936
	global_load_lds_dwordx4 v130, s[62:63]
	s_mov_b32 m0, s29
	s_nop 0
	global_load_lds_dwordx4 v134, s[62:63]
	s_waitcnt vmcnt(8)
	s_waitcnt lgkmcnt(0)
	s_barrier
	s_waitcnt lgkmcnt(0)
	v_mfma_f32_16x16x32_bf16 v[126:129], v[146:149], v[198:201], v[126:129]
	v_mfma_f32_16x16x32_bf16 v[126:129], v[150:153], v[202:205], v[126:129]
	v_mfma_f32_16x16x32_bf16 v[110:113], v[150:153], v[210:213], v[110:113]
	v_mfma_f32_16x16x32_bf16 v[110:113], v[146:149], v[206:209], v[110:113]
	v_mfma_f32_16x16x32_bf16 v[94:97], v[146:149], v[214:217], v[94:97]
	v_mfma_f32_16x16x32_bf16 v[94:97], v[150:153], v[218:221], v[94:97]
	v_mfma_f32_16x16x32_bf16 v[78:81], v[150:153], v[226:229], v[78:81]
	v_mfma_f32_16x16x32_bf16 v[78:81], v[146:149], v[222:225], v[78:81]
	v_mfma_f32_16x16x32_bf16 v[74:77], v[154:157], v[222:225], v[74:77]
	v_mfma_f32_16x16x32_bf16 v[74:77], v[168:171], v[226:229], v[74:77]
	v_mfma_f32_16x16x32_bf16 v[90:93], v[168:171], v[218:221], v[90:93]
	v_mfma_f32_16x16x32_bf16 v[90:93], v[154:157], v[214:217], v[90:93]
	v_mfma_f32_16x16x32_bf16 v[106:109], v[154:157], v[206:209], v[106:109]
	v_mfma_f32_16x16x32_bf16 v[106:109], v[168:171], v[210:213], v[106:109]
	v_mfma_f32_16x16x32_bf16 v[122:125], v[168:171], v[202:205], v[122:125]
	v_mfma_f32_16x16x32_bf16 v[122:125], v[154:157], v[198:201], v[122:125]
	v_mfma_f32_16x16x32_bf16 v[118:121], v[172:175], v[198:201], v[118:121]
	v_mfma_f32_16x16x32_bf16 v[118:121], v[180:183], v[202:205], v[118:121]
	v_mfma_f32_16x16x32_bf16 v[102:105], v[180:183], v[210:213], v[102:105]
	v_mfma_f32_16x16x32_bf16 v[102:105], v[172:175], v[206:209], v[102:105]
	v_mfma_f32_16x16x32_bf16 v[86:89], v[172:175], v[214:217], v[86:89]
	v_mfma_f32_16x16x32_bf16 v[86:89], v[180:183], v[218:221], v[86:89]
	v_mfma_f32_16x16x32_bf16 v[70:73], v[180:183], v[226:229], v[70:73]
	v_mfma_f32_16x16x32_bf16 v[70:73], v[172:175], v[222:225], v[70:73]
	v_mfma_f32_16x16x32_bf16 v[66:69], v[184:187], v[222:225], v[66:69]
	v_mfma_f32_16x16x32_bf16 v[66:69], v[188:191], v[226:229], v[66:69]
	v_mfma_f32_16x16x32_bf16 v[82:85], v[188:191], v[218:221], v[82:85]
	v_mfma_f32_16x16x32_bf16 v[82:85], v[184:187], v[214:217], v[82:85]
	v_mfma_f32_16x16x32_bf16 v[98:101], v[184:187], v[206:209], v[98:101]
	v_mfma_f32_16x16x32_bf16 v[98:101], v[188:191], v[210:213], v[98:101]
	v_mfma_f32_16x16x32_bf16 v[114:117], v[188:191], v[202:205], v[114:117]
	v_mfma_f32_16x16x32_bf16 v[114:117], v[184:187], v[198:201], v[114:117]
	s_barrier
; #define PG8_STAGE(bufoff, gbase, voff) do { _Pragma("unroll") for (int _i = 0; _i < 2; ++_i) \
;         __builtin_amdgcn_global_load_lds((const unsigned*)((const char*)(gbase) + (voff)[_i]), (PG8_LAS unsigned*)(lds + (bufoff) + ldsw + _i * 8192), 16, 0, 0); } while (0)
; #define PG8_LDA(dst, b, h) do { _Pragma("unroll") for (int m = 0; m < 4; ++m) _Pragma("unroll") for (int k = 0; k < 2; ++k) dst[m][k] = *(const PG8_LAS bf16x8*)(lds + PG8_SA(b, h) + aoff + m * 2048 + k * 1024); } while (0)
; #define PG8_LDB(dst, b, h) do { _Pragma("unroll") for (int n = 0; n < 2; ++n) _Pragma("unroll") for (int k = 0; k < 2; ++k) dst[n][k] = *(const PG8_LAS bf16x8*)(lds + PG8_SB(b, h) + boff + n * 2048 + k * 1024); } while (0)
; template <class Epi, class Sched, bool ALIGN_EPI = false, bool SP2 = false>
; __device__ __forceinline__ void gemm_phase(PG8_LAS unsigned char* lds, const Gemm g, const Sched& S, const Epi& E) {
;     ...
;         for (; t < tend; t += 2) {
;             const bool last = (t == nt - 2);
;             const char* a1 = cA + (size_t)(t + 1) * kstep;
;             const char* a2 = last ? nA : cA + (size_t)(t + 2) * kstep; const char* b2 = last ? nB : cB + (size_t)(t + 2) * kstep;
;             const char* a3 = a2 + kstep; const char* b3 = b2 + kstep;
;             if (last && has_next) S.a_ready(nxt);
;             if constexpr (SP2) {
;             PG8_LDB(B0, 0, 0); PG8_LDB(B1, 0, 1); PG8_SCHED; PG8_LDA(At, 0, 0); PG8_STAGE(PG8_SA(1, 1), a1 + hstep, voffA);
;             PG8_WAIT_V(8); PG8_WAIT_L(0); PG8_BAR; PG8_MMA(0, 0, At, B0); PG8_MMA(0, 1, At, B1); PG8_BAR; PG8_SCHED;
;             PG8_LDA(At, 0, 1); PG8_STAGE(PG8_SB(0, 0), b2, voffB); PG8_STAGE(PG8_SB(0, 1), b2 + hstep, voffB); PG8_STAGE(PG8_SA(0, 0), a2, voffA);
;             PG8_WAIT_V(8); PG8_WAIT_L(0); PG8_BAR; PG8_MMA(1, 0, At, B0); PG8_MMA(1, 1, At, B1); PG8_BAR; PG8_SCHED;
;             PG8_LDB(B0, 1, 0); PG8_LDB(B1, 1, 1); PG8_SCHED; PG8_LDA(At, 1, 0); PG8_STAGE(PG8_SA(0, 1), a2 + hstep, voffA);
;             PG8_WAIT_V(8); PG8_WAIT_L(0); PG8_BAR; PG8_MMA(0, 0, At, B0); PG8_MMA(0, 1, At, B1); PG8_BAR; PG8_SCHED;
;             PG8_LDA(At, 1, 1); PG8_STAGE(PG8_SB(1, 0), b3, voffB); PG8_STAGE(PG8_SB(1, 1), b3 + hstep, voffB); PG8_STAGE(PG8_SA(1, 0), a3, voffA);
;             PG8_WAIT_V(8); PG8_WAIT_L(0); PG8_BAR; PG8_MMA(1, 0, At, B0); PG8_MMA(1, 1, At, B1); PG8_BAR; PG8_SCHED;
	s_add_u32 s62, s76, 0x8000
	s_addc_u32 s63, s77, 0
	s_add_i32 s59, s59, s3
	s_mov_b32 m0, s59
	ds_read_b128 v[198:201], v164 offset:49152
	ds_read_b128 v[202:205], v164 offset:50176
	ds_read_b128 v[206:209], v164 offset:51200
	ds_read_b128 v[210:213], v164 offset:52224
	ds_read_b128 v[214:217], v164 offset:53248
	ds_read_b128 v[218:221], v164 offset:54272
	ds_read_b128 v[222:225], v164 offset:55296
	ds_read_b128 v[226:229], v164 offset:56320
	global_load_lds_dwordx4 v132, s[62:63]
	s_add_i32 m0, s59, 0x2000
	v_lshl_add_u64 v[158:159], s[62:63], 0, v[136:137]
	s_add_u32 s62, s76, 0xc000
	s_addc_u32 s63, s77, 0
	s_add_i32 s59, s64, s3
	global_load_lds_dwordx4 v[158:159], off
	s_mov_b32 m0, s59
	s_nop 0
	global_load_lds_dwordx4 v132, s[62:63]
	s_add_i32 m0, s59, 0x2000
	s_nop 0
	global_load_lds_dwordx4 v136, s[62:63]
	s_add_i32 s58, s58, 2
	s_add_u32 s72, s72, 0x10000
	s_addc_u32 s73, s73, 0
	s_add_u32 s33, s33, 0x10000
	s_addc_u32 s56, s56, 0
	s_add_u32 s59, s72, 0x4000
	s_addc_u32 s62, s73, 0
	s_cmp_eq_u32 s58, 60
	s_cselect_b32 s78, s19, s59
	s_cselect_b32 s79, s5, s62
	s_cselect_b32 s76, s26, s33
	s_cselect_b32 s77, s17, s56
	s_add_u32 s74, s78, 0x8000
	s_addc_u32 s75, s79, 0
	s_sub_u32 s74, s72, 0x4000
	s_subb_u32 s75, s73, 0
	s_cmp_gt_u32 s58, 61
	s_waitcnt vmcnt(6)
	s_waitcnt lgkmcnt(0)
	s_barrier
	s_waitcnt lgkmcnt(0)
	v_mfma_f32_16x16x32_bf16 v[62:65], v[146:149], v[198:201], v[62:65]
	v_mfma_f32_16x16x32_bf16 v[62:65], v[150:153], v[202:205], v[62:65]
	v_mfma_f32_16x16x32_bf16 v[46:49], v[150:153], v[210:213], v[46:49]
	v_mfma_f32_16x16x32_bf16 v[46:49], v[146:149], v[206:209], v[46:49]
	v_mfma_f32_16x16x32_bf16 v[30:33], v[146:149], v[214:217], v[30:33]
	v_mfma_f32_16x16x32_bf16 v[30:33], v[150:153], v[218:221], v[30:33]
	v_mfma_f32_16x16x32_bf16 v[14:17], v[150:153], v[226:229], v[14:17]
	v_mfma_f32_16x16x32_bf16 v[14:17], v[146:149], v[222:225], v[14:17]
	v_mfma_f32_16x16x32_bf16 v[10:13], v[154:157], v[222:225], v[10:13]
	v_mfma_f32_16x16x32_bf16 v[10:13], v[168:171], v[226:229], v[10:13]
	v_mfma_f32_16x16x32_bf16 v[26:29], v[168:171], v[218:221], v[26:29]
	v_mfma_f32_16x16x32_bf16 v[26:29], v[154:157], v[214:217], v[26:29]
	v_mfma_f32_16x16x32_bf16 v[42:45], v[154:157], v[206:209], v[42:45]
	v_mfma_f32_16x16x32_bf16 v[42:45], v[168:171], v[210:213], v[42:45]
	v_mfma_f32_16x16x32_bf16 v[58:61], v[168:171], v[202:205], v[58:61]
	v_mfma_f32_16x16x32_bf16 v[58:61], v[154:157], v[198:201], v[58:61]
	v_mfma_f32_16x16x32_bf16 v[54:57], v[172:175], v[198:201], v[54:57]
	v_mfma_f32_16x16x32_bf16 v[54:57], v[180:183], v[202:205], v[54:57]
	v_mfma_f32_16x16x32_bf16 v[38:41], v[180:183], v[210:213], v[38:41]
	v_mfma_f32_16x16x32_bf16 v[38:41], v[172:175], v[206:209], v[38:41]
	v_mfma_f32_16x16x32_bf16 v[22:25], v[172:175], v[214:217], v[22:25]
	v_mfma_f32_16x16x32_bf16 v[22:25], v[180:183], v[218:221], v[22:25]
	v_mfma_f32_16x16x32_bf16 v[6:9], v[180:183], v[226:229], v[6:9]
	v_mfma_f32_16x16x32_bf16 v[6:9], v[172:175], v[222:225], v[6:9]
	v_mfma_f32_16x16x32_bf16 v[2:5], v[184:187], v[222:225], v[2:5]
	v_mfma_f32_16x16x32_bf16 v[2:5], v[188:191], v[226:229], v[2:5]
	v_mfma_f32_16x16x32_bf16 v[18:21], v[188:191], v[218:221], v[18:21]
	v_mfma_f32_16x16x32_bf16 v[18:21], v[184:187], v[214:217], v[18:21]
	v_mfma_f32_16x16x32_bf16 v[34:37], v[184:187], v[206:209], v[34:37]
	v_mfma_f32_16x16x32_bf16 v[34:37], v[188:191], v[210:213], v[34:37]
	v_mfma_f32_16x16x32_bf16 v[50:53], v[188:191], v[202:205], v[50:53]
	v_mfma_f32_16x16x32_bf16 v[50:53], v[184:187], v[198:201], v[50:53]
	s_barrier
	s_cbranch_scc0 .LBB0_290
	s_and_b64 vcc, exec, s[12:13]
	s_cbranch_vccz .LBB0_293
	s_barrier

;     __device__ __forceinline__ bool next(int i, Unit& u) const { if (i >= 2) return false; const int xcd = c & 7, off = c >> 3; u.pm = 16 * i + 4 * (xcd >> 1) + (off & 3); u.pn = 8 * (xcd & 1) + (off >> 2); return true; }
; #define PG8_STAGE(bufoff, gbase, voff) do { _Pragma("unroll") for (int _i = 0; _i < 2; ++_i) \
;         __builtin_amdgcn_global_load_lds((const unsigned*)((const char*)(gbase) + (voff)[_i]), (PG8_LAS unsigned*)(lds + (bufoff) + ldsw + _i * 8192), 16, 0, 0); } while (0)
; #define PG8_LDA(dst, b, h) do { _Pragma("unroll") for (int m = 0; m < 4; ++m) _Pragma("unroll") for (int k = 0; k < 2; ++k) dst[m][k] = *(const PG8_LAS bf16x8*)(lds + PG8_SA(b, h) + aoff + m * 2048 + k * 1024); } while (0)
; #define PG8_LDB(dst, b, h) do { _Pragma("unroll") for (int n = 0; n < 2; ++n) _Pragma("unroll") for (int k = 0; k < 2; ++k) dst[n][k] = *(const PG8_LAS bf16x8*)(lds + PG8_SB(b, h) + boff + n * 2048 + k * 1024); } while (0)
; #define PG8_WAIT_V(n) asm volatile("s_waitcnt vmcnt(" #n ")" ::: "memory")
; #define PG8_WAIT_L(n) asm volatile("s_waitcnt lgkmcnt(" #n ")" ::: "memory")
; template <class Epi, class Sched, bool ALIGN_EPI = false, bool SP2 = false>
; __device__ __forceinline__ void gemm_phase(PG8_LAS unsigned char* lds, const Gemm g, const Sched& S, const Epi& E) {
;     ...
;         const bool has_next = S.next(ui + 1, nxt);
;         const char* nA = has_next ? (const char*)g.A + (size_t)nxt.pm * tstep : cA; const char* nB = has_next ? (const char*)g.Bt + (size_t)nxt.pn * tstep : cB;
;         constexpr int NSEG = Epi::HAS_MID ? 2 : 1; int t = 0;
; #pragma unroll
;         for (int seg = 0; seg < NSEG; ++seg) { const int tend = (seg + 1 < NSEG) ? (nt >> 1) : nt;
;         for (; t < tend; t += 2) {
;             const bool last = (t == nt - 2);
;             const char* a1 = cA + (size_t)(t + 1) * kstep;
;             const char* a2 = last ? nA : cA + (size_t)(t + 2) * kstep; const char* b2 = last ? nB : cB + (size_t)(t + 2) * kstep;
;             const char* a3 = a2 + kstep; const char* b3 = b2 + kstep;
;             if (last && has_next) S.a_ready(nxt);
;             if constexpr (SP2) {
;             PG8_LDB(B0, 0, 0); PG8_LDB(B1, 0, 1); PG8_SCHED; PG8_LDA(At, 0, 0); PG8_STAGE(PG8_SA(1, 1), a1 + hstep, voffA);
;             PG8_WAIT_V(8); PG8_WAIT_L(0); PG8_BAR; PG8_MMA(0, 0, At, B0); PG8_MMA(0, 1, At, B1); PG8_BAR; PG8_SCHED;
.LBB0_756:
	s_ashr_i32 s17, s16, 31
	s_lshl_b64 s[22:23], s[16:17], 21
	s_add_u32 s22, s66, s22
	s_addc_u32 s23, s67, s23
	s_and_b64 s[36:37], s[4:5], exec
	s_cselect_b32 s17, s23, s45
	s_cselect_b32 s39, s22, s44
	s_ashr_i32 s15, s14, 31
	s_lshl_b64 s[36:37], s[14:15], 21
	v_readlane_b32 s48, v255, 17
	v_readlane_b32 s49, v255, 18
	s_add_u32 s36, s48, s36
	s_addc_u32 s37, s49, s37
	s_and_b64 s[48:49], s[4:5], exec
	s_cselect_b32 s15, s37, s47
	s_cselect_b32 s41, s36, s46
	s_add_u32 s44, s44, 0xc000
	s_addc_u32 s45, s45, 0
	s_add_u32 s68, s46, 0x10000
	s_addc_u32 s69, s47, 0
	s_mov_b32 s70, -2
	s_waitcnt lgkmcnt(0)
	s_nop 3
	s_add_u32 s46, s44, 0x4000
	s_addc_u32 s47, s45, 0
	s_cmp_eq_u32 s70, 60
	s_cselect_b32 s50, s39, s46
	s_cselect_b32 s51, s17, s47
	s_cselect_b32 s48, s41, s68
	s_cselect_b32 s49, s15, s69
	s_add_u32 s46, s50, 0x8000
	s_addc_u32 s47, s51, 0
	s_sub_u32 s46, s44, 0x4000
	s_subb_u32 s47, s45, 0
	ds_read_b128 v[154:157], v149
	ds_read_b128 v[158:161], v149 offset:1024
	ds_read_b128 v[162:165], v149 offset:2048
	ds_read_b128 v[166:169], v149 offset:3072
	ds_read_b128 v[170:173], v150
	ds_read_b128 v[174:177], v150 offset:1024
	ds_read_b128 v[180:183], v150 offset:2048
	ds_read_b128 v[184:187], v150 offset:3072
	s_mov_b32 m0, s57
	s_nop 0
	global_load_lds_dwordx4 v130, s[46:47]
	s_mov_b32 m0, s58
	s_nop 0
	global_load_lds_dwordx4 v134, s[46:47]
	s_add_i32 m0, s26, 0xc000
	ds_read_b128 v[188:191], v151
	ds_read_b128 v[198:201], v151 offset:1024
	ds_read_b128 v[202:205], v151 offset:2048
	ds_read_b128 v[206:209], v151 offset:3072
	ds_read_b128 v[210:213], v151 offset:4096
	ds_read_b128 v[214:217], v151 offset:5120
	ds_read_b128 v[218:221], v151 offset:6144
	ds_read_b128 v[222:225], v151 offset:7168
	global_load_lds_dwordx4 v138, s[44:45]
	s_add_i32 m0, s26, 0xe000
	s_nop 0
	global_load_lds_dwordx4 v140, s[44:45]
	s_waitcnt vmcnt(8)
	s_waitcnt lgkmcnt(0)
	s_barrier
	s_waitcnt lgkmcnt(0)
	v_mfma_f32_16x16x32_bf16 v[126:129], v[154:157], v[188:191], 0
	v_mfma_f32_16x16x32_bf16 v[126:129], v[158:161], v[198:201], v[126:129]
	v_mfma_f32_16x16x32_bf16 v[110:113], v[158:161], v[206:209], 0
	v_mfma_f32_16x16x32_bf16 v[110:113], v[154:157], v[202:205], v[110:113]
	v_mfma_f32_16x16x32_bf16 v[94:97], v[154:157], v[210:213], 0
	v_mfma_f32_16x16x32_bf16 v[94:97], v[158:161], v[214:217], v[94:97]
	v_mfma_f32_16x16x32_bf16 v[78:81], v[158:161], v[222:225], 0
	v_mfma_f32_16x16x32_bf16 v[78:81], v[154:157], v[218:221], v[78:81]
	v_mfma_f32_16x16x32_bf16 v[74:77], v[162:165], v[218:221], 0
	v_mfma_f32_16x16x32_bf16 v[74:77], v[166:169], v[222:225], v[74:77]
	v_mfma_f32_16x16x32_bf16 v[90:93], v[166:169], v[214:217], 0
	v_mfma_f32_16x16x32_bf16 v[90:93], v[162:165], v[210:213], v[90:93]
	v_mfma_f32_16x16x32_bf16 v[106:109], v[162:165], v[202:205], 0
	v_mfma_f32_16x16x32_bf16 v[106:109], v[166:169], v[206:209], v[106:109]
	v_mfma_f32_16x16x32_bf16 v[122:125], v[166:169], v[198:201], 0
	v_mfma_f32_16x16x32_bf16 v[122:125], v[162:165], v[188:191], v[122:125]
	v_mfma_f32_16x16x32_bf16 v[118:121], v[170:173], v[188:191], 0
	v_mfma_f32_16x16x32_bf16 v[118:121], v[174:177], v[198:201], v[118:121]
	v_mfma_f32_16x16x32_bf16 v[102:105], v[174:177], v[206:209], 0
	v_mfma_f32_16x16x32_bf16 v[102:105], v[170:173], v[202:205], v[102:105]
	v_mfma_f32_16x16x32_bf16 v[86:89], v[170:173], v[210:213], 0
	v_mfma_f32_16x16x32_bf16 v[86:89], v[174:177], v[214:217], v[86:89]
	v_mfma_f32_16x16x32_bf16 v[70:73], v[174:177], v[222:225], 0
	v_mfma_f32_16x16x32_bf16 v[70:73], v[170:173], v[218:221], v[70:73]
	v_mfma_f32_16x16x32_bf16 v[66:69], v[180:183], v[218:221], 0
	v_mfma_f32_16x16x32_bf16 v[66:69], v[184:187], v[222:225], v[66:69]
	v_mfma_f32_16x16x32_bf16 v[82:85], v[184:187], v[214:217], 0
	v_mfma_f32_16x16x32_bf16 v[82:85], v[180:183], v[210:213], v[82:85]
	v_mfma_f32_16x16x32_bf16 v[98:101], v[180:183], v[202:205], 0
	v_mfma_f32_16x16x32_bf16 v[98:101], v[184:187], v[206:209], v[98:101]
	v_mfma_f32_16x16x32_bf16 v[114:117], v[184:187], v[198:201], 0
	v_mfma_f32_16x16x32_bf16 v[114:117], v[180:183], v[188:191], v[114:117]
	s_barrier
	s_add_i32 s71, s59, s3
	s_mov_b32 m0, s71
	ds_read_b128 v[188:191], v151 offset:16384
	ds_read_b128 v[198:201], v151 offset:17408
	ds_read_b128 v[202:205], v151 offset:18432
	ds_read_b128 v[206:209], v151 offset:19456
	ds_read_b128 v[210:213], v151 offset:20480
	ds_read_b128 v[214:217], v151 offset:21504
	ds_read_b128 v[218:221], v151 offset:22528
	ds_read_b128 v[222:225], v151 offset:23552
	global_load_lds_dwordx4 v132, s[48:49]
	s_add_i32 m0, s71, 0x2000
	s_add_u32 s72, s48, 0x4000
	s_addc_u32 s73, s49, 0
	s_add_i32 s71, s61, s3
	global_load_lds_dwordx4 v136, s[48:49]
	s_mov_b32 m0, s71
	s_nop 0
	global_load_lds_dwordx4 v132, s[72:73]
	s_add_i32 m0, s71, 0x2000
	s_nop 0
	global_load_lds_dwordx4 v136, s[72:73]
	s_waitcnt vmcnt(6)
	s_waitcnt lgkmcnt(0)
	s_barrier
; #define PG8_STAGE(bufoff, gbase, voff) do { _Pragma("unroll") for (int _i = 0; _i < 2; ++_i) \
;         __builtin_amdgcn_global_load_lds((const unsigned*)((const char*)(gbase) + (voff)[_i]), (PG8_LAS unsigned*)(lds + (bufoff) + ldsw + _i * 8192), 16, 0, 0); } while (0)
; #define PG8_LDA(dst, b, h) do { _Pragma("unroll") for (int m = 0; m < 4; ++m) _Pragma("unroll") for (int k = 0; k < 2; ++k) dst[m][k] = *(const PG8_LAS bf16x8*)(lds + PG8_SA(b, h) + aoff + m * 2048 + k * 1024); } while (0)
; #define PG8_LDB(dst, b, h) do { _Pragma("unroll") for (int n = 0; n < 2; ++n) _Pragma("unroll") for (int k = 0; k < 2; ++k) dst[n][k] = *(const PG8_LAS bf16x8*)(lds + PG8_SB(b, h) + boff + n * 2048 + k * 1024); } while (0)
; #define PG8_MMA(ai, bj, At, Bt) do { __builtin_amdgcn_s_setprio(1); _Pragma("unroll") for (int m = 0; m < 4; ++m) _Pragma("unroll") for (int n = 0; n < 2; ++n) _Pragma("unroll") for (int k = 0; k < 2; ++k) \
;         acc[ai][bj][m][n] = __builtin_amdgcn_mfma_f32_16x16x32_bf16(Bt[n][k], At[m][k], acc[ai][bj][m][n], 0, 0, 0); __builtin_amdgcn_s_setprio(0); } while (0)
; #define PG8_WAIT_V(n) asm volatile("s_waitcnt vmcnt(" #n ")" ::: "memory")
; #define PG8_WAIT_L(n) asm volatile("s_waitcnt lgkmcnt(" #n ")" ::: "memory")
; #define PG8_BAR __builtin_amdgcn_s_barrier()
; #define PG8_SCHED __builtin_amdgcn_sched_barrier(0)
; template <class Epi, class Sched, bool ALIGN_EPI = false, bool SP2 = false>
; __device__ __forceinline__ void gemm_phase(PG8_LAS unsigned char* lds, const Gemm g, const Sched& S, const Epi& E) {
;     ...
;             PG8_WAIT_V(8); PG8_WAIT_L(0); PG8_BAR; PG8_MMA(0, 0, At, B0); PG8_MMA(0, 1, At, B1); PG8_BAR; PG8_SCHED;
;             PG8_LDA(At, 0, 1); PG8_STAGE(PG8_SB(0, 0), b2, voffB); PG8_STAGE(PG8_SB(0, 1), b2 + hstep, voffB); PG8_STAGE(PG8_SA(0, 0), a2, voffA);
;             PG8_WAIT_V(8); PG8_WAIT_L(0); PG8_BAR; PG8_MMA(1, 0, At, B0); PG8_MMA(1, 1, At, B1); PG8_BAR; PG8_SCHED;
;             PG8_LDB(B0, 1, 0); PG8_LDB(B1, 1, 1); PG8_SCHED; PG8_LDA(At, 1, 0); PG8_STAGE(PG8_SA(0, 1), a2 + hstep, voffA);
;             PG8_WAIT_V(8); PG8_WAIT_L(0); PG8_BAR; PG8_MMA(0, 0, At, B0); PG8_MMA(0, 1, At, B1); PG8_BAR; PG8_SCHED;
	s_waitcnt lgkmcnt(0)
	v_mfma_f32_16x16x32_bf16 v[62:65], v[154:157], v[188:191], 0
	v_mfma_f32_16x16x32_bf16 v[62:65], v[158:161], v[198:201], v[62:65]
	v_mfma_f32_16x16x32_bf16 v[46:49], v[158:161], v[206:209], 0
	v_mfma_f32_16x16x32_bf16 v[46:49], v[154:157], v[202:205], v[46:49]
	v_mfma_f32_16x16x32_bf16 v[30:33], v[154:157], v[210:213], 0
	v_mfma_f32_16x16x32_bf16 v[30:33], v[158:161], v[214:217], v[30:33]
	v_mfma_f32_16x16x32_bf16 v[14:17], v[158:161], v[222:225], 0
	v_mfma_f32_16x16x32_bf16 v[14:17], v[154:157], v[218:221], v[14:17]
	v_mfma_f32_16x16x32_bf16 v[10:13], v[162:165], v[218:221], 0
	v_mfma_f32_16x16x32_bf16 v[10:13], v[166:169], v[222:225], v[10:13]
	v_mfma_f32_16x16x32_bf16 v[26:29], v[166:169], v[214:217], 0
	v_mfma_f32_16x16x32_bf16 v[26:29], v[162:165], v[210:213], v[26:29]
	v_mfma_f32_16x16x32_bf16 v[42:45], v[162:165], v[202:205], 0
	v_mfma_f32_16x16x32_bf16 v[42:45], v[166:169], v[206:209], v[42:45]
	v_mfma_f32_16x16x32_bf16 v[58:61], v[166:169], v[198:201], 0
	v_mfma_f32_16x16x32_bf16 v[58:61], v[162:165], v[188:191], v[58:61]
	v_mfma_f32_16x16x32_bf16 v[54:57], v[170:173], v[188:191], 0
	v_mfma_f32_16x16x32_bf16 v[54:57], v[174:177], v[198:201], v[54:57]
	v_mfma_f32_16x16x32_bf16 v[38:41], v[174:177], v[206:209], 0
	v_mfma_f32_16x16x32_bf16 v[38:41], v[170:173], v[202:205], v[38:41]
	v_mfma_f32_16x16x32_bf16 v[22:25], v[170:173], v[210:213], 0
	v_mfma_f32_16x16x32_bf16 v[22:25], v[174:177], v[214:217], v[22:25]
	v_mfma_f32_16x16x32_bf16 v[6:9], v[174:177], v[222:225], 0
	v_mfma_f32_16x16x32_bf16 v[6:9], v[170:173], v[218:221], v[6:9]
	v_mfma_f32_16x16x32_bf16 v[2:5], v[180:183], v[218:221], 0
	v_mfma_f32_16x16x32_bf16 v[2:5], v[184:187], v[222:225], v[2:5]
	v_mfma_f32_16x16x32_bf16 v[18:21], v[184:187], v[214:217], 0
	v_mfma_f32_16x16x32_bf16 v[18:21], v[180:183], v[210:213], v[18:21]
	v_mfma_f32_16x16x32_bf16 v[34:37], v[180:183], v[202:205], 0
	v_mfma_f32_16x16x32_bf16 v[34:37], v[184:187], v[206:209], v[34:37]
	v_mfma_f32_16x16x32_bf16 v[50:53], v[184:187], v[198:201], 0
	v_mfma_f32_16x16x32_bf16 v[50:53], v[180:183], v[188:191], v[50:53]
	s_barrier
	s_add_i32 s71, 0, 0x18000
	v_add_u32_e32 v146, s71, v1
	s_add_i32 s72, 0, 0x1c000
	ds_read_b128 v[154:157], v146
	ds_read_b128 v[158:161], v146 offset:1024
	ds_read_b128 v[162:165], v146 offset:2048
	ds_read_b128 v[166:169], v146 offset:3072
	v_add_u32_e32 v146, s72, v1
	ds_read_b128 v[170:173], v146
	ds_read_b128 v[174:177], v146 offset:1024
	ds_read_b128 v[180:183], v146 offset:2048
	ds_read_b128 v[184:187], v146 offset:3072
	s_mov_b32 m0, s26
	s_nop 0
	global_load_lds_dwordx4 v130, s[50:51]
	s_mov_b32 m0, s27
	s_nop 0
	global_load_lds_dwordx4 v134, s[50:51]
	s_add_u32 s50, s50, 0x4000
	s_addc_u32 s51, s51, 0
	s_mov_b32 m0, s28
	ds_read_b128 v[188:191], v151 offset:32768
	ds_read_b128 v[198:201], v151 offset:33792
	ds_read_b128 v[202:205], v151 offset:34816
	ds_read_b128 v[206:209], v151 offset:35840
	ds_read_b128 v[210:213], v151 offset:36864
	ds_read_b128 v[214:217], v151 offset:37888
	ds_read_b128 v[218:221], v151 offset:38912
	ds_read_b128 v[222:225], v151 offset:39936
	global_load_lds_dwordx4 v130, s[50:51]
	s_mov_b32 m0, s29
	s_nop 0
	global_load_lds_dwordx4 v134, s[50:51]
	s_waitcnt vmcnt(8)
	s_waitcnt lgkmcnt(0)
	s_barrier
	s_waitcnt lgkmcnt(0)
	v_mfma_f32_16x16x32_bf16 v[126:129], v[154:157], v[188:191], v[126:129]
	v_mfma_f32_16x16x32_bf16 v[126:129], v[158:161], v[198:201], v[126:129]
	v_mfma_f32_16x16x32_bf16 v[110:113], v[158:161], v[206:209], v[110:113]
	v_mfma_f32_16x16x32_bf16 v[110:113], v[154:157], v[202:205], v[110:113]
	v_mfma_f32_16x16x32_bf16 v[94:97], v[154:157], v[210:213], v[94:97]
	v_mfma_f32_16x16x32_bf16 v[94:97], v[158:161], v[214:217], v[94:97]
	v_mfma_f32_16x16x32_bf16 v[78:81], v[158:161], v[222:225], v[78:81]
	v_mfma_f32_16x16x32_bf16 v[78:81], v[154:157], v[218:221], v[78:81]
	v_mfma_f32_16x16x32_bf16 v[74:77], v[162:165], v[218:221], v[74:77]
	v_mfma_f32_16x16x32_bf16 v[74:77], v[166:169], v[222:225], v[74:77]
	v_mfma_f32_16x16x32_bf16 v[90:93], v[166:169], v[214:217], v[90:93]
	v_mfma_f32_16x16x32_bf16 v[90:93], v[162:165], v[210:213], v[90:93]
	v_mfma_f32_16x16x32_bf16 v[106:109], v[162:165], v[202:205], v[106:109]
	v_mfma_f32_16x16x32_bf16 v[106:109], v[166:169], v[206:209], v[106:109]
	v_mfma_f32_16x16x32_bf16 v[122:125], v[166:169], v[198:201], v[122:125]
	v_mfma_f32_16x16x32_bf16 v[122:125], v[162:165], v[188:191], v[122:125]
	v_mfma_f32_16x16x32_bf16 v[118:121], v[170:173], v[188:191], v[118:121]
	v_mfma_f32_16x16x32_bf16 v[118:121], v[174:177], v[198:201], v[118:121]
	v_mfma_f32_16x16x32_bf16 v[102:105], v[174:177], v[206:209], v[102:105]
	v_mfma_f32_16x16x32_bf16 v[102:105], v[170:173], v[202:205], v[102:105]
	v_mfma_f32_16x16x32_bf16 v[86:89], v[170:173], v[210:213], v[86:89]
	v_mfma_f32_16x16x32_bf16 v[86:89], v[174:177], v[214:217], v[86:89]
	v_mfma_f32_16x16x32_bf16 v[70:73], v[174:177], v[222:225], v[70:73]
	v_mfma_f32_16x16x32_bf16 v[70:73], v[170:173], v[218:221], v[70:73]
	v_mfma_f32_16x16x32_bf16 v[66:69], v[180:183], v[218:221], v[66:69]
	v_mfma_f32_16x16x32_bf16 v[66:69], v[184:187], v[222:225], v[66:69]
	v_mfma_f32_16x16x32_bf16 v[82:85], v[184:187], v[214:217], v[82:85]
	v_mfma_f32_16x16x32_bf16 v[82:85], v[180:183], v[210:213], v[82:85]
	v_mfma_f32_16x16x32_bf16 v[98:101], v[180:183], v[202:205], v[98:101]
	v_mfma_f32_16x16x32_bf16 v[98:101], v[184:187], v[206:209], v[98:101]
	v_mfma_f32_16x16x32_bf16 v[114:117], v[184:187], v[198:201], v[114:117]
	v_mfma_f32_16x16x32_bf16 v[114:117], v[180:183], v[188:191], v[114:117]
	s_barrier
; #define PG8_STAGE(bufoff, gbase, voff) do { _Pragma("unroll") for (int _i = 0; _i < 2; ++_i) \
;         __builtin_amdgcn_global_load_lds((const unsigned*)((const char*)(gbase) + (voff)[_i]), (PG8_LAS unsigned*)(lds + (bufoff) + ldsw + _i * 8192), 16, 0, 0); } while (0)
; #define PG8_LDA(dst, b, h) do { _Pragma("unroll") for (int m = 0; m < 4; ++m) _Pragma("unroll") for (int k = 0; k < 2; ++k) dst[m][k] = *(const PG8_LAS bf16x8*)(lds + PG8_SA(b, h) + aoff + m * 2048 + k * 1024); } while (0)
; #define PG8_LDB(dst, b, h) do { _Pragma("unroll") for (int n = 0; n < 2; ++n) _Pragma("unroll") for (int k = 0; k < 2; ++k) dst[n][k] = *(const PG8_LAS bf16x8*)(lds + PG8_SB(b, h) + boff + n * 2048 + k * 1024); } while (0)
; template <class Epi, class Sched, bool ALIGN_EPI = false, bool SP2 = false>
; __device__ __forceinline__ void gemm_phase(PG8_LAS unsigned char* lds, const Gemm g, const Sched& S, const Epi& E) {
;     ...
;         for (; t < tend; t += 2) {
;             const bool last = (t == nt - 2);
;             const char* a1 = cA + (size_t)(t + 1) * kstep;
;             const char* a2 = last ? nA : cA + (size_t)(t + 2) * kstep; const char* b2 = last ? nB : cB + (size_t)(t + 2) * kstep;
;             const char* a3 = a2 + kstep; const char* b3 = b2 + kstep;
;             if (last && has_next) S.a_ready(nxt);
;             if constexpr (SP2) {
;             PG8_LDB(B0, 0, 0); PG8_LDB(B1, 0, 1); PG8_SCHED; PG8_LDA(At, 0, 0); PG8_STAGE(PG8_SA(1, 1), a1 + hstep, voffA);
;             PG8_WAIT_V(8); PG8_WAIT_L(0); PG8_BAR; PG8_MMA(0, 0, At, B0); PG8_MMA(0, 1, At, B1); PG8_BAR; PG8_SCHED;
;             PG8_LDA(At, 0, 1); PG8_STAGE(PG8_SB(0, 0), b2, voffB); PG8_STAGE(PG8_SB(0, 1), b2 + hstep, voffB); PG8_STAGE(PG8_SA(0, 0), a2, voffA);
;             PG8_WAIT_V(8); PG8_WAIT_L(0); PG8_BAR; PG8_MMA(1, 0, At, B0); PG8_MMA(1, 1, At, B1); PG8_BAR; PG8_SCHED;
;             PG8_LDB(B0, 1, 0); PG8_LDB(B1, 1, 1); PG8_SCHED; PG8_LDA(At, 1, 0); PG8_STAGE(PG8_SA(0, 1), a2 + hstep, voffA);
;             PG8_WAIT_V(8); PG8_WAIT_L(0); PG8_BAR; PG8_MMA(0, 0, At, B0); PG8_MMA(0, 1, At, B1); PG8_BAR; PG8_SCHED;
;             PG8_LDA(At, 1, 1); PG8_STAGE(PG8_SB(1, 0), b3, voffB); PG8_STAGE(PG8_SB(1, 1), b3 + hstep, voffB); PG8_STAGE(PG8_SA(1, 0), a3, voffA);
;             PG8_WAIT_V(8); PG8_WAIT_L(0); PG8_BAR; PG8_MMA(1, 0, At, B0); PG8_MMA(1, 1, At, B1); PG8_BAR; PG8_SCHED;
	s_add_u32 s50, s48, 0x8000
	s_addc_u32 s51, s49, 0
	s_add_i32 s71, s71, s3
	s_mov_b32 m0, s71
	ds_read_b128 v[188:191], v151 offset:49152
	ds_read_b128 v[198:201], v151 offset:50176
	ds_read_b128 v[202:205], v151 offset:51200
	ds_read_b128 v[206:209], v151 offset:52224
	ds_read_b128 v[210:213], v151 offset:53248
	ds_read_b128 v[214:217], v151 offset:54272
	ds_read_b128 v[218:221], v151 offset:55296
	ds_read_b128 v[222:225], v151 offset:56320
	global_load_lds_dwordx4 v132, s[50:51]
	s_add_i32 m0, s71, 0x2000
	s_add_u32 s48, s48, 0xc000
	v_lshl_add_u64 v[146:147], s[50:51], 0, v[136:137]
	s_addc_u32 s49, s49, 0
	s_add_i32 s50, s72, s3
	global_load_lds_dwordx4 v[146:147], off
	s_mov_b32 m0, s50
	s_nop 0
	global_load_lds_dwordx4 v132, s[48:49]
	s_add_i32 m0, s50, 0x2000
	s_nop 0
	global_load_lds_dwordx4 v136, s[48:49]
	s_add_i32 s70, s70, 2
	s_add_u32 s44, s44, 0x10000
	s_addc_u32 s45, s45, 0
	s_add_u32 s68, s68, 0x10000
	s_addc_u32 s69, s69, 0
	s_add_u32 s46, s44, 0x4000
	s_addc_u32 s47, s45, 0
	s_cmp_eq_u32 s70, 60
	s_cselect_b32 s50, s39, s46
	s_cselect_b32 s51, s17, s47
	s_cselect_b32 s48, s41, s68
	s_cselect_b32 s49, s15, s69
	s_add_u32 s46, s50, 0x8000
	s_addc_u32 s47, s51, 0
	s_sub_u32 s46, s44, 0x4000
	s_subb_u32 s47, s45, 0
	s_cmp_gt_u32 s70, 61
	s_waitcnt vmcnt(6)
	s_waitcnt lgkmcnt(0)
	s_barrier
	s_waitcnt lgkmcnt(0)
	v_mfma_f32_16x16x32_bf16 v[62:65], v[154:157], v[188:191], v[62:65]
	v_mfma_f32_16x16x32_bf16 v[62:65], v[158:161], v[198:201], v[62:65]
	v_mfma_f32_16x16x32_bf16 v[46:49], v[158:161], v[206:209], v[46:49]
	v_mfma_f32_16x16x32_bf16 v[46:49], v[154:157], v[202:205], v[46:49]
	v_mfma_f32_16x16x32_bf16 v[30:33], v[154:157], v[210:213], v[30:33]
	v_mfma_f32_16x16x32_bf16 v[30:33], v[158:161], v[214:217], v[30:33]
	v_mfma_f32_16x16x32_bf16 v[14:17], v[158:161], v[222:225], v[14:17]
	v_mfma_f32_16x16x32_bf16 v[14:17], v[154:157], v[218:221], v[14:17]
	v_mfma_f32_16x16x32_bf16 v[10:13], v[162:165], v[218:221], v[10:13]
	v_mfma_f32_16x16x32_bf16 v[10:13], v[166:169], v[222:225], v[10:13]
	v_mfma_f32_16x16x32_bf16 v[26:29], v[166:169], v[214:217], v[26:29]
	v_mfma_f32_16x16x32_bf16 v[26:29], v[162:165], v[210:213], v[26:29]
	v_mfma_f32_16x16x32_bf16 v[42:45], v[162:165], v[202:205], v[42:45]
	v_mfma_f32_16x16x32_bf16 v[42:45], v[166:169], v[206:209], v[42:45]
	v_mfma_f32_16x16x32_bf16 v[58:61], v[166:169], v[198:201], v[58:61]
	v_mfma_f32_16x16x32_bf16 v[58:61], v[162:165], v[188:191], v[58:61]
	v_mfma_f32_16x16x32_bf16 v[54:57], v[170:173], v[188:191], v[54:57]
	v_mfma_f32_16x16x32_bf16 v[54:57], v[174:177], v[198:201], v[54:57]
	v_mfma_f32_16x16x32_bf16 v[38:41], v[174:177], v[206:209], v[38:41]
	v_mfma_f32_16x16x32_bf16 v[38:41], v[170:173], v[202:205], v[38:41]
	v_mfma_f32_16x16x32_bf16 v[22:25], v[170:173], v[210:213], v[22:25]
	v_mfma_f32_16x16x32_bf16 v[22:25], v[174:177], v[214:217], v[22:25]
	v_mfma_f32_16x16x32_bf16 v[6:9], v[174:177], v[222:225], v[6:9]
	v_mfma_f32_16x16x32_bf16 v[6:9], v[170:173], v[218:221], v[6:9]
	v_mfma_f32_16x16x32_bf16 v[2:5], v[180:183], v[218:221], v[2:5]
	v_mfma_f32_16x16x32_bf16 v[2:5], v[184:187], v[222:225], v[2:5]
	v_mfma_f32_16x16x32_bf16 v[18:21], v[184:187], v[214:217], v[18:21]
	v_mfma_f32_16x16x32_bf16 v[18:21], v[180:183], v[210:213], v[18:21]
	v_mfma_f32_16x16x32_bf16 v[34:37], v[180:183], v[202:205], v[34:37]
	v_mfma_f32_16x16x32_bf16 v[34:37], v[184:187], v[206:209], v[34:37]
	v_mfma_f32_16x16x32_bf16 v[50:53], v[184:187], v[198:201], v[50:53]
	v_mfma_f32_16x16x32_bf16 v[50:53], v[180:183], v[188:191], v[50:53]
	s_barrier
.LBB0_757:
	ds_read_b128 v[154:157], v149
	ds_read_b128 v[158:161], v149 offset:1024
	ds_read_b128 v[162:165], v149 offset:2048
	ds_read_b128 v[166:169], v149 offset:3072
	ds_read_b128 v[170:173], v150
	ds_read_b128 v[174:177], v150 offset:1024
	ds_read_b128 v[180:183], v150 offset:2048
	ds_read_b128 v[184:187], v150 offset:3072
	s_mov_b32 m0, s57
	s_nop 0
	global_load_lds_dwordx4 v130, s[46:47]
	s_mov_b32 m0, s58
	s_nop 0
	global_load_lds_dwordx4 v134, s[46:47]
	s_add_i32 m0, s26, 0xc000
	ds_read_b128 v[188:191], v151
	ds_read_b128 v[198:201], v151 offset:1024
	ds_read_b128 v[202:205], v151 offset:2048
	ds_read_b128 v[206:209], v151 offset:3072
	ds_read_b128 v[210:213], v151 offset:4096
	ds_read_b128 v[214:217], v151 offset:5120
	ds_read_b128 v[218:221], v151 offset:6144
	ds_read_b128 v[222:225], v151 offset:7168
	global_load_lds_dwordx4 v138, s[44:45]
	s_add_i32 m0, s26, 0xe000
	s_nop 0
	global_load_lds_dwordx4 v140, s[44:45]
	s_waitcnt vmcnt(8)
	s_waitcnt lgkmcnt(0)
	s_barrier
; #define PG8_STAGE(bufoff, gbase, voff) do { _Pragma("unroll") for (int _i = 0; _i < 2; ++_i) \
;         __builtin_amdgcn_global_load_lds((const unsigned*)((const char*)(gbase) + (voff)[_i]), (PG8_LAS unsigned*)(lds + (bufoff) + ldsw + _i * 8192), 16, 0, 0); } while (0)
; #define PG8_LDA(dst, b, h) do { _Pragma("unroll") for (int m = 0; m < 4; ++m) _Pragma("unroll") for (int k = 0; k < 2; ++k) dst[m][k] = *(const PG8_LAS bf16x8*)(lds + PG8_SA(b, h) + aoff + m * 2048 + k * 1024); } while (0)
; #define PG8_MMA(ai, bj, At, Bt) do { __builtin_amdgcn_s_setprio(1); _Pragma("unroll") for (int m = 0; m < 4; ++m) _Pragma("unroll") for (int n = 0; n < 2; ++n) _Pragma("unroll") for (int k = 0; k < 2; ++k) \
;         acc[ai][bj][m][n] = __builtin_amdgcn_mfma_f32_16x16x32_bf16(Bt[n][k], At[m][k], acc[ai][bj][m][n], 0, 0, 0); __builtin_amdgcn_s_setprio(0); } while (0)
; #define PG8_WAIT_V(n) asm volatile("s_waitcnt vmcnt(" #n ")" ::: "memory")
; #define PG8_WAIT_L(n) asm volatile("s_waitcnt lgkmcnt(" #n ")" ::: "memory")
; #define PG8_BAR __builtin_amdgcn_s_barrier()
; #define PG8_SCHED __builtin_amdgcn_sched_barrier(0)
; template <class Epi, class Sched, bool ALIGN_EPI = false, bool SP2 = false>
; __device__ __forceinline__ void gemm_phase(PG8_LAS unsigned char* lds, const Gemm g, const Sched& S, const Epi& E) {
;     ...
;             PG8_WAIT_V(8); PG8_WAIT_L(0); PG8_BAR; PG8_MMA(0, 0, At, B0); PG8_MMA(0, 1, At, B1); PG8_BAR; PG8_SCHED;
;             PG8_LDA(At, 0, 1); PG8_STAGE(PG8_SB(0, 0), b2, voffB); PG8_STAGE(PG8_SB(0, 1), b2 + hstep, voffB); PG8_STAGE(PG8_SA(0, 0), a2, voffA);
;             PG8_WAIT_V(8); PG8_WAIT_L(0); PG8_BAR; PG8_MMA(1, 0, At, B0); PG8_MMA(1, 1, At, B1); PG8_BAR; PG8_SCHED;
	s_waitcnt lgkmcnt(0)
	v_mfma_f32_16x16x32_bf16 v[126:129], v[154:157], v[188:191], v[126:129]
	v_mfma_f32_16x16x32_bf16 v[126:129], v[158:161], v[198:201], v[126:129]
	v_mfma_f32_16x16x32_bf16 v[110:113], v[158:161], v[206:209], v[110:113]
	v_mfma_f32_16x16x32_bf16 v[110:113], v[154:157], v[202:205], v[110:113]
	v_mfma_f32_16x16x32_bf16 v[94:97], v[154:157], v[210:213], v[94:97]
	v_mfma_f32_16x16x32_bf16 v[94:97], v[158:161], v[214:217], v[94:97]
	v_mfma_f32_16x16x32_bf16 v[78:81], v[158:161], v[222:225], v[78:81]
	v_mfma_f32_16x16x32_bf16 v[78:81], v[154:157], v[218:221], v[78:81]
	v_mfma_f32_16x16x32_bf16 v[74:77], v[162:165], v[218:221], v[74:77]
	v_mfma_f32_16x16x32_bf16 v[74:77], v[166:169], v[222:225], v[74:77]
	v_mfma_f32_16x16x32_bf16 v[90:93], v[166:169], v[214:217], v[90:93]
	v_mfma_f32_16x16x32_bf16 v[90:93], v[162:165], v[210:213], v[90:93]
	v_mfma_f32_16x16x32_bf16 v[106:109], v[162:165], v[202:205], v[106:109]
	v_mfma_f32_16x16x32_bf16 v[106:109], v[166:169], v[206:209], v[106:109]
	v_mfma_f32_16x16x32_bf16 v[122:125], v[166:169], v[198:201], v[122:125]
	v_mfma_f32_16x16x32_bf16 v[122:125], v[162:165], v[188:191], v[122:125]
	v_mfma_f32_16x16x32_bf16 v[118:121], v[170:173], v[188:191], v[118:121]
	v_mfma_f32_16x16x32_bf16 v[118:121], v[174:177], v[198:201], v[118:121]
	v_mfma_f32_16x16x32_bf16 v[102:105], v[174:177], v[206:209], v[102:105]
	v_mfma_f32_16x16x32_bf16 v[102:105], v[170:173], v[202:205], v[102:105]
	v_mfma_f32_16x16x32_bf16 v[86:89], v[170:173], v[210:213], v[86:89]
	v_mfma_f32_16x16x32_bf16 v[86:89], v[174:177], v[214:217], v[86:89]
	v_mfma_f32_16x16x32_bf16 v[70:73], v[174:177], v[222:225], v[70:73]
	v_mfma_f32_16x16x32_bf16 v[70:73], v[170:173], v[218:221], v[70:73]
	v_mfma_f32_16x16x32_bf16 v[66:69], v[180:183], v[218:221], v[66:69]
	v_mfma_f32_16x16x32_bf16 v[66:69], v[184:187], v[222:225], v[66:69]
	v_mfma_f32_16x16x32_bf16 v[82:85], v[184:187], v[214:217], v[82:85]
	v_mfma_f32_16x16x32_bf16 v[82:85], v[180:183], v[210:213], v[82:85]
	v_mfma_f32_16x16x32_bf16 v[98:101], v[180:183], v[202:205], v[98:101]
	v_mfma_f32_16x16x32_bf16 v[98:101], v[184:187], v[206:209], v[98:101]
	v_mfma_f32_16x16x32_bf16 v[114:117], v[184:187], v[198:201], v[114:117]
	v_mfma_f32_16x16x32_bf16 v[114:117], v[180:183], v[188:191], v[114:117]
	s_barrier
	s_add_i32 s71, s59, s3
	s_mov_b32 m0, s71
	ds_read_b128 v[188:191], v151 offset:16384
	ds_read_b128 v[198:201], v151 offset:17408
	ds_read_b128 v[202:205], v151 offset:18432
	ds_read_b128 v[206:209], v151 offset:19456
	ds_read_b128 v[210:213], v151 offset:20480
	ds_read_b128 v[214:217], v151 offset:21504
	ds_read_b128 v[218:221], v151 offset:22528
	ds_read_b128 v[222:225], v151 offset:23552
	global_load_lds_dwordx4 v132, s[48:49]
	s_add_i32 m0, s71, 0x2000
	s_add_u32 s72, s48, 0x4000
	s_addc_u32 s73, s49, 0
	s_add_i32 s71, s61, s3
	global_load_lds_dwordx4 v136, s[48:49]
	s_mov_b32 m0, s71
	s_nop 0
	global_load_lds_dwordx4 v132, s[72:73]
	s_add_i32 m0, s71, 0x2000
	s_nop 0
	global_load_lds_dwordx4 v136, s[72:73]
	s_waitcnt vmcnt(6)
	s_waitcnt lgkmcnt(0)
	s_barrier
	s_waitcnt lgkmcnt(0)
	v_mfma_f32_16x16x32_bf16 v[62:65], v[154:157], v[188:191], v[62:65]
	v_mfma_f32_16x16x32_bf16 v[62:65], v[158:161], v[198:201], v[62:65]
	v_mfma_f32_16x16x32_bf16 v[46:49], v[158:161], v[206:209], v[46:49]
	v_mfma_f32_16x16x32_bf16 v[46:49], v[154:157], v[202:205], v[46:49]
	v_mfma_f32_16x16x32_bf16 v[30:33], v[154:157], v[210:213], v[30:33]
	v_mfma_f32_16x16x32_bf16 v[30:33], v[158:161], v[214:217], v[30:33]
	v_mfma_f32_16x16x32_bf16 v[14:17], v[158:161], v[222:225], v[14:17]
	v_mfma_f32_16x16x32_bf16 v[14:17], v[154:157], v[218:221], v[14:17]
	v_mfma_f32_16x16x32_bf16 v[10:13], v[162:165], v[218:221], v[10:13]
	v_mfma_f32_16x16x32_bf16 v[10:13], v[166:169], v[222:225], v[10:13]
	v_mfma_f32_16x16x32_bf16 v[26:29], v[166:169], v[214:217], v[26:29]
	v_mfma_f32_16x16x32_bf16 v[26:29], v[162:165], v[210:213], v[26:29]
	v_mfma_f32_16x16x32_bf16 v[42:45], v[162:165], v[202:205], v[42:45]
	v_mfma_f32_16x16x32_bf16 v[42:45], v[166:169], v[206:209], v[42:45]
	v_mfma_f32_16x16x32_bf16 v[58:61], v[166:169], v[198:201], v[58:61]
	v_mfma_f32_16x16x32_bf16 v[58:61], v[162:165], v[188:191], v[58:61]
	v_mfma_f32_16x16x32_bf16 v[54:57], v[170:173], v[188:191], v[54:57]
	v_mfma_f32_16x16x32_bf16 v[54:57], v[174:177], v[198:201], v[54:57]
	v_mfma_f32_16x16x32_bf16 v[38:41], v[174:177], v[206:209], v[38:41]
	v_mfma_f32_16x16x32_bf16 v[38:41], v[170:173], v[202:205], v[38:41]
	v_mfma_f32_16x16x32_bf16 v[22:25], v[170:173], v[210:213], v[22:25]
	v_mfma_f32_16x16x32_bf16 v[22:25], v[174:177], v[214:217], v[22:25]
	v_mfma_f32_16x16x32_bf16 v[6:9], v[174:177], v[222:225], v[6:9]
	v_mfma_f32_16x16x32_bf16 v[6:9], v[170:173], v[218:221], v[6:9]
	v_mfma_f32_16x16x32_bf16 v[2:5], v[180:183], v[218:221], v[2:5]
	v_mfma_f32_16x16x32_bf16 v[2:5], v[184:187], v[222:225], v[2:5]
	v_mfma_f32_16x16x32_bf16 v[18:21], v[184:187], v[214:217], v[18:21]
	v_mfma_f32_16x16x32_bf16 v[18:21], v[180:183], v[210:213], v[18:21]
	v_mfma_f32_16x16x32_bf16 v[34:37], v[180:183], v[202:205], v[34:37]
	v_mfma_f32_16x16x32_bf16 v[34:37], v[184:187], v[206:209], v[34:37]
	v_mfma_f32_16x16x32_bf16 v[50:53], v[184:187], v[198:201], v[50:53]
	v_mfma_f32_16x16x32_bf16 v[50:53], v[180:183], v[188:191], v[50:53]
	s_barrier
; #define PG8_STAGE(bufoff, gbase, voff) do { _Pragma("unroll") for (int _i = 0; _i < 2; ++_i) \
;         __builtin_amdgcn_global_load_lds((const unsigned*)((const char*)(gbase) + (voff)[_i]), (PG8_LAS unsigned*)(lds + (bufoff) + ldsw + _i * 8192), 16, 0, 0); } while (0)
; #define PG8_LDA(dst, b, h) do { _Pragma("unroll") for (int m = 0; m < 4; ++m) _Pragma("unroll") for (int k = 0; k < 2; ++k) dst[m][k] = *(const PG8_LAS bf16x8*)(lds + PG8_SA(b, h) + aoff + m * 2048 + k * 1024); } while (0)
; #define PG8_LDB(dst, b, h) do { _Pragma("unroll") for (int n = 0; n < 2; ++n) _Pragma("unroll") for (int k = 0; k < 2; ++k) dst[n][k] = *(const PG8_LAS bf16x8*)(lds + PG8_SB(b, h) + boff + n * 2048 + k * 1024); } while (0)
; #define PG8_MMA(ai, bj, At, Bt) do { __builtin_amdgcn_s_setprio(1); _Pragma("unroll") for (int m = 0; m < 4; ++m) _Pragma("unroll") for (int n = 0; n < 2; ++n) _Pragma("unroll") for (int k = 0; k < 2; ++k) \
;         acc[ai][bj][m][n] = __builtin_amdgcn_mfma_f32_16x16x32_bf16(Bt[n][k], At[m][k], acc[ai][bj][m][n], 0, 0, 0); __builtin_amdgcn_s_setprio(0); } while (0)
; #define PG8_WAIT_V(n) asm volatile("s_waitcnt vmcnt(" #n ")" ::: "memory")
; #define PG8_WAIT_L(n) asm volatile("s_waitcnt lgkmcnt(" #n ")" ::: "memory")
; #define PG8_BAR __builtin_amdgcn_s_barrier()
; #define PG8_SCHED __builtin_amdgcn_sched_barrier(0)
; template <class Epi, class Sched, bool ALIGN_EPI = false, bool SP2 = false>
; __device__ __forceinline__ void gemm_phase(PG8_LAS unsigned char* lds, const Gemm g, const Sched& S, const Epi& E) {
;     ...
;             PG8_LDB(B0, 1, 0); PG8_LDB(B1, 1, 1); PG8_SCHED; PG8_LDA(At, 1, 0); PG8_STAGE(PG8_SA(0, 1), a2 + hstep, voffA);
;             PG8_WAIT_V(8); PG8_WAIT_L(0); PG8_BAR; PG8_MMA(0, 0, At, B0); PG8_MMA(0, 1, At, B1); PG8_BAR; PG8_SCHED;
	s_add_i32 s71, 0, 0x18000
	v_add_u32_e32 v146, s71, v1
	s_add_i32 s72, 0, 0x1c000
	ds_read_b128 v[154:157], v146
	ds_read_b128 v[158:161], v146 offset:1024
	ds_read_b128 v[162:165], v146 offset:2048
	ds_read_b128 v[166:169], v146 offset:3072
	v_add_u32_e32 v146, s72, v1
	ds_read_b128 v[170:173], v146
	ds_read_b128 v[174:177], v146 offset:1024
	ds_read_b128 v[180:183], v146 offset:2048
	ds_read_b128 v[184:187], v146 offset:3072
	s_mov_b32 m0, s26
	s_nop 0
	global_load_lds_dwordx4 v130, s[50:51]
	s_mov_b32 m0, s27
	s_nop 0
	global_load_lds_dwordx4 v134, s[50:51]
	s_add_u32 s50, s50, 0x4000
	s_addc_u32 s51, s51, 0
	s_mov_b32 m0, s28
	ds_read_b128 v[188:191], v151 offset:32768
	ds_read_b128 v[198:201], v151 offset:33792
	ds_read_b128 v[202:205], v151 offset:34816
	ds_read_b128 v[206:209], v151 offset:35840
	ds_read_b128 v[210:213], v151 offset:36864
	ds_read_b128 v[214:217], v151 offset:37888
	ds_read_b128 v[218:221], v151 offset:38912
	ds_read_b128 v[222:225], v151 offset:39936
	global_load_lds_dwordx4 v130, s[50:51]
	s_mov_b32 m0, s29
	s_nop 0
	global_load_lds_dwordx4 v134, s[50:51]
	s_waitcnt vmcnt(8)
	s_waitcnt lgkmcnt(0)
	s_barrier
	s_waitcnt lgkmcnt(0)
	v_mfma_f32_16x16x32_bf16 v[126:129], v[154:157], v[188:191], v[126:129]
	v_mfma_f32_16x16x32_bf16 v[126:129], v[158:161], v[198:201], v[126:129]
	v_mfma_f32_16x16x32_bf16 v[110:113], v[158:161], v[206:209], v[110:113]
	v_mfma_f32_16x16x32_bf16 v[110:113], v[154:157], v[202:205], v[110:113]
	v_mfma_f32_16x16x32_bf16 v[94:97], v[154:157], v[210:213], v[94:97]
	v_mfma_f32_16x16x32_bf16 v[94:97], v[158:161], v[214:217], v[94:97]
	v_mfma_f32_16x16x32_bf16 v[78:81], v[158:161], v[222:225], v[78:81]
	v_mfma_f32_16x16x32_bf16 v[78:81], v[154:157], v[218:221], v[78:81]
	v_mfma_f32_16x16x32_bf16 v[74:77], v[162:165], v[218:221], v[74:77]
	v_mfma_f32_16x16x32_bf16 v[74:77], v[166:169], v[222:225], v[74:77]
	v_mfma_f32_16x16x32_bf16 v[90:93], v[166:169], v[214:217], v[90:93]
	v_mfma_f32_16x16x32_bf16 v[90:93], v[162:165], v[210:213], v[90:93]
	v_mfma_f32_16x16x32_bf16 v[106:109], v[162:165], v[202:205], v[106:109]
	v_mfma_f32_16x16x32_bf16 v[106:109], v[166:169], v[206:209], v[106:109]
	v_mfma_f32_16x16x32_bf16 v[122:125], v[166:169], v[198:201], v[122:125]
	v_mfma_f32_16x16x32_bf16 v[122:125], v[162:165], v[188:191], v[122:125]
	v_mfma_f32_16x16x32_bf16 v[118:121], v[170:173], v[188:191], v[118:121]
	v_mfma_f32_16x16x32_bf16 v[118:121], v[174:177], v[198:201], v[118:121]
	v_mfma_f32_16x16x32_bf16 v[102:105], v[174:177], v[206:209], v[102:105]
	v_mfma_f32_16x16x32_bf16 v[102:105], v[170:173], v[202:205], v[102:105]
	v_mfma_f32_16x16x32_bf16 v[86:89], v[170:173], v[210:213], v[86:89]
	v_mfma_f32_16x16x32_bf16 v[86:89], v[174:177], v[214:217], v[86:89]
	v_mfma_f32_16x16x32_bf16 v[70:73], v[174:177], v[222:225], v[70:73]
	v_mfma_f32_16x16x32_bf16 v[70:73], v[170:173], v[218:221], v[70:73]
	v_mfma_f32_16x16x32_bf16 v[66:69], v[180:183], v[218:221], v[66:69]
	v_mfma_f32_16x16x32_bf16 v[66:69], v[184:187], v[222:225], v[66:69]
	v_mfma_f32_16x16x32_bf16 v[82:85], v[184:187], v[214:217], v[82:85]
	v_mfma_f32_16x16x32_bf16 v[82:85], v[180:183], v[210:213], v[82:85]
	v_mfma_f32_16x16x32_bf16 v[98:101], v[180:183], v[202:205], v[98:101]
	v_mfma_f32_16x16x32_bf16 v[98:101], v[184:187], v[206:209], v[98:101]
	v_mfma_f32_16x16x32_bf16 v[114:117], v[184:187], v[198:201], v[114:117]
	v_mfma_f32_16x16x32_bf16 v[114:117], v[180:183], v[188:191], v[114:117]
	s_barrier
; #define PG8_STAGE(bufoff, gbase, voff) do { _Pragma("unroll") for (int _i = 0; _i < 2; ++_i) \
;         __builtin_amdgcn_global_load_lds((const unsigned*)((const char*)(gbase) + (voff)[_i]), (PG8_LAS unsigned*)(lds + (bufoff) + ldsw + _i * 8192), 16, 0, 0); } while (0)
; #define PG8_LDA(dst, b, h) do { _Pragma("unroll") for (int m = 0; m < 4; ++m) _Pragma("unroll") for (int k = 0; k < 2; ++k) dst[m][k] = *(const PG8_LAS bf16x8*)(lds + PG8_SA(b, h) + aoff + m * 2048 + k * 1024); } while (0)
; #define PG8_MMA(ai, bj, At, Bt) do { __builtin_amdgcn_s_setprio(1); _Pragma("unroll") for (int m = 0; m < 4; ++m) _Pragma("unroll") for (int n = 0; n < 2; ++n) _Pragma("unroll") for (int k = 0; k < 2; ++k) \
;         acc[ai][bj][m][n] = __builtin_amdgcn_mfma_f32_16x16x32_bf16(Bt[n][k], At[m][k], acc[ai][bj][m][n], 0, 0, 0); __builtin_amdgcn_s_setprio(0); } while (0)
; #define PG8_WAIT_V(n) asm volatile("s_waitcnt vmcnt(" #n ")" ::: "memory")
; #define PG8_WAIT_L(n) asm volatile("s_waitcnt lgkmcnt(" #n ")" ::: "memory")
; #define PG8_BAR __builtin_amdgcn_s_barrier()
; #define PG8_SCHED __builtin_amdgcn_sched_barrier(0)
; template <class Epi, class Sched, bool ALIGN_EPI = false, bool SP2 = false>
; __device__ __forceinline__ void gemm_phase(PG8_LAS unsigned char* lds, const Gemm g, const Sched& S, const Epi& E) {
;     ...
;         for (; t < tend; t += 2) {
;             const bool last = (t == nt - 2);
;             const char* a1 = cA + (size_t)(t + 1) * kstep;
;             const char* a2 = last ? nA : cA + (size_t)(t + 2) * kstep; const char* b2 = last ? nB : cB + (size_t)(t + 2) * kstep;
;             const char* a3 = a2 + kstep; const char* b3 = b2 + kstep;
;             if (last && has_next) S.a_ready(nxt);
;     ...
;             PG8_LDA(At, 1, 1); PG8_STAGE(PG8_SB(1, 0), b3, voffB); PG8_STAGE(PG8_SB(1, 1), b3 + hstep, voffB); PG8_STAGE(PG8_SA(1, 0), a3, voffA);
;             PG8_WAIT_V(8); PG8_WAIT_L(0); PG8_BAR; PG8_MMA(1, 0, At, B0); PG8_MMA(1, 1, At, B1); PG8_BAR; PG8_SCHED;
	s_add_u32 s50, s48, 0x8000
	s_addc_u32 s51, s49, 0
	s_add_i32 s71, s71, s3
	s_mov_b32 m0, s71
	ds_read_b128 v[188:191], v151 offset:49152
	ds_read_b128 v[198:201], v151 offset:50176
	ds_read_b128 v[202:205], v151 offset:51200
	ds_read_b128 v[206:209], v151 offset:52224
	ds_read_b128 v[210:213], v151 offset:53248
	ds_read_b128 v[214:217], v151 offset:54272
	ds_read_b128 v[218:221], v151 offset:55296
	ds_read_b128 v[222:225], v151 offset:56320
	global_load_lds_dwordx4 v132, s[50:51]
	s_add_i32 m0, s71, 0x2000
	s_add_u32 s48, s48, 0xc000
	v_lshl_add_u64 v[146:147], s[50:51], 0, v[136:137]
	s_addc_u32 s49, s49, 0
	s_add_i32 s50, s72, s3
	global_load_lds_dwordx4 v[146:147], off
	s_mov_b32 m0, s50
	s_nop 0
	global_load_lds_dwordx4 v132, s[48:49]
	s_add_i32 m0, s50, 0x2000
	s_nop 0
	global_load_lds_dwordx4 v136, s[48:49]
	s_add_i32 s70, s70, 2
	s_add_u32 s44, s44, 0x10000
	s_addc_u32 s45, s45, 0
	s_add_u32 s68, s68, 0x10000
	s_addc_u32 s69, s69, 0
	s_add_u32 s46, s44, 0x4000
	s_addc_u32 s47, s45, 0
	s_cmp_eq_u32 s70, 60
	s_cselect_b32 s50, s39, s46
	s_cselect_b32 s51, s17, s47
	s_cselect_b32 s48, s41, s68
	s_cselect_b32 s49, s15, s69
	s_add_u32 s46, s50, 0x8000
	s_addc_u32 s47, s51, 0
	s_sub_u32 s46, s44, 0x4000
	s_subb_u32 s47, s45, 0
	s_cmp_gt_u32 s70, 61
	s_waitcnt vmcnt(6)
	s_waitcnt lgkmcnt(0)
	s_barrier
	s_waitcnt lgkmcnt(0)
	v_mfma_f32_16x16x32_bf16 v[62:65], v[154:157], v[188:191], v[62:65]
	v_mfma_f32_16x16x32_bf16 v[62:65], v[158:161], v[198:201], v[62:65]
	v_mfma_f32_16x16x32_bf16 v[46:49], v[158:161], v[206:209], v[46:49]
	v_mfma_f32_16x16x32_bf16 v[46:49], v[154:157], v[202:205], v[46:49]
	v_mfma_f32_16x16x32_bf16 v[30:33], v[154:157], v[210:213], v[30:33]
	v_mfma_f32_16x16x32_bf16 v[30:33], v[158:161], v[214:217], v[30:33]
	v_mfma_f32_16x16x32_bf16 v[14:17], v[158:161], v[222:225], v[14:17]
	v_mfma_f32_16x16x32_bf16 v[14:17], v[154:157], v[218:221], v[14:17]
	v_mfma_f32_16x16x32_bf16 v[10:13], v[162:165], v[218:221], v[10:13]
	v_mfma_f32_16x16x32_bf16 v[10:13], v[166:169], v[222:225], v[10:13]
	v_mfma_f32_16x16x32_bf16 v[26:29], v[166:169], v[214:217], v[26:29]
	v_mfma_f32_16x16x32_bf16 v[26:29], v[162:165], v[210:213], v[26:29]
	v_mfma_f32_16x16x32_bf16 v[42:45], v[162:165], v[202:205], v[42:45]
	v_mfma_f32_16x16x32_bf16 v[42:45], v[166:169], v[206:209], v[42:45]
	v_mfma_f32_16x16x32_bf16 v[58:61], v[166:169], v[198:201], v[58:61]
	v_mfma_f32_16x16x32_bf16 v[58:61], v[162:165], v[188:191], v[58:61]
	v_mfma_f32_16x16x32_bf16 v[54:57], v[170:173], v[188:191], v[54:57]
	v_mfma_f32_16x16x32_bf16 v[54:57], v[174:177], v[198:201], v[54:57]
	v_mfma_f32_16x16x32_bf16 v[38:41], v[174:177], v[206:209], v[38:41]
	v_mfma_f32_16x16x32_bf16 v[38:41], v[170:173], v[202:205], v[38:41]
	v_mfma_f32_16x16x32_bf16 v[22:25], v[170:173], v[210:213], v[22:25]
	v_mfma_f32_16x16x32_bf16 v[22:25], v[174:177], v[214:217], v[22:25]
	v_mfma_f32_16x16x32_bf16 v[6:9], v[174:177], v[222:225], v[6:9]
	v_mfma_f32_16x16x32_bf16 v[6:9], v[170:173], v[218:221], v[6:9]
	v_mfma_f32_16x16x32_bf16 v[2:5], v[180:183], v[218:221], v[2:5]
	v_mfma_f32_16x16x32_bf16 v[2:5], v[184:187], v[222:225], v[2:5]
	v_mfma_f32_16x16x32_bf16 v[18:21], v[184:187], v[214:217], v[18:21]
	v_mfma_f32_16x16x32_bf16 v[18:21], v[180:183], v[210:213], v[18:21]
	v_mfma_f32_16x16x32_bf16 v[34:37], v[180:183], v[202:205], v[34:37]
	v_mfma_f32_16x16x32_bf16 v[34:37], v[184:187], v[206:209], v[34:37]
	v_mfma_f32_16x16x32_bf16 v[50:53], v[184:187], v[198:201], v[50:53]
	v_mfma_f32_16x16x32_bf16 v[50:53], v[180:183], v[188:191], v[50:53]
	s_barrier
	s_cbranch_scc0 .LBB0_757
	s_and_b64 vcc, exec, s[12:13]
	s_cbranch_vccz .LBB0_760
	s_barrier

;     __device__ __forceinline__ bool next(int i, Unit& u) const { if (i >= 2) return false; const int xcd = c & 7, off = c >> 3; u.pm = 16 * i + 4 * (xcd >> 1) + (off & 3); u.pn = 8 * (xcd & 1) + (off >> 2); return true; }
; #define PG8_STAGE(bufoff, gbase, voff) do { _Pragma("unroll") for (int _i = 0; _i < 2; ++_i) \
;         __builtin_amdgcn_global_load_lds((const unsigned*)((const char*)(gbase) + (voff)[_i]), (PG8_LAS unsigned*)(lds + (bufoff) + ldsw + _i * 8192), 16, 0, 0); } while (0)
; #define PG8_LDA(dst, b, h) do { _Pragma("unroll") for (int m = 0; m < 4; ++m) _Pragma("unroll") for (int k = 0; k < 2; ++k) dst[m][k] = *(const PG8_LAS bf16x8*)(lds + PG8_SA(b, h) + aoff + m * 2048 + k * 1024); } while (0)
; #define PG8_WAIT_V(n) asm volatile("s_waitcnt vmcnt(" #n ")" ::: "memory")
; #define PG8_BAR __builtin_amdgcn_s_barrier()
; template <class Epi, class Sched, bool ALIGN_EPI = false, bool SP2 = false>
; __device__ __forceinline__ void gemm_phase(PG8_LAS unsigned char* lds, const Gemm g, const Sched& S, const Epi& E) {
;     ...
;         const bool has_next = S.next(ui + 1, nxt);
;         const char* nA = has_next ? (const char*)g.A + (size_t)nxt.pm * tstep : cA; const char* nB = has_next ? (const char*)g.Bt + (size_t)nxt.pn * tstep : cB;
;         constexpr int NSEG = Epi::HAS_MID ? 2 : 1; int t = 0;
; #pragma unroll
;         for (int seg = 0; seg < NSEG; ++seg) { const int tend = (seg + 1 < NSEG) ? (nt >> 1) : nt;
;         for (; t < tend; t += 2) {
;             const bool last = (t == nt - 2);
;             const char* a1 = cA + (size_t)(t + 1) * kstep;
;             const char* a2 = last ? nA : cA + (size_t)(t + 2) * kstep; const char* b2 = last ? nB : cB + (size_t)(t + 2) * kstep;
;             const char* a3 = a2 + kstep; const char* b3 = b2 + kstep;
;             if (last && has_next) S.a_ready(nxt);
;             if constexpr (SP2) {
;             PG8_LDB(B0, 0, 0); PG8_LDB(B1, 0, 1); PG8_SCHED; PG8_LDA(At, 0, 0); PG8_STAGE(PG8_SA(1, 1), a1 + hstep, voffA);
;             PG8_WAIT_V(8); PG8_WAIT_L(0); PG8_BAR; PG8_MMA(0, 0, At, B0); PG8_MMA(0, 1, At, B1); PG8_BAR; PG8_SCHED;
;             PG8_LDA(At, 0, 1); PG8_STAGE(PG8_SB(0, 0), b2, voffB); PG8_STAGE(PG8_SB(0, 1), b2 + hstep, voffB); PG8_STAGE(PG8_SA(0, 0), a2, voffA);
;             PG8_WAIT_V(8); PG8_WAIT_L(0); PG8_BAR; PG8_MMA(1, 0, At, B0); PG8_MMA(1, 1, At, B1); PG8_BAR; PG8_SCHED;
.LBB0_839:
	s_ashr_i32 s23, s22, 31
	s_lshl_b64 s[36:37], s[22:23], 21
	s_add_u32 s36, s18, s36
	s_addc_u32 s37, s19, s37
	s_and_b64 s[38:39], s[0:1], exec
	s_cselect_b32 s23, s37, s41
	s_cselect_b32 s65, s36, s40
	s_ashr_i32 s17, s16, 31
	s_lshl_b64 s[38:39], s[16:17], 21
	v_readlane_b32 s17, v255, 13
	s_add_u32 s38, s17, s38
	v_readlane_b32 s17, v255, 14
	s_addc_u32 s39, s17, s39
	s_and_b64 s[44:45], s[0:1], exec
	s_cselect_b32 s17, s39, s43
	s_cselect_b32 s66, s38, s42
	s_add_u32 s40, s40, 0xc000
	s_addc_u32 s41, s41, 0
	s_add_u32 s67, s42, 0x10000
	s_addc_u32 s68, s43, 0
	s_mov_b32 s69, -2
	s_nop 3
	s_add_u32 s42, s40, 0x4000
	s_addc_u32 s43, s41, 0
	s_cmp_eq_u32 s69, 60
	s_cselect_b32 s46, s65, s42
	s_cselect_b32 s47, s23, s43
	s_cselect_b32 s44, s66, s67
	s_cselect_b32 s45, s17, s68
	s_add_u32 s42, s46, 0x8000
	s_addc_u32 s43, s47, 0
	s_sub_u32 s42, s40, 0x4000
	s_subb_u32 s43, s41, 0
	ds_read_b128 v[148:151], v153
	ds_read_b128 v[158:161], v153 offset:1024
	ds_read_b128 v[162:165], v153 offset:2048
	ds_read_b128 v[166:169], v153 offset:3072
	ds_read_b128 v[170:173], v154
	ds_read_b128 v[174:177], v154 offset:1024
	ds_read_b128 v[180:183], v154 offset:2048
	ds_read_b128 v[184:187], v154 offset:3072
	s_mov_b32 m0, s50
	s_nop 0
	global_load_lds_dwordx4 v130, s[42:43]
	s_mov_b32 m0, s51
	s_nop 0
	global_load_lds_dwordx4 v134, s[42:43]
	s_add_i32 m0, s28, 0xc000
	ds_read_b128 v[188:191], v155
	ds_read_b128 v[198:201], v155 offset:1024
	ds_read_b128 v[202:205], v155 offset:2048
	ds_read_b128 v[206:209], v155 offset:3072
	ds_read_b128 v[210:213], v155 offset:4096
	ds_read_b128 v[214:217], v155 offset:5120
	ds_read_b128 v[218:221], v155 offset:6144
	ds_read_b128 v[222:225], v155 offset:7168
	global_load_lds_dwordx4 v140, s[40:41]
	s_add_i32 m0, s28, 0xe000
	s_nop 0
	global_load_lds_dwordx4 v142, s[40:41]
	s_waitcnt vmcnt(8)
	s_waitcnt lgkmcnt(0)
	s_barrier
	s_waitcnt lgkmcnt(0)
	v_mfma_f32_16x16x32_bf16 v[126:129], v[148:151], v[188:191], 0
	v_mfma_f32_16x16x32_bf16 v[126:129], v[158:161], v[198:201], v[126:129]
	v_mfma_f32_16x16x32_bf16 v[110:113], v[158:161], v[206:209], 0
	v_mfma_f32_16x16x32_bf16 v[110:113], v[148:151], v[202:205], v[110:113]
	v_mfma_f32_16x16x32_bf16 v[94:97], v[148:151], v[210:213], 0
	v_mfma_f32_16x16x32_bf16 v[94:97], v[158:161], v[214:217], v[94:97]
	v_mfma_f32_16x16x32_bf16 v[78:81], v[158:161], v[222:225], 0
	v_mfma_f32_16x16x32_bf16 v[78:81], v[148:151], v[218:221], v[78:81]
	v_mfma_f32_16x16x32_bf16 v[74:77], v[162:165], v[218:221], 0
	v_mfma_f32_16x16x32_bf16 v[74:77], v[166:169], v[222:225], v[74:77]
	v_mfma_f32_16x16x32_bf16 v[90:93], v[166:169], v[214:217], 0
	v_mfma_f32_16x16x32_bf16 v[90:93], v[162:165], v[210:213], v[90:93]
	v_mfma_f32_16x16x32_bf16 v[106:109], v[162:165], v[202:205], 0
	v_mfma_f32_16x16x32_bf16 v[106:109], v[166:169], v[206:209], v[106:109]
	v_mfma_f32_16x16x32_bf16 v[122:125], v[166:169], v[198:201], 0
	v_mfma_f32_16x16x32_bf16 v[122:125], v[162:165], v[188:191], v[122:125]
	v_mfma_f32_16x16x32_bf16 v[118:121], v[170:173], v[188:191], 0
	v_mfma_f32_16x16x32_bf16 v[118:121], v[174:177], v[198:201], v[118:121]
	v_mfma_f32_16x16x32_bf16 v[102:105], v[174:177], v[206:209], 0
	v_mfma_f32_16x16x32_bf16 v[102:105], v[170:173], v[202:205], v[102:105]
	v_mfma_f32_16x16x32_bf16 v[86:89], v[170:173], v[210:213], 0
	v_mfma_f32_16x16x32_bf16 v[86:89], v[174:177], v[214:217], v[86:89]
	v_mfma_f32_16x16x32_bf16 v[70:73], v[174:177], v[222:225], 0
	v_mfma_f32_16x16x32_bf16 v[70:73], v[170:173], v[218:221], v[70:73]
	v_mfma_f32_16x16x32_bf16 v[66:69], v[180:183], v[218:221], 0
	v_mfma_f32_16x16x32_bf16 v[66:69], v[184:187], v[222:225], v[66:69]
	v_mfma_f32_16x16x32_bf16 v[82:85], v[184:187], v[214:217], 0
	v_mfma_f32_16x16x32_bf16 v[82:85], v[180:183], v[210:213], v[82:85]
	v_mfma_f32_16x16x32_bf16 v[98:101], v[180:183], v[202:205], 0
	v_mfma_f32_16x16x32_bf16 v[98:101], v[184:187], v[206:209], v[98:101]
	v_mfma_f32_16x16x32_bf16 v[114:117], v[184:187], v[198:201], 0
	v_mfma_f32_16x16x32_bf16 v[114:117], v[180:183], v[188:191], v[114:117]
	s_barrier
	s_add_i32 s70, s56, s3
	s_mov_b32 m0, s70
	ds_read_b128 v[188:191], v155 offset:16384
	ds_read_b128 v[198:201], v155 offset:17408
	ds_read_b128 v[202:205], v155 offset:18432
	ds_read_b128 v[206:209], v155 offset:19456
	ds_read_b128 v[210:213], v155 offset:20480
	ds_read_b128 v[214:217], v155 offset:21504
	ds_read_b128 v[218:221], v155 offset:22528
	ds_read_b128 v[222:225], v155 offset:23552
	global_load_lds_dwordx4 v132, s[44:45]
	s_add_i32 m0, s70, 0x2000
	s_add_u32 s70, s44, 0x4000
	s_addc_u32 s71, s45, 0
	s_add_i32 s72, s57, s3
	global_load_lds_dwordx4 v136, s[44:45]
	s_mov_b32 m0, s72
	s_nop 0
	global_load_lds_dwordx4 v132, s[70:71]
	s_add_i32 m0, s72, 0x2000
	s_nop 0
	global_load_lds_dwordx4 v136, s[70:71]
	s_waitcnt vmcnt(6)
	s_waitcnt lgkmcnt(0)
	s_barrier
; #define PG8_STAGE(bufoff, gbase, voff) do { _Pragma("unroll") for (int _i = 0; _i < 2; ++_i) \
;         __builtin_amdgcn_global_load_lds((const unsigned*)((const char*)(gbase) + (voff)[_i]), (PG8_LAS unsigned*)(lds + (bufoff) + ldsw + _i * 8192), 16, 0, 0); } while (0)
; #define PG8_LDA(dst, b, h) do { _Pragma("unroll") for (int m = 0; m < 4; ++m) _Pragma("unroll") for (int k = 0; k < 2; ++k) dst[m][k] = *(const PG8_LAS bf16x8*)(lds + PG8_SA(b, h) + aoff + m * 2048 + k * 1024); } while (0)
; #define PG8_LDB(dst, b, h) do { _Pragma("unroll") for (int n = 0; n < 2; ++n) _Pragma("unroll") for (int k = 0; k < 2; ++k) dst[n][k] = *(const PG8_LAS bf16x8*)(lds + PG8_SB(b, h) + boff + n * 2048 + k * 1024); } while (0)
; #define PG8_MMA(ai, bj, At, Bt) do { __builtin_amdgcn_s_setprio(1); _Pragma("unroll") for (int m = 0; m < 4; ++m) _Pragma("unroll") for (int n = 0; n < 2; ++n) _Pragma("unroll") for (int k = 0; k < 2; ++k) \
;         acc[ai][bj][m][n] = __builtin_amdgcn_mfma_f32_16x16x32_bf16(Bt[n][k], At[m][k], acc[ai][bj][m][n], 0, 0, 0); __builtin_amdgcn_s_setprio(0); } while (0)
; #define PG8_WAIT_V(n) asm volatile("s_waitcnt vmcnt(" #n ")" ::: "memory")
; #define PG8_WAIT_L(n) asm volatile("s_waitcnt lgkmcnt(" #n ")" ::: "memory")
; #define PG8_BAR __builtin_amdgcn_s_barrier()
; #define PG8_SCHED __builtin_amdgcn_sched_barrier(0)
; template <class Epi, class Sched, bool ALIGN_EPI = false, bool SP2 = false>
; __device__ __forceinline__ void gemm_phase(PG8_LAS unsigned char* lds, const Gemm g, const Sched& S, const Epi& E) {
;     ...
;             PG8_WAIT_V(8); PG8_WAIT_L(0); PG8_BAR; PG8_MMA(1, 0, At, B0); PG8_MMA(1, 1, At, B1); PG8_BAR; PG8_SCHED;
;             PG8_LDB(B0, 1, 0); PG8_LDB(B1, 1, 1); PG8_SCHED; PG8_LDA(At, 1, 0); PG8_STAGE(PG8_SA(0, 1), a2 + hstep, voffA);
;             PG8_WAIT_V(8); PG8_WAIT_L(0); PG8_BAR; PG8_MMA(0, 0, At, B0); PG8_MMA(0, 1, At, B1); PG8_BAR; PG8_SCHED;
	s_waitcnt lgkmcnt(0)
	v_mfma_f32_16x16x32_bf16 v[62:65], v[148:151], v[188:191], 0
	v_mfma_f32_16x16x32_bf16 v[62:65], v[158:161], v[198:201], v[62:65]
	v_mfma_f32_16x16x32_bf16 v[46:49], v[158:161], v[206:209], 0
	v_mfma_f32_16x16x32_bf16 v[46:49], v[148:151], v[202:205], v[46:49]
	v_mfma_f32_16x16x32_bf16 v[30:33], v[148:151], v[210:213], 0
	v_mfma_f32_16x16x32_bf16 v[30:33], v[158:161], v[214:217], v[30:33]
	v_mfma_f32_16x16x32_bf16 v[14:17], v[158:161], v[222:225], 0
	v_mfma_f32_16x16x32_bf16 v[14:17], v[148:151], v[218:221], v[14:17]
	v_mfma_f32_16x16x32_bf16 v[10:13], v[162:165], v[218:221], 0
	v_mfma_f32_16x16x32_bf16 v[10:13], v[166:169], v[222:225], v[10:13]
	v_mfma_f32_16x16x32_bf16 v[26:29], v[166:169], v[214:217], 0
	v_mfma_f32_16x16x32_bf16 v[26:29], v[162:165], v[210:213], v[26:29]
	v_mfma_f32_16x16x32_bf16 v[42:45], v[162:165], v[202:205], 0
	v_mfma_f32_16x16x32_bf16 v[42:45], v[166:169], v[206:209], v[42:45]
	v_mfma_f32_16x16x32_bf16 v[58:61], v[166:169], v[198:201], 0
	v_mfma_f32_16x16x32_bf16 v[58:61], v[162:165], v[188:191], v[58:61]
	v_mfma_f32_16x16x32_bf16 v[54:57], v[170:173], v[188:191], 0
	v_mfma_f32_16x16x32_bf16 v[54:57], v[174:177], v[198:201], v[54:57]
	v_mfma_f32_16x16x32_bf16 v[38:41], v[174:177], v[206:209], 0
	v_mfma_f32_16x16x32_bf16 v[38:41], v[170:173], v[202:205], v[38:41]
	v_mfma_f32_16x16x32_bf16 v[22:25], v[170:173], v[210:213], 0
	v_mfma_f32_16x16x32_bf16 v[22:25], v[174:177], v[214:217], v[22:25]
	v_mfma_f32_16x16x32_bf16 v[6:9], v[174:177], v[222:225], 0
	v_mfma_f32_16x16x32_bf16 v[6:9], v[170:173], v[218:221], v[6:9]
	v_mfma_f32_16x16x32_bf16 v[2:5], v[180:183], v[218:221], 0
	v_mfma_f32_16x16x32_bf16 v[2:5], v[184:187], v[222:225], v[2:5]
	v_mfma_f32_16x16x32_bf16 v[18:21], v[184:187], v[214:217], 0
	v_mfma_f32_16x16x32_bf16 v[18:21], v[180:183], v[210:213], v[18:21]
	v_mfma_f32_16x16x32_bf16 v[34:37], v[180:183], v[202:205], 0
	v_mfma_f32_16x16x32_bf16 v[34:37], v[184:187], v[206:209], v[34:37]
	v_mfma_f32_16x16x32_bf16 v[50:53], v[184:187], v[198:201], 0
	v_mfma_f32_16x16x32_bf16 v[50:53], v[180:183], v[188:191], v[50:53]
	s_barrier
	s_add_i32 s70, 0, 0x18000
	v_add_u32_e32 v138, s70, v1
	s_add_i32 s71, 0, 0x1c000
	ds_read_b128 v[148:151], v138
	ds_read_b128 v[158:161], v138 offset:1024
	ds_read_b128 v[162:165], v138 offset:2048
	ds_read_b128 v[166:169], v138 offset:3072
	v_add_u32_e32 v138, s71, v1
	ds_read_b128 v[170:173], v138
	ds_read_b128 v[174:177], v138 offset:1024
	ds_read_b128 v[180:183], v138 offset:2048
	ds_read_b128 v[184:187], v138 offset:3072
	s_mov_b32 m0, s28
	s_nop 0
	global_load_lds_dwordx4 v130, s[46:47]
	s_mov_b32 m0, s29
	s_nop 0
	global_load_lds_dwordx4 v134, s[46:47]
	s_add_u32 s46, s46, 0x4000
	s_addc_u32 s47, s47, 0
	s_mov_b32 m0, s30
	ds_read_b128 v[188:191], v155 offset:32768
	ds_read_b128 v[198:201], v155 offset:33792
	ds_read_b128 v[202:205], v155 offset:34816
	ds_read_b128 v[206:209], v155 offset:35840
	ds_read_b128 v[210:213], v155 offset:36864
	ds_read_b128 v[214:217], v155 offset:37888
	ds_read_b128 v[218:221], v155 offset:38912
	ds_read_b128 v[222:225], v155 offset:39936
	global_load_lds_dwordx4 v130, s[46:47]
	s_mov_b32 m0, s31
	s_nop 0
	global_load_lds_dwordx4 v134, s[46:47]
	s_waitcnt vmcnt(8)
	s_waitcnt lgkmcnt(0)
	s_barrier
	s_waitcnt lgkmcnt(0)
	v_mfma_f32_16x16x32_bf16 v[126:129], v[148:151], v[188:191], v[126:129]
	v_mfma_f32_16x16x32_bf16 v[126:129], v[158:161], v[198:201], v[126:129]
	v_mfma_f32_16x16x32_bf16 v[110:113], v[158:161], v[206:209], v[110:113]
	v_mfma_f32_16x16x32_bf16 v[110:113], v[148:151], v[202:205], v[110:113]
	v_mfma_f32_16x16x32_bf16 v[94:97], v[148:151], v[210:213], v[94:97]
	v_mfma_f32_16x16x32_bf16 v[94:97], v[158:161], v[214:217], v[94:97]
	v_mfma_f32_16x16x32_bf16 v[78:81], v[158:161], v[222:225], v[78:81]
	v_mfma_f32_16x16x32_bf16 v[78:81], v[148:151], v[218:221], v[78:81]
	v_mfma_f32_16x16x32_bf16 v[74:77], v[162:165], v[218:221], v[74:77]
	v_mfma_f32_16x16x32_bf16 v[74:77], v[166:169], v[222:225], v[74:77]
	v_mfma_f32_16x16x32_bf16 v[90:93], v[166:169], v[214:217], v[90:93]
	v_mfma_f32_16x16x32_bf16 v[90:93], v[162:165], v[210:213], v[90:93]
	v_mfma_f32_16x16x32_bf16 v[106:109], v[162:165], v[202:205], v[106:109]
	v_mfma_f32_16x16x32_bf16 v[106:109], v[166:169], v[206:209], v[106:109]
	v_mfma_f32_16x16x32_bf16 v[122:125], v[166:169], v[198:201], v[122:125]
	v_mfma_f32_16x16x32_bf16 v[122:125], v[162:165], v[188:191], v[122:125]
	v_mfma_f32_16x16x32_bf16 v[118:121], v[170:173], v[188:191], v[118:121]
	v_mfma_f32_16x16x32_bf16 v[118:121], v[174:177], v[198:201], v[118:121]
	v_mfma_f32_16x16x32_bf16 v[102:105], v[174:177], v[206:209], v[102:105]
	v_mfma_f32_16x16x32_bf16 v[102:105], v[170:173], v[202:205], v[102:105]
	v_mfma_f32_16x16x32_bf16 v[86:89], v[170:173], v[210:213], v[86:89]
	v_mfma_f32_16x16x32_bf16 v[86:89], v[174:177], v[214:217], v[86:89]
	v_mfma_f32_16x16x32_bf16 v[70:73], v[174:177], v[222:225], v[70:73]
	v_mfma_f32_16x16x32_bf16 v[70:73], v[170:173], v[218:221], v[70:73]
	v_mfma_f32_16x16x32_bf16 v[66:69], v[180:183], v[218:221], v[66:69]
	v_mfma_f32_16x16x32_bf16 v[66:69], v[184:187], v[222:225], v[66:69]
	v_mfma_f32_16x16x32_bf16 v[82:85], v[184:187], v[214:217], v[82:85]
	v_mfma_f32_16x16x32_bf16 v[82:85], v[180:183], v[210:213], v[82:85]
	v_mfma_f32_16x16x32_bf16 v[98:101], v[180:183], v[202:205], v[98:101]
	v_mfma_f32_16x16x32_bf16 v[98:101], v[184:187], v[206:209], v[98:101]
	v_mfma_f32_16x16x32_bf16 v[114:117], v[184:187], v[198:201], v[114:117]
	v_mfma_f32_16x16x32_bf16 v[114:117], v[180:183], v[188:191], v[114:117]
	s_barrier
; #define PG8_STAGE(bufoff, gbase, voff) do { _Pragma("unroll") for (int _i = 0; _i < 2; ++_i) \
;         __builtin_amdgcn_global_load_lds((const unsigned*)((const char*)(gbase) + (voff)[_i]), (PG8_LAS unsigned*)(lds + (bufoff) + ldsw + _i * 8192), 16, 0, 0); } while (0)
; #define PG8_LDA(dst, b, h) do { _Pragma("unroll") for (int m = 0; m < 4; ++m) _Pragma("unroll") for (int k = 0; k < 2; ++k) dst[m][k] = *(const PG8_LAS bf16x8*)(lds + PG8_SA(b, h) + aoff + m * 2048 + k * 1024); } while (0)
; #define PG8_LDB(dst, b, h) do { _Pragma("unroll") for (int n = 0; n < 2; ++n) _Pragma("unroll") for (int k = 0; k < 2; ++k) dst[n][k] = *(const PG8_LAS bf16x8*)(lds + PG8_SB(b, h) + boff + n * 2048 + k * 1024); } while (0)
; template <class Epi, class Sched, bool ALIGN_EPI = false, bool SP2 = false>
; __device__ __forceinline__ void gemm_phase(PG8_LAS unsigned char* lds, const Gemm g, const Sched& S, const Epi& E) {
;     ...
;         for (; t < tend; t += 2) {
;             const bool last = (t == nt - 2);
;             const char* a1 = cA + (size_t)(t + 1) * kstep;
;             const char* a2 = last ? nA : cA + (size_t)(t + 2) * kstep; const char* b2 = last ? nB : cB + (size_t)(t + 2) * kstep;
;             const char* a3 = a2 + kstep; const char* b3 = b2 + kstep;
;             if (last && has_next) S.a_ready(nxt);
;             if constexpr (SP2) {
;             PG8_LDB(B0, 0, 0); PG8_LDB(B1, 0, 1); PG8_SCHED; PG8_LDA(At, 0, 0); PG8_STAGE(PG8_SA(1, 1), a1 + hstep, voffA);
;             PG8_WAIT_V(8); PG8_WAIT_L(0); PG8_BAR; PG8_MMA(0, 0, At, B0); PG8_MMA(0, 1, At, B1); PG8_BAR; PG8_SCHED;
;             PG8_LDA(At, 0, 1); PG8_STAGE(PG8_SB(0, 0), b2, voffB); PG8_STAGE(PG8_SB(0, 1), b2 + hstep, voffB); PG8_STAGE(PG8_SA(0, 0), a2, voffA);
;             PG8_WAIT_V(8); PG8_WAIT_L(0); PG8_BAR; PG8_MMA(1, 0, At, B0); PG8_MMA(1, 1, At, B1); PG8_BAR; PG8_SCHED;
;             PG8_LDB(B0, 1, 0); PG8_LDB(B1, 1, 1); PG8_SCHED; PG8_LDA(At, 1, 0); PG8_STAGE(PG8_SA(0, 1), a2 + hstep, voffA);
;             PG8_WAIT_V(8); PG8_WAIT_L(0); PG8_BAR; PG8_MMA(0, 0, At, B0); PG8_MMA(0, 1, At, B1); PG8_BAR; PG8_SCHED;
;             PG8_LDA(At, 1, 1); PG8_STAGE(PG8_SB(1, 0), b3, voffB); PG8_STAGE(PG8_SB(1, 1), b3 + hstep, voffB); PG8_STAGE(PG8_SA(1, 0), a3, voffA);
;             PG8_WAIT_V(8); PG8_WAIT_L(0); PG8_BAR; PG8_MMA(1, 0, At, B0); PG8_MMA(1, 1, At, B1); PG8_BAR; PG8_SCHED;
	s_add_u32 s46, s44, 0x8000
	s_addc_u32 s47, s45, 0
	s_add_i32 s70, s70, s3
	s_mov_b32 m0, s70
	ds_read_b128 v[188:191], v155 offset:49152
	ds_read_b128 v[198:201], v155 offset:50176
	ds_read_b128 v[202:205], v155 offset:51200
	ds_read_b128 v[206:209], v155 offset:52224
	ds_read_b128 v[210:213], v155 offset:53248
	ds_read_b128 v[214:217], v155 offset:54272
	ds_read_b128 v[218:221], v155 offset:55296
	ds_read_b128 v[222:225], v155 offset:56320
	global_load_lds_dwordx4 v132, s[46:47]
	s_add_i32 m0, s70, 0x2000
	s_add_u32 s44, s44, 0xc000
	v_lshl_add_u64 v[226:227], s[46:47], 0, v[136:137]
	s_addc_u32 s45, s45, 0
	s_add_i32 s46, s71, s3
	global_load_lds_dwordx4 v[226:227], off
	s_mov_b32 m0, s46
	s_nop 0
	global_load_lds_dwordx4 v132, s[44:45]
	s_add_i32 m0, s46, 0x2000
	s_nop 0
	global_load_lds_dwordx4 v136, s[44:45]
	s_add_i32 s69, s69, 2
	s_add_u32 s40, s40, 0x10000
	s_addc_u32 s41, s41, 0
	s_add_u32 s67, s67, 0x10000
	s_addc_u32 s68, s68, 0
	s_add_u32 s42, s40, 0x4000
	s_addc_u32 s43, s41, 0
	s_cmp_eq_u32 s69, 60
	s_cselect_b32 s46, s65, s42
	s_cselect_b32 s47, s23, s43
	s_cselect_b32 s44, s66, s67
	s_cselect_b32 s45, s17, s68
	s_add_u32 s42, s46, 0x8000
	s_addc_u32 s43, s47, 0
	s_sub_u32 s42, s40, 0x4000
	s_subb_u32 s43, s41, 0
	s_cmp_gt_u32 s69, 61
	s_waitcnt vmcnt(6)
	s_waitcnt lgkmcnt(0)
	s_barrier
	s_waitcnt lgkmcnt(0)
	v_mfma_f32_16x16x32_bf16 v[62:65], v[148:151], v[188:191], v[62:65]
	v_mfma_f32_16x16x32_bf16 v[62:65], v[158:161], v[198:201], v[62:65]
	v_mfma_f32_16x16x32_bf16 v[46:49], v[158:161], v[206:209], v[46:49]
	v_mfma_f32_16x16x32_bf16 v[46:49], v[148:151], v[202:205], v[46:49]
	v_mfma_f32_16x16x32_bf16 v[30:33], v[148:151], v[210:213], v[30:33]
	v_mfma_f32_16x16x32_bf16 v[30:33], v[158:161], v[214:217], v[30:33]
	v_mfma_f32_16x16x32_bf16 v[14:17], v[158:161], v[222:225], v[14:17]
	v_mfma_f32_16x16x32_bf16 v[14:17], v[148:151], v[218:221], v[14:17]
	v_mfma_f32_16x16x32_bf16 v[10:13], v[162:165], v[218:221], v[10:13]
	v_mfma_f32_16x16x32_bf16 v[10:13], v[166:169], v[222:225], v[10:13]
	v_mfma_f32_16x16x32_bf16 v[26:29], v[166:169], v[214:217], v[26:29]
	v_mfma_f32_16x16x32_bf16 v[26:29], v[162:165], v[210:213], v[26:29]
	v_mfma_f32_16x16x32_bf16 v[42:45], v[162:165], v[202:205], v[42:45]
	v_mfma_f32_16x16x32_bf16 v[42:45], v[166:169], v[206:209], v[42:45]
	v_mfma_f32_16x16x32_bf16 v[58:61], v[166:169], v[198:201], v[58:61]
	v_mfma_f32_16x16x32_bf16 v[58:61], v[162:165], v[188:191], v[58:61]
	v_mfma_f32_16x16x32_bf16 v[54:57], v[170:173], v[188:191], v[54:57]
	v_mfma_f32_16x16x32_bf16 v[54:57], v[174:177], v[198:201], v[54:57]
	v_mfma_f32_16x16x32_bf16 v[38:41], v[174:177], v[206:209], v[38:41]
	v_mfma_f32_16x16x32_bf16 v[38:41], v[170:173], v[202:205], v[38:41]
	v_mfma_f32_16x16x32_bf16 v[22:25], v[170:173], v[210:213], v[22:25]
	v_mfma_f32_16x16x32_bf16 v[22:25], v[174:177], v[214:217], v[22:25]
	v_mfma_f32_16x16x32_bf16 v[6:9], v[174:177], v[222:225], v[6:9]
	v_mfma_f32_16x16x32_bf16 v[6:9], v[170:173], v[218:221], v[6:9]
	v_mfma_f32_16x16x32_bf16 v[2:5], v[180:183], v[218:221], v[2:5]
	v_mfma_f32_16x16x32_bf16 v[2:5], v[184:187], v[222:225], v[2:5]
	v_mfma_f32_16x16x32_bf16 v[18:21], v[184:187], v[214:217], v[18:21]
	v_mfma_f32_16x16x32_bf16 v[18:21], v[180:183], v[210:213], v[18:21]
	v_mfma_f32_16x16x32_bf16 v[34:37], v[180:183], v[202:205], v[34:37]
	v_mfma_f32_16x16x32_bf16 v[34:37], v[184:187], v[206:209], v[34:37]
	v_mfma_f32_16x16x32_bf16 v[50:53], v[184:187], v[198:201], v[50:53]
	v_mfma_f32_16x16x32_bf16 v[50:53], v[180:183], v[188:191], v[50:53]
	s_barrier
.LBB0_840:
	ds_read_b128 v[148:151], v153
	ds_read_b128 v[158:161], v153 offset:1024
	ds_read_b128 v[162:165], v153 offset:2048
	ds_read_b128 v[166:169], v153 offset:3072
	ds_read_b128 v[170:173], v154
	ds_read_b128 v[174:177], v154 offset:1024
	ds_read_b128 v[180:183], v154 offset:2048
	ds_read_b128 v[184:187], v154 offset:3072
	s_mov_b32 m0, s50
	s_nop 0
	global_load_lds_dwordx4 v130, s[42:43]
	s_mov_b32 m0, s51
	s_nop 0
	global_load_lds_dwordx4 v134, s[42:43]
	s_add_i32 m0, s28, 0xc000
	ds_read_b128 v[188:191], v155
	ds_read_b128 v[198:201], v155 offset:1024
	ds_read_b128 v[202:205], v155 offset:2048
	ds_read_b128 v[206:209], v155 offset:3072
	ds_read_b128 v[210:213], v155 offset:4096
	ds_read_b128 v[214:217], v155 offset:5120
	ds_read_b128 v[218:221], v155 offset:6144
	ds_read_b128 v[222:225], v155 offset:7168
	global_load_lds_dwordx4 v140, s[40:41]
	s_add_i32 m0, s28, 0xe000
	s_nop 0
	global_load_lds_dwordx4 v142, s[40:41]
	s_waitcnt vmcnt(8)
	s_waitcnt lgkmcnt(0)
	s_barrier
; #define PG8_STAGE(bufoff, gbase, voff) do { _Pragma("unroll") for (int _i = 0; _i < 2; ++_i) \
;         __builtin_amdgcn_global_load_lds((const unsigned*)((const char*)(gbase) + (voff)[_i]), (PG8_LAS unsigned*)(lds + (bufoff) + ldsw + _i * 8192), 16, 0, 0); } while (0)
; #define PG8_LDA(dst, b, h) do { _Pragma("unroll") for (int m = 0; m < 4; ++m) _Pragma("unroll") for (int k = 0; k < 2; ++k) dst[m][k] = *(const PG8_LAS bf16x8*)(lds + PG8_SA(b, h) + aoff + m * 2048 + k * 1024); } while (0)
; #define PG8_MMA(ai, bj, At, Bt) do { __builtin_amdgcn_s_setprio(1); _Pragma("unroll") for (int m = 0; m < 4; ++m) _Pragma("unroll") for (int n = 0; n < 2; ++n) _Pragma("unroll") for (int k = 0; k < 2; ++k) \
;         acc[ai][bj][m][n] = __builtin_amdgcn_mfma_f32_16x16x32_bf16(Bt[n][k], At[m][k], acc[ai][bj][m][n], 0, 0, 0); __builtin_amdgcn_s_setprio(0); } while (0)
; #define PG8_WAIT_V(n) asm volatile("s_waitcnt vmcnt(" #n ")" ::: "memory")
; #define PG8_WAIT_L(n) asm volatile("s_waitcnt lgkmcnt(" #n ")" ::: "memory")
; #define PG8_BAR __builtin_amdgcn_s_barrier()
; #define PG8_SCHED __builtin_amdgcn_sched_barrier(0)
; template <class Epi, class Sched, bool ALIGN_EPI = false, bool SP2 = false>
; __device__ __forceinline__ void gemm_phase(PG8_LAS unsigned char* lds, const Gemm g, const Sched& S, const Epi& E) {
;     ...
;             PG8_WAIT_V(8); PG8_WAIT_L(0); PG8_BAR; PG8_MMA(0, 0, At, B0); PG8_MMA(0, 1, At, B1); PG8_BAR; PG8_SCHED;
;             PG8_LDA(At, 0, 1); PG8_STAGE(PG8_SB(0, 0), b2, voffB); PG8_STAGE(PG8_SB(0, 1), b2 + hstep, voffB); PG8_STAGE(PG8_SA(0, 0), a2, voffA);
;             PG8_WAIT_V(8); PG8_WAIT_L(0); PG8_BAR; PG8_MMA(1, 0, At, B0); PG8_MMA(1, 1, At, B1); PG8_BAR; PG8_SCHED;
	s_waitcnt lgkmcnt(0)
	v_mfma_f32_16x16x32_bf16 v[126:129], v[148:151], v[188:191], v[126:129]
	v_mfma_f32_16x16x32_bf16 v[126:129], v[158:161], v[198:201], v[126:129]
	v_mfma_f32_16x16x32_bf16 v[110:113], v[158:161], v[206:209], v[110:113]
	v_mfma_f32_16x16x32_bf16 v[110:113], v[148:151], v[202:205], v[110:113]
	v_mfma_f32_16x16x32_bf16 v[94:97], v[148:151], v[210:213], v[94:97]
	v_mfma_f32_16x16x32_bf16 v[94:97], v[158:161], v[214:217], v[94:97]
	v_mfma_f32_16x16x32_bf16 v[78:81], v[158:161], v[222:225], v[78:81]
	v_mfma_f32_16x16x32_bf16 v[78:81], v[148:151], v[218:221], v[78:81]
	v_mfma_f32_16x16x32_bf16 v[74:77], v[162:165], v[218:221], v[74:77]
	v_mfma_f32_16x16x32_bf16 v[74:77], v[166:169], v[222:225], v[74:77]
	v_mfma_f32_16x16x32_bf16 v[90:93], v[166:169], v[214:217], v[90:93]
	v_mfma_f32_16x16x32_bf16 v[90:93], v[162:165], v[210:213], v[90:93]
	v_mfma_f32_16x16x32_bf16 v[106:109], v[162:165], v[202:205], v[106:109]
	v_mfma_f32_16x16x32_bf16 v[106:109], v[166:169], v[206:209], v[106:109]
	v_mfma_f32_16x16x32_bf16 v[122:125], v[166:169], v[198:201], v[122:125]
	v_mfma_f32_16x16x32_bf16 v[122:125], v[162:165], v[188:191], v[122:125]
	v_mfma_f32_16x16x32_bf16 v[118:121], v[170:173], v[188:191], v[118:121]
	v_mfma_f32_16x16x32_bf16 v[118:121], v[174:177], v[198:201], v[118:121]
	v_mfma_f32_16x16x32_bf16 v[102:105], v[174:177], v[206:209], v[102:105]
	v_mfma_f32_16x16x32_bf16 v[102:105], v[170:173], v[202:205], v[102:105]
	v_mfma_f32_16x16x32_bf16 v[86:89], v[170:173], v[210:213], v[86:89]
	v_mfma_f32_16x16x32_bf16 v[86:89], v[174:177], v[214:217], v[86:89]
	v_mfma_f32_16x16x32_bf16 v[70:73], v[174:177], v[222:225], v[70:73]
	v_mfma_f32_16x16x32_bf16 v[70:73], v[170:173], v[218:221], v[70:73]
	v_mfma_f32_16x16x32_bf16 v[66:69], v[180:183], v[218:221], v[66:69]
	v_mfma_f32_16x16x32_bf16 v[66:69], v[184:187], v[222:225], v[66:69]
	v_mfma_f32_16x16x32_bf16 v[82:85], v[184:187], v[214:217], v[82:85]
	v_mfma_f32_16x16x32_bf16 v[82:85], v[180:183], v[210:213], v[82:85]
	v_mfma_f32_16x16x32_bf16 v[98:101], v[180:183], v[202:205], v[98:101]
	v_mfma_f32_16x16x32_bf16 v[98:101], v[184:187], v[206:209], v[98:101]
	v_mfma_f32_16x16x32_bf16 v[114:117], v[184:187], v[198:201], v[114:117]
	v_mfma_f32_16x16x32_bf16 v[114:117], v[180:183], v[188:191], v[114:117]
	s_barrier
	s_add_i32 s70, s56, s3
	s_mov_b32 m0, s70
	ds_read_b128 v[188:191], v155 offset:16384
	ds_read_b128 v[198:201], v155 offset:17408
	ds_read_b128 v[202:205], v155 offset:18432
	ds_read_b128 v[206:209], v155 offset:19456
	ds_read_b128 v[210:213], v155 offset:20480
	ds_read_b128 v[214:217], v155 offset:21504
	ds_read_b128 v[218:221], v155 offset:22528
	ds_read_b128 v[222:225], v155 offset:23552
	global_load_lds_dwordx4 v132, s[44:45]
	s_add_i32 m0, s70, 0x2000
	s_add_u32 s70, s44, 0x4000
	s_addc_u32 s71, s45, 0
	s_add_i32 s72, s57, s3
	global_load_lds_dwordx4 v136, s[44:45]
	s_mov_b32 m0, s72
	s_nop 0
	global_load_lds_dwordx4 v132, s[70:71]
	s_add_i32 m0, s72, 0x2000
	s_nop 0
	global_load_lds_dwordx4 v136, s[70:71]
	s_waitcnt vmcnt(6)
	s_waitcnt lgkmcnt(0)
	s_barrier
	s_waitcnt lgkmcnt(0)
	v_mfma_f32_16x16x32_bf16 v[62:65], v[148:151], v[188:191], v[62:65]
	v_mfma_f32_16x16x32_bf16 v[62:65], v[158:161], v[198:201], v[62:65]
	v_mfma_f32_16x16x32_bf16 v[46:49], v[158:161], v[206:209], v[46:49]
	v_mfma_f32_16x16x32_bf16 v[46:49], v[148:151], v[202:205], v[46:49]
	v_mfma_f32_16x16x32_bf16 v[30:33], v[148:151], v[210:213], v[30:33]
	v_mfma_f32_16x16x32_bf16 v[30:33], v[158:161], v[214:217], v[30:33]
	v_mfma_f32_16x16x32_bf16 v[14:17], v[158:161], v[222:225], v[14:17]
	v_mfma_f32_16x16x32_bf16 v[14:17], v[148:151], v[218:221], v[14:17]
	v_mfma_f32_16x16x32_bf16 v[10:13], v[162:165], v[218:221], v[10:13]
	v_mfma_f32_16x16x32_bf16 v[10:13], v[166:169], v[222:225], v[10:13]
	v_mfma_f32_16x16x32_bf16 v[26:29], v[166:169], v[214:217], v[26:29]
	v_mfma_f32_16x16x32_bf16 v[26:29], v[162:165], v[210:213], v[26:29]
	v_mfma_f32_16x16x32_bf16 v[42:45], v[162:165], v[202:205], v[42:45]
	v_mfma_f32_16x16x32_bf16 v[42:45], v[166:169], v[206:209], v[42:45]
	v_mfma_f32_16x16x32_bf16 v[58:61], v[166:169], v[198:201], v[58:61]
	v_mfma_f32_16x16x32_bf16 v[58:61], v[162:165], v[188:191], v[58:61]
	v_mfma_f32_16x16x32_bf16 v[54:57], v[170:173], v[188:191], v[54:57]
	v_mfma_f32_16x16x32_bf16 v[54:57], v[174:177], v[198:201], v[54:57]
	v_mfma_f32_16x16x32_bf16 v[38:41], v[174:177], v[206:209], v[38:41]
	v_mfma_f32_16x16x32_bf16 v[38:41], v[170:173], v[202:205], v[38:41]
	v_mfma_f32_16x16x32_bf16 v[22:25], v[170:173], v[210:213], v[22:25]
	v_mfma_f32_16x16x32_bf16 v[22:25], v[174:177], v[214:217], v[22:25]
	v_mfma_f32_16x16x32_bf16 v[6:9], v[174:177], v[222:225], v[6:9]
	v_mfma_f32_16x16x32_bf16 v[6:9], v[170:173], v[218:221], v[6:9]
	v_mfma_f32_16x16x32_bf16 v[2:5], v[180:183], v[218:221], v[2:5]
	v_mfma_f32_16x16x32_bf16 v[2:5], v[184:187], v[222:225], v[2:5]
	v_mfma_f32_16x16x32_bf16 v[18:21], v[184:187], v[214:217], v[18:21]
	v_mfma_f32_16x16x32_bf16 v[18:21], v[180:183], v[210:213], v[18:21]
	v_mfma_f32_16x16x32_bf16 v[34:37], v[180:183], v[202:205], v[34:37]
	v_mfma_f32_16x16x32_bf16 v[34:37], v[184:187], v[206:209], v[34:37]
	v_mfma_f32_16x16x32_bf16 v[50:53], v[184:187], v[198:201], v[50:53]
	v_mfma_f32_16x16x32_bf16 v[50:53], v[180:183], v[188:191], v[50:53]
	s_barrier
; #define PG8_STAGE(bufoff, gbase, voff) do { _Pragma("unroll") for (int _i = 0; _i < 2; ++_i) \
;         __builtin_amdgcn_global_load_lds((const unsigned*)((const char*)(gbase) + (voff)[_i]), (PG8_LAS unsigned*)(lds + (bufoff) + ldsw + _i * 8192), 16, 0, 0); } while (0)
; #define PG8_LDA(dst, b, h) do { _Pragma("unroll") for (int m = 0; m < 4; ++m) _Pragma("unroll") for (int k = 0; k < 2; ++k) dst[m][k] = *(const PG8_LAS bf16x8*)(lds + PG8_SA(b, h) + aoff + m * 2048 + k * 1024); } while (0)
; #define PG8_LDB(dst, b, h) do { _Pragma("unroll") for (int n = 0; n < 2; ++n) _Pragma("unroll") for (int k = 0; k < 2; ++k) dst[n][k] = *(const PG8_LAS bf16x8*)(lds + PG8_SB(b, h) + boff + n * 2048 + k * 1024); } while (0)
; #define PG8_MMA(ai, bj, At, Bt) do { __builtin_amdgcn_s_setprio(1); _Pragma("unroll") for (int m = 0; m < 4; ++m) _Pragma("unroll") for (int n = 0; n < 2; ++n) _Pragma("unroll") for (int k = 0; k < 2; ++k) \
;         acc[ai][bj][m][n] = __builtin_amdgcn_mfma_f32_16x16x32_bf16(Bt[n][k], At[m][k], acc[ai][bj][m][n], 0, 0, 0); __builtin_amdgcn_s_setprio(0); } while (0)
; #define PG8_WAIT_V(n) asm volatile("s_waitcnt vmcnt(" #n ")" ::: "memory")
; #define PG8_WAIT_L(n) asm volatile("s_waitcnt lgkmcnt(" #n ")" ::: "memory")
; #define PG8_BAR __builtin_amdgcn_s_barrier()
; #define PG8_SCHED __builtin_amdgcn_sched_barrier(0)
; template <class Epi, class Sched, bool ALIGN_EPI = false, bool SP2 = false>
; __device__ __forceinline__ void gemm_phase(PG8_LAS unsigned char* lds, const Gemm g, const Sched& S, const Epi& E) {
;     ...
;             PG8_LDB(B0, 1, 0); PG8_LDB(B1, 1, 1); PG8_SCHED; PG8_LDA(At, 1, 0); PG8_STAGE(PG8_SA(0, 1), a2 + hstep, voffA);
;             PG8_WAIT_V(8); PG8_WAIT_L(0); PG8_BAR; PG8_MMA(0, 0, At, B0); PG8_MMA(0, 1, At, B1); PG8_BAR; PG8_SCHED;
	s_add_i32 s70, 0, 0x18000
	v_add_u32_e32 v138, s70, v1
	s_add_i32 s71, 0, 0x1c000
	ds_read_b128 v[148:151], v138
	ds_read_b128 v[158:161], v138 offset:1024
	ds_read_b128 v[162:165], v138 offset:2048
	ds_read_b128 v[166:169], v138 offset:3072
	v_add_u32_e32 v138, s71, v1
	ds_read_b128 v[170:173], v138
	ds_read_b128 v[174:177], v138 offset:1024
	ds_read_b128 v[180:183], v138 offset:2048
	ds_read_b128 v[184:187], v138 offset:3072
	s_mov_b32 m0, s28
	s_nop 0
	global_load_lds_dwordx4 v130, s[46:47]
	s_mov_b32 m0, s29
	s_nop 0
	global_load_lds_dwordx4 v134, s[46:47]
	s_add_u32 s46, s46, 0x4000
	s_addc_u32 s47, s47, 0
	s_mov_b32 m0, s30
	ds_read_b128 v[188:191], v155 offset:32768
	ds_read_b128 v[198:201], v155 offset:33792
	ds_read_b128 v[202:205], v155 offset:34816
	ds_read_b128 v[206:209], v155 offset:35840
	ds_read_b128 v[210:213], v155 offset:36864
	ds_read_b128 v[214:217], v155 offset:37888
	ds_read_b128 v[218:221], v155 offset:38912
	ds_read_b128 v[222:225], v155 offset:39936
	global_load_lds_dwordx4 v130, s[46:47]
	s_mov_b32 m0, s31
	s_nop 0
	global_load_lds_dwordx4 v134, s[46:47]
	s_waitcnt vmcnt(8)
	s_waitcnt lgkmcnt(0)
	s_barrier
	s_waitcnt lgkmcnt(0)
	v_mfma_f32_16x16x32_bf16 v[126:129], v[148:151], v[188:191], v[126:129]
	v_mfma_f32_16x16x32_bf16 v[126:129], v[158:161], v[198:201], v[126:129]
	v_mfma_f32_16x16x32_bf16 v[110:113], v[158:161], v[206:209], v[110:113]
	v_mfma_f32_16x16x32_bf16 v[110:113], v[148:151], v[202:205], v[110:113]
	v_mfma_f32_16x16x32_bf16 v[94:97], v[148:151], v[210:213], v[94:97]
	v_mfma_f32_16x16x32_bf16 v[94:97], v[158:161], v[214:217], v[94:97]
	v_mfma_f32_16x16x32_bf16 v[78:81], v[158:161], v[222:225], v[78:81]
	v_mfma_f32_16x16x32_bf16 v[78:81], v[148:151], v[218:221], v[78:81]
	v_mfma_f32_16x16x32_bf16 v[74:77], v[162:165], v[218:221], v[74:77]
	v_mfma_f32_16x16x32_bf16 v[74:77], v[166:169], v[222:225], v[74:77]
	v_mfma_f32_16x16x32_bf16 v[90:93], v[166:169], v[214:217], v[90:93]
	v_mfma_f32_16x16x32_bf16 v[90:93], v[162:165], v[210:213], v[90:93]
	v_mfma_f32_16x16x32_bf16 v[106:109], v[162:165], v[202:205], v[106:109]
	v_mfma_f32_16x16x32_bf16 v[106:109], v[166:169], v[206:209], v[106:109]
	v_mfma_f32_16x16x32_bf16 v[122:125], v[166:169], v[198:201], v[122:125]
	v_mfma_f32_16x16x32_bf16 v[122:125], v[162:165], v[188:191], v[122:125]
	v_mfma_f32_16x16x32_bf16 v[118:121], v[170:173], v[188:191], v[118:121]
	v_mfma_f32_16x16x32_bf16 v[118:121], v[174:177], v[198:201], v[118:121]
	v_mfma_f32_16x16x32_bf16 v[102:105], v[174:177], v[206:209], v[102:105]
	v_mfma_f32_16x16x32_bf16 v[102:105], v[170:173], v[202:205], v[102:105]
	v_mfma_f32_16x16x32_bf16 v[86:89], v[170:173], v[210:213], v[86:89]
	v_mfma_f32_16x16x32_bf16 v[86:89], v[174:177], v[214:217], v[86:89]
	v_mfma_f32_16x16x32_bf16 v[70:73], v[174:177], v[222:225], v[70:73]
	v_mfma_f32_16x16x32_bf16 v[70:73], v[170:173], v[218:221], v[70:73]
	v_mfma_f32_16x16x32_bf16 v[66:69], v[180:183], v[218:221], v[66:69]
	v_mfma_f32_16x16x32_bf16 v[66:69], v[184:187], v[222:225], v[66:69]
	v_mfma_f32_16x16x32_bf16 v[82:85], v[184:187], v[214:217], v[82:85]
	v_mfma_f32_16x16x32_bf16 v[82:85], v[180:183], v[210:213], v[82:85]
	v_mfma_f32_16x16x32_bf16 v[98:101], v[180:183], v[202:205], v[98:101]
	v_mfma_f32_16x16x32_bf16 v[98:101], v[184:187], v[206:209], v[98:101]
	v_mfma_f32_16x16x32_bf16 v[114:117], v[184:187], v[198:201], v[114:117]
	v_mfma_f32_16x16x32_bf16 v[114:117], v[180:183], v[188:191], v[114:117]
	s_barrier
; #define PG8_STAGE(bufoff, gbase, voff) do { _Pragma("unroll") for (int _i = 0; _i < 2; ++_i) \
;         __builtin_amdgcn_global_load_lds((const unsigned*)((const char*)(gbase) + (voff)[_i]), (PG8_LAS unsigned*)(lds + (bufoff) + ldsw + _i * 8192), 16, 0, 0); } while (0)
; #define PG8_LDA(dst, b, h) do { _Pragma("unroll") for (int m = 0; m < 4; ++m) _Pragma("unroll") for (int k = 0; k < 2; ++k) dst[m][k] = *(const PG8_LAS bf16x8*)(lds + PG8_SA(b, h) + aoff + m * 2048 + k * 1024); } while (0)
; #define PG8_MMA(ai, bj, At, Bt) do { __builtin_amdgcn_s_setprio(1); _Pragma("unroll") for (int m = 0; m < 4; ++m) _Pragma("unroll") for (int n = 0; n < 2; ++n) _Pragma("unroll") for (int k = 0; k < 2; ++k) \
;         acc[ai][bj][m][n] = __builtin_amdgcn_mfma_f32_16x16x32_bf16(Bt[n][k], At[m][k], acc[ai][bj][m][n], 0, 0, 0); __builtin_amdgcn_s_setprio(0); } while (0)
; #define PG8_WAIT_V(n) asm volatile("s_waitcnt vmcnt(" #n ")" ::: "memory")
; #define PG8_WAIT_L(n) asm volatile("s_waitcnt lgkmcnt(" #n ")" ::: "memory")
; #define PG8_BAR __builtin_amdgcn_s_barrier()
; #define PG8_SCHED __builtin_amdgcn_sched_barrier(0)
; template <class Epi, class Sched, bool ALIGN_EPI = false, bool SP2 = false>
; __device__ __forceinline__ void gemm_phase(PG8_LAS unsigned char* lds, const Gemm g, const Sched& S, const Epi& E) {
;     ...
;         for (; t < tend; t += 2) {
;             const bool last = (t == nt - 2);
;             const char* a1 = cA + (size_t)(t + 1) * kstep;
;             const char* a2 = last ? nA : cA + (size_t)(t + 2) * kstep; const char* b2 = last ? nB : cB + (size_t)(t + 2) * kstep;
;             const char* a3 = a2 + kstep; const char* b3 = b2 + kstep;
;             if (last && has_next) S.a_ready(nxt);
;     ...
;             PG8_LDA(At, 1, 1); PG8_STAGE(PG8_SB(1, 0), b3, voffB); PG8_STAGE(PG8_SB(1, 1), b3 + hstep, voffB); PG8_STAGE(PG8_SA(1, 0), a3, voffA);
;             PG8_WAIT_V(8); PG8_WAIT_L(0); PG8_BAR; PG8_MMA(1, 0, At, B0); PG8_MMA(1, 1, At, B1); PG8_BAR; PG8_SCHED;
	s_add_u32 s46, s44, 0x8000
	s_addc_u32 s47, s45, 0
	s_add_i32 s70, s70, s3
	s_mov_b32 m0, s70
	ds_read_b128 v[188:191], v155 offset:49152
	ds_read_b128 v[198:201], v155 offset:50176
	ds_read_b128 v[202:205], v155 offset:51200
	ds_read_b128 v[206:209], v155 offset:52224
	ds_read_b128 v[210:213], v155 offset:53248
	ds_read_b128 v[214:217], v155 offset:54272
	ds_read_b128 v[218:221], v155 offset:55296
	ds_read_b128 v[222:225], v155 offset:56320
	global_load_lds_dwordx4 v132, s[46:47]
	s_add_i32 m0, s70, 0x2000
	s_add_u32 s44, s44, 0xc000
	v_lshl_add_u64 v[226:227], s[46:47], 0, v[136:137]
	s_addc_u32 s45, s45, 0
	s_add_i32 s46, s71, s3
	global_load_lds_dwordx4 v[226:227], off
	s_mov_b32 m0, s46
	s_nop 0
	global_load_lds_dwordx4 v132, s[44:45]
	s_add_i32 m0, s46, 0x2000
	s_nop 0
	global_load_lds_dwordx4 v136, s[44:45]
	s_add_i32 s69, s69, 2
	s_add_u32 s40, s40, 0x10000
	s_addc_u32 s41, s41, 0
	s_add_u32 s67, s67, 0x10000
	s_addc_u32 s68, s68, 0
	s_add_u32 s42, s40, 0x4000
	s_addc_u32 s43, s41, 0
	s_cmp_eq_u32 s69, 60
	s_cselect_b32 s46, s65, s42
	s_cselect_b32 s47, s23, s43
	s_cselect_b32 s44, s66, s67
	s_cselect_b32 s45, s17, s68
	s_add_u32 s42, s46, 0x8000
	s_addc_u32 s43, s47, 0
	s_sub_u32 s42, s40, 0x4000
	s_subb_u32 s43, s41, 0
	s_cmp_gt_u32 s69, 61
	s_waitcnt vmcnt(6)
	s_waitcnt lgkmcnt(0)
	s_barrier
	s_waitcnt lgkmcnt(0)
	v_mfma_f32_16x16x32_bf16 v[62:65], v[148:151], v[188:191], v[62:65]
	v_mfma_f32_16x16x32_bf16 v[62:65], v[158:161], v[198:201], v[62:65]
	v_mfma_f32_16x16x32_bf16 v[46:49], v[158:161], v[206:209], v[46:49]
	v_mfma_f32_16x16x32_bf16 v[46:49], v[148:151], v[202:205], v[46:49]
	v_mfma_f32_16x16x32_bf16 v[30:33], v[148:151], v[210:213], v[30:33]
	v_mfma_f32_16x16x32_bf16 v[30:33], v[158:161], v[214:217], v[30:33]
	v_mfma_f32_16x16x32_bf16 v[14:17], v[158:161], v[222:225], v[14:17]
	v_mfma_f32_16x16x32_bf16 v[14:17], v[148:151], v[218:221], v[14:17]
	v_mfma_f32_16x16x32_bf16 v[10:13], v[162:165], v[218:221], v[10:13]
	v_mfma_f32_16x16x32_bf16 v[10:13], v[166:169], v[222:225], v[10:13]
	v_mfma_f32_16x16x32_bf16 v[26:29], v[166:169], v[214:217], v[26:29]
	v_mfma_f32_16x16x32_bf16 v[26:29], v[162:165], v[210:213], v[26:29]
	v_mfma_f32_16x16x32_bf16 v[42:45], v[162:165], v[202:205], v[42:45]
	v_mfma_f32_16x16x32_bf16 v[42:45], v[166:169], v[206:209], v[42:45]
	v_mfma_f32_16x16x32_bf16 v[58:61], v[166:169], v[198:201], v[58:61]
	v_mfma_f32_16x16x32_bf16 v[58:61], v[162:165], v[188:191], v[58:61]
	v_mfma_f32_16x16x32_bf16 v[54:57], v[170:173], v[188:191], v[54:57]
	v_mfma_f32_16x16x32_bf16 v[54:57], v[174:177], v[198:201], v[54:57]
	v_mfma_f32_16x16x32_bf16 v[38:41], v[174:177], v[206:209], v[38:41]
	v_mfma_f32_16x16x32_bf16 v[38:41], v[170:173], v[202:205], v[38:41]
	v_mfma_f32_16x16x32_bf16 v[22:25], v[170:173], v[210:213], v[22:25]
	v_mfma_f32_16x16x32_bf16 v[22:25], v[174:177], v[214:217], v[22:25]
	v_mfma_f32_16x16x32_bf16 v[6:9], v[174:177], v[222:225], v[6:9]
	v_mfma_f32_16x16x32_bf16 v[6:9], v[170:173], v[218:221], v[6:9]
	v_mfma_f32_16x16x32_bf16 v[2:5], v[180:183], v[218:221], v[2:5]
	v_mfma_f32_16x16x32_bf16 v[2:5], v[184:187], v[222:225], v[2:5]
	v_mfma_f32_16x16x32_bf16 v[18:21], v[184:187], v[214:217], v[18:21]
	v_mfma_f32_16x16x32_bf16 v[18:21], v[180:183], v[210:213], v[18:21]
	v_mfma_f32_16x16x32_bf16 v[34:37], v[180:183], v[202:205], v[34:37]
	v_mfma_f32_16x16x32_bf16 v[34:37], v[184:187], v[206:209], v[34:37]
	v_mfma_f32_16x16x32_bf16 v[50:53], v[184:187], v[198:201], v[50:53]
	v_mfma_f32_16x16x32_bf16 v[50:53], v[180:183], v[188:191], v[50:53]
	s_barrier
	s_cbranch_scc0 .LBB0_840
	s_and_b64 vcc, exec, s[14:15]
	s_cbranch_vccz .LBB0_843
	s_barrier
